# GEMM K-loops: in the light load phases the loading wave drains its LDS reads before the pre-MFMA barrier so nothing stands between barrier release and the first MFMA
# speedup vs baseline: 1.0096x; 1.0092x over previous
; #define PG8_STAGE(bufoff, gbase, voff) do { _Pragma("unroll") for (int _i = 0; _i < 2; ++_i) \
;         __builtin_amdgcn_global_load_lds((const unsigned*)((const char*)(gbase) + (voff)[_i]), (LAS unsigned*)(lds + (bufoff) + ldsw + _i * 8192), 16, 0, 0); } while (0)
; #define PG8_LDA(dst, b, h) do { _Pragma("unroll") for (int m = 0; m < 4; ++m) _Pragma("unroll") for (int k = 0; k < 2; ++k) dst[m][k] = *(const LAS bf16x8*)(lds + PG8_SA(b, h) + aoff + m * 2048 + k * 1024); } while (0)
; #define PG8_LDB(dst, b, h) do { _Pragma("unroll") for (int n = 0; n < 2; ++n) _Pragma("unroll") for (int k = 0; k < 2; ++k) dst[n][k] = *(const LAS bf16x8*)(lds + PG8_SB(b, h) + boff + n * 2048 + k * 1024); } while (0)
; #define PG8_WAIT_V(n) asm volatile("s_waitcnt vmcnt(" #n ")" ::: "memory")
; #define PG8_WAIT_L(n) asm volatile("s_waitcnt lgkmcnt(" #n ")" ::: "memory")
; #define PG8_BAR __builtin_amdgcn_s_barrier()
; #define PG8_SCHED __builtin_amdgcn_sched_barrier(0)
; template <class Epi>
; __device__ __forceinline__ void gemm_phase(LAS unsigned char* lds, const Gemm g, const StaticOrder& S, const Epi& E) {
;     ...
;         const bool has_next = S.next(ui + 1, nxt);
;         const char* nA = has_next ? (const char*)g.A + (size_t)nxt.pm * tstep : cA; const char* nB = has_next ? (const char*)g.Bt + (size_t)nxt.pn * tstep : cB;
;         for (int t = 0; t < nt; t += 2) {
;             const bool last = (t == nt - 2);
;             const char* a1 = cA + (size_t)(t + 1) * kstep;
;             const char* a2 = last ? nA : cA + (size_t)(t + 2) * kstep; const char* b2 = last ? nB : cB + (size_t)(t + 2) * kstep;
;             const char* a3 = a2 + kstep; const char* b3 = b2 + kstep;
;             PG8_LDB(B0, 0, 0); PG8_SCHED; PG8_LDA(At, 0, 0); PG8_STAGE(PG8_SA(1, 1), a1 + hstep, voffA);
;             PG8_WAIT_L(8); PG8_BAR; PG8_WAIT_L(0); PG8_MMA(0, 0, At, B0); PG8_BAR; PG8_SCHED;
;             PG8_LDB(B1, 0, 1); PG8_STAGE(PG8_SB(0, 0), b2, voffB);
;             PG8_BAR; PG8_WAIT_L(0); PG8_MMA(0, 1, At, B1); PG8_BAR;
;             PG8_LDA(At, 0, 1); PG8_STAGE(PG8_SA(0, 0), a2, voffA);
;             PG8_BAR; PG8_WAIT_L(0); PG8_MMA(1, 0, At, B0); PG8_BAR; PG8_SCHED;
;             PG8_STAGE(PG8_SB(0, 1), b2 + hstep, voffB);
;             PG8_WAIT_V(6); PG8_BAR; PG8_MMA(1, 1, At, B1); PG8_BAR;
.LBB0_203:
	ds_read_b128 v[144:147], v153
	ds_read_b128 v[160:163], v153 offset:1024
	ds_read_b128 v[164:167], v153 offset:2048
	ds_read_b128 v[168:171], v153 offset:3072
	s_add_u32 s44, s42, 0xfff80080
	s_addc_u32 s45, s43, -1
	s_cmp_eq_u32 s54, 28
	s_cselect_b32 s47, s25, s45
	s_cselect_b32 s46, s50, s44
	s_cselect_b32 s45, s23, s53
	s_cselect_b32 s44, s51, s52
	s_add_i32 m0, s11, 0xc000
	ds_read_b128 v[172:175], v154
	ds_read_b128 v[176:179], v154 offset:1024
	ds_read_b128 v[180:183], v154 offset:2048
	ds_read_b128 v[184:187], v154 offset:3072
	ds_read_b128 v[188:191], v154 offset:4096
	ds_read_b128 v[192:195], v154 offset:5120
	ds_read_b128 v[196:199], v154 offset:6144
	ds_read_b128 v[200:203], v154 offset:7168
	global_load_lds_dwordx4 v136, s[42:43]
	s_add_i32 m0, s11, 0xe000
	s_nop 0
	global_load_lds_dwordx4 v138, s[42:43]
	s_waitcnt lgkmcnt(8)
	s_barrier
	s_waitcnt lgkmcnt(0)
	v_mfma_f32_16x16x32_bf16 v[124:127], v[144:147], v[172:175], v[124:127]
	v_mfma_f32_16x16x32_bf16 v[120:123], v[164:167], v[172:175], v[120:123]
	v_mfma_f32_16x16x32_bf16 v[108:111], v[144:147], v[180:183], v[108:111]
	v_mfma_f32_16x16x32_bf16 v[104:107], v[164:167], v[180:183], v[104:107]
	v_mfma_f32_16x16x32_bf16 v[92:95], v[144:147], v[188:191], v[92:95]
	v_mfma_f32_16x16x32_bf16 v[88:91], v[164:167], v[188:191], v[88:91]
	v_mfma_f32_16x16x32_bf16 v[76:79], v[144:147], v[196:199], v[76:79]
	v_mfma_f32_16x16x32_bf16 v[72:75], v[164:167], v[196:199], v[72:75]
	v_mfma_f32_16x16x32_bf16 v[124:127], v[160:163], v[176:179], v[124:127]
	v_mfma_f32_16x16x32_bf16 v[120:123], v[168:171], v[176:179], v[120:123]
	v_mfma_f32_16x16x32_bf16 v[108:111], v[160:163], v[184:187], v[108:111]
	v_mfma_f32_16x16x32_bf16 v[104:107], v[168:171], v[184:187], v[104:107]
	v_mfma_f32_16x16x32_bf16 v[92:95], v[160:163], v[192:195], v[92:95]
	v_mfma_f32_16x16x32_bf16 v[88:91], v[168:171], v[192:195], v[88:91]
	v_mfma_f32_16x16x32_bf16 v[76:79], v[160:163], v[200:203], v[76:79]
	v_mfma_f32_16x16x32_bf16 v[72:75], v[168:171], v[200:203], v[72:75]
	s_barrier
	s_add_i32 s55, s41, s10
	s_add_u32 s98, s44, s8
	s_addc_u32 s99, s45, s9
	s_mov_b32 m0, s55
	ds_read_b128 v[204:207], v155
	ds_read_b128 v[208:211], v155 offset:1024
	ds_read_b128 v[212:215], v155 offset:2048
	ds_read_b128 v[216:219], v155 offset:3072
	global_load_lds_dwordx4 v132, s[44:45]
	s_add_i32 m0, s55, 0x2000
	s_nop 0
	global_load_lds_dwordx4 v128, s[44:45]
	s_waitcnt lgkmcnt(0)
	s_barrier
	v_mfma_f32_16x16x32_bf16 v[116:119], v[204:207], v[172:175], v[116:119]
	v_mfma_f32_16x16x32_bf16 v[112:115], v[212:215], v[172:175], v[112:115]
	v_mfma_f32_16x16x32_bf16 v[100:103], v[204:207], v[180:183], v[100:103]
	v_mfma_f32_16x16x32_bf16 v[96:99], v[212:215], v[180:183], v[96:99]
	v_mfma_f32_16x16x32_bf16 v[84:87], v[204:207], v[188:191], v[84:87]
	v_mfma_f32_16x16x32_bf16 v[80:83], v[212:215], v[188:191], v[80:83]
	v_mfma_f32_16x16x32_bf16 v[68:71], v[204:207], v[196:199], v[68:71]
	v_mfma_f32_16x16x32_bf16 v[64:67], v[212:215], v[196:199], v[64:67]
	v_mfma_f32_16x16x32_bf16 v[116:119], v[208:211], v[176:179], v[116:119]
	v_mfma_f32_16x16x32_bf16 v[112:115], v[216:219], v[176:179], v[112:115]
	v_mfma_f32_16x16x32_bf16 v[100:103], v[208:211], v[184:187], v[100:103]
	v_mfma_f32_16x16x32_bf16 v[96:99], v[216:219], v[184:187], v[96:99]
	v_mfma_f32_16x16x32_bf16 v[84:87], v[208:211], v[192:195], v[84:87]
	v_mfma_f32_16x16x32_bf16 v[80:83], v[216:219], v[192:195], v[80:83]
	v_mfma_f32_16x16x32_bf16 v[68:71], v[208:211], v[200:203], v[68:71]
	v_mfma_f32_16x16x32_bf16 v[64:67], v[216:219], v[200:203], v[64:67]
	s_mov_b32 m0, s11
	s_add_u32 s100, s46, s8
	s_addc_u32 s101, s47, s9
	s_barrier
	ds_read_b128 v[172:175], v154 offset:16384
	ds_read_b128 v[176:179], v154 offset:17408
	ds_read_b128 v[180:183], v154 offset:18432
	ds_read_b128 v[184:187], v154 offset:19456
	ds_read_b128 v[188:191], v154 offset:20480
	ds_read_b128 v[192:195], v154 offset:21504
	ds_read_b128 v[196:199], v154 offset:22528
	ds_read_b128 v[200:203], v154 offset:23552
	global_load_lds_dwordx4 v134, s[46:47]
	s_mov_b32 m0, s13
	s_nop 0
	global_load_lds_dwordx4 v130, s[46:47]
	s_waitcnt lgkmcnt(0)
	s_barrier
	v_mfma_f32_16x16x32_bf16 v[60:63], v[144:147], v[172:175], v[60:63]
	v_mfma_f32_16x16x32_bf16 v[56:59], v[164:167], v[172:175], v[56:59]
	v_mfma_f32_16x16x32_bf16 v[44:47], v[144:147], v[180:183], v[44:47]
	v_mfma_f32_16x16x32_bf16 v[40:43], v[164:167], v[180:183], v[40:43]
	v_mfma_f32_16x16x32_bf16 v[28:31], v[144:147], v[188:191], v[28:31]
	v_mfma_f32_16x16x32_bf16 v[24:27], v[164:167], v[188:191], v[24:27]
	v_mfma_f32_16x16x32_bf16 v[12:15], v[144:147], v[196:199], v[12:15]
	v_mfma_f32_16x16x32_bf16 v[8:11], v[164:167], v[196:199], v[8:11]
	v_mfma_f32_16x16x32_bf16 v[60:63], v[160:163], v[176:179], v[60:63]
	v_mfma_f32_16x16x32_bf16 v[56:59], v[168:171], v[176:179], v[56:59]
	v_mfma_f32_16x16x32_bf16 v[44:47], v[160:163], v[184:187], v[44:47]
	v_mfma_f32_16x16x32_bf16 v[40:43], v[168:171], v[184:187], v[40:43]
	v_mfma_f32_16x16x32_bf16 v[28:31], v[160:163], v[192:195], v[28:31]
	v_mfma_f32_16x16x32_bf16 v[24:27], v[168:171], v[192:195], v[24:27]
	v_mfma_f32_16x16x32_bf16 v[12:15], v[160:163], v[200:203], v[12:15]
	v_mfma_f32_16x16x32_bf16 v[8:11], v[168:171], v[200:203], v[8:11]
	s_barrier
	s_add_u32 s56, s44, 0x80000
	s_addc_u32 s57, s45, 0
	s_add_i32 s55, s48, s10
	s_mov_b32 m0, s55
	s_nop 0
	global_load_lds_dwordx4 v132, s[56:57]
	s_add_i32 m0, s55, 0x2000
	s_nop 0
	global_load_lds_dwordx4 v128, s[56:57]
	s_waitcnt vmcnt(6)
	s_barrier
; #define PG8_STAGE(bufoff, gbase, voff) do { _Pragma("unroll") for (int _i = 0; _i < 2; ++_i) \
;         __builtin_amdgcn_global_load_lds((const unsigned*)((const char*)(gbase) + (voff)[_i]), (LAS unsigned*)(lds + (bufoff) + ldsw + _i * 8192), 16, 0, 0); } while (0)
; #define PG8_LDA(dst, b, h) do { _Pragma("unroll") for (int m = 0; m < 4; ++m) _Pragma("unroll") for (int k = 0; k < 2; ++k) dst[m][k] = *(const LAS bf16x8*)(lds + PG8_SA(b, h) + aoff + m * 2048 + k * 1024); } while (0)
; #define PG8_LDB(dst, b, h) do { _Pragma("unroll") for (int n = 0; n < 2; ++n) _Pragma("unroll") for (int k = 0; k < 2; ++k) dst[n][k] = *(const LAS bf16x8*)(lds + PG8_SB(b, h) + boff + n * 2048 + k * 1024); } while (0)
; #define PG8_MMA(ai, bj, At, Bt) do { __builtin_amdgcn_s_setprio(1); _Pragma("unroll") for (int m = 0; m < 4; ++m) _Pragma("unroll") for (int n = 0; n < 2; ++n) _Pragma("unroll") for (int k = 0; k < 2; ++k) \
;         acc[ai][bj][m][n] = __builtin_amdgcn_mfma_f32_16x16x32_bf16(Bt[n][k], At[m][k], acc[ai][bj][m][n], 0, 0, 0); __builtin_amdgcn_s_setprio(0); } while (0)
; #define PG8_WAIT_V(n) asm volatile("s_waitcnt vmcnt(" #n ")" ::: "memory")
; #define PG8_WAIT_L(n) asm volatile("s_waitcnt lgkmcnt(" #n ")" ::: "memory")
; #define PG8_BAR __builtin_amdgcn_s_barrier()
; #define PG8_SCHED __builtin_amdgcn_sched_barrier(0)
; template <class Epi>
; __device__ __forceinline__ void gemm_phase(LAS unsigned char* lds, const Gemm g, const StaticOrder& S, const Epi& E) {
;     ...
;             PG8_WAIT_V(6); PG8_BAR; PG8_MMA(1, 1, At, B1); PG8_BAR;
;             PG8_LDB(B0, 1, 0); PG8_SCHED; PG8_LDA(At, 1, 0); PG8_STAGE(PG8_SA(0, 1), a2 + hstep, voffA);
;             PG8_WAIT_L(8); PG8_BAR; PG8_WAIT_L(0); PG8_MMA(0, 0, At, B0); PG8_BAR; PG8_SCHED;
;             PG8_LDB(B1, 1, 1); PG8_STAGE(PG8_SB(1, 0), b3, voffB);
;             PG8_BAR; PG8_WAIT_L(0); PG8_MMA(0, 1, At, B1); PG8_BAR;
;             PG8_LDA(At, 1, 1); PG8_STAGE(PG8_SA(1, 0), a3, voffA);
;             PG8_BAR; PG8_WAIT_L(0); PG8_MMA(1, 0, At, B0); PG8_BAR; PG8_SCHED;
	v_mfma_f32_16x16x32_bf16 v[52:55], v[204:207], v[172:175], v[52:55]
	v_mfma_f32_16x16x32_bf16 v[48:51], v[212:215], v[172:175], v[48:51]
	v_mfma_f32_16x16x32_bf16 v[36:39], v[204:207], v[180:183], v[36:39]
	v_mfma_f32_16x16x32_bf16 v[32:35], v[212:215], v[180:183], v[32:35]
	v_mfma_f32_16x16x32_bf16 v[20:23], v[204:207], v[188:191], v[20:23]
	v_mfma_f32_16x16x32_bf16 v[16:19], v[212:215], v[188:191], v[16:19]
	v_mfma_f32_16x16x32_bf16 v[4:7], v[204:207], v[196:199], v[4:7]
	v_mfma_f32_16x16x32_bf16 v[0:3], v[212:215], v[196:199], v[0:3]
	v_mfma_f32_16x16x32_bf16 v[52:55], v[208:211], v[176:179], v[52:55]
	v_mfma_f32_16x16x32_bf16 v[48:51], v[216:219], v[176:179], v[48:51]
	v_mfma_f32_16x16x32_bf16 v[36:39], v[208:211], v[184:187], v[36:39]
	v_mfma_f32_16x16x32_bf16 v[32:35], v[216:219], v[184:187], v[32:35]
	v_mfma_f32_16x16x32_bf16 v[20:23], v[208:211], v[192:195], v[20:23]
	v_mfma_f32_16x16x32_bf16 v[16:19], v[216:219], v[192:195], v[16:19]
	v_mfma_f32_16x16x32_bf16 v[4:7], v[208:211], v[200:203], v[4:7]
	v_mfma_f32_16x16x32_bf16 v[0:3], v[216:219], v[200:203], v[0:3]
	s_add_i32 s55, 0, 0x18000
	v_add_u32_e32 v168, s55, v151
	s_barrier
	ds_read_b128 v[144:147], v168
	ds_read_b128 v[160:163], v168 offset:1024
	ds_read_b128 v[164:167], v168 offset:2048
	ds_read_b128 v[168:171], v168 offset:3072
	s_add_u32 s46, s46, 0x80000
	s_addc_u32 s47, s47, 0
	s_mov_b32 m0, s30
	ds_read_b128 v[172:175], v154 offset:32768
	ds_read_b128 v[176:179], v154 offset:33792
	ds_read_b128 v[180:183], v154 offset:34816
	ds_read_b128 v[184:187], v154 offset:35840
	ds_read_b128 v[188:191], v154 offset:36864
	ds_read_b128 v[192:195], v154 offset:37888
	ds_read_b128 v[196:199], v154 offset:38912
	ds_read_b128 v[200:203], v154 offset:39936
	global_load_lds_dwordx4 v134, s[46:47]
	s_mov_b32 m0, s31
	s_nop 0
	global_load_lds_dwordx4 v130, s[46:47]
	s_waitcnt lgkmcnt(8)
	s_barrier
	s_waitcnt lgkmcnt(0)
	v_mfma_f32_16x16x32_bf16 v[124:127], v[144:147], v[172:175], v[124:127]
	v_mfma_f32_16x16x32_bf16 v[120:123], v[164:167], v[172:175], v[120:123]
	v_mfma_f32_16x16x32_bf16 v[108:111], v[144:147], v[180:183], v[108:111]
	v_mfma_f32_16x16x32_bf16 v[104:107], v[164:167], v[180:183], v[104:107]
	v_mfma_f32_16x16x32_bf16 v[92:95], v[144:147], v[188:191], v[92:95]
	v_mfma_f32_16x16x32_bf16 v[88:91], v[164:167], v[188:191], v[88:91]
	v_mfma_f32_16x16x32_bf16 v[76:79], v[144:147], v[196:199], v[76:79]
	v_mfma_f32_16x16x32_bf16 v[72:75], v[164:167], v[196:199], v[72:75]
	v_mfma_f32_16x16x32_bf16 v[124:127], v[160:163], v[176:179], v[124:127]
	v_mfma_f32_16x16x32_bf16 v[120:123], v[168:171], v[176:179], v[120:123]
	v_mfma_f32_16x16x32_bf16 v[108:111], v[160:163], v[184:187], v[108:111]
	v_mfma_f32_16x16x32_bf16 v[104:107], v[168:171], v[184:187], v[104:107]
	v_mfma_f32_16x16x32_bf16 v[92:95], v[160:163], v[192:195], v[92:95]
	v_mfma_f32_16x16x32_bf16 v[88:91], v[168:171], v[192:195], v[88:91]
	v_mfma_f32_16x16x32_bf16 v[76:79], v[160:163], v[200:203], v[76:79]
	v_mfma_f32_16x16x32_bf16 v[72:75], v[168:171], v[200:203], v[72:75]
	s_barrier
	s_add_i32 s46, 0, 0x1c000
	s_add_i32 s47, s55, s10
	v_add_u32_e32 v216, s46, v151
	s_mov_b32 m0, s47
	ds_read_b128 v[204:207], v216
	ds_read_b128 v[208:211], v216 offset:1024
	ds_read_b128 v[212:215], v216 offset:2048
	ds_read_b128 v[216:219], v216 offset:3072
	global_load_lds_dwordx4 v132, s[98:99]
	s_add_i32 m0, s47, 0x2000
	s_nop 0
	global_load_lds_dwordx4 v128, s[98:99]
	s_waitcnt lgkmcnt(0)
	s_barrier
	v_mfma_f32_16x16x32_bf16 v[116:119], v[204:207], v[172:175], v[116:119]
	v_mfma_f32_16x16x32_bf16 v[112:115], v[212:215], v[172:175], v[112:115]
	v_mfma_f32_16x16x32_bf16 v[100:103], v[204:207], v[180:183], v[100:103]
	v_mfma_f32_16x16x32_bf16 v[96:99], v[212:215], v[180:183], v[96:99]
	v_mfma_f32_16x16x32_bf16 v[84:87], v[204:207], v[188:191], v[84:87]
	v_mfma_f32_16x16x32_bf16 v[80:83], v[212:215], v[188:191], v[80:83]
	v_mfma_f32_16x16x32_bf16 v[68:71], v[204:207], v[196:199], v[68:71]
	v_mfma_f32_16x16x32_bf16 v[64:67], v[212:215], v[196:199], v[64:67]
	v_mfma_f32_16x16x32_bf16 v[116:119], v[208:211], v[176:179], v[116:119]
	v_mfma_f32_16x16x32_bf16 v[112:115], v[216:219], v[176:179], v[112:115]
	v_mfma_f32_16x16x32_bf16 v[100:103], v[208:211], v[184:187], v[100:103]
	v_mfma_f32_16x16x32_bf16 v[96:99], v[216:219], v[184:187], v[96:99]
	v_mfma_f32_16x16x32_bf16 v[84:87], v[208:211], v[192:195], v[84:87]
	v_mfma_f32_16x16x32_bf16 v[80:83], v[216:219], v[192:195], v[80:83]
	v_mfma_f32_16x16x32_bf16 v[68:71], v[208:211], v[200:203], v[68:71]
	v_mfma_f32_16x16x32_bf16 v[64:67], v[216:219], v[200:203], v[64:67]
	s_mov_b32 m0, s36
	s_barrier
	ds_read_b128 v[172:175], v154 offset:49152
	ds_read_b128 v[176:179], v154 offset:50176
	ds_read_b128 v[180:183], v154 offset:51200
	ds_read_b128 v[184:187], v154 offset:52224
	ds_read_b128 v[188:191], v154 offset:53248
	ds_read_b128 v[192:195], v154 offset:54272
	ds_read_b128 v[196:199], v154 offset:55296
	ds_read_b128 v[200:203], v154 offset:56320
	global_load_lds_dwordx4 v134, s[100:101]
	s_mov_b32 m0, s37
	s_nop 0
	global_load_lds_dwordx4 v130, s[100:101]
	s_waitcnt lgkmcnt(0)
	s_barrier
; __device__ __forceinline__ float fast_rcp(float x) { return __builtin_amdgcn_rcpf(x); }
; __device__ __forceinline__ float fast_exp2(float x) { return __builtin_amdgcn_exp2f(x); }
; #define PG8_STAGE(bufoff, gbase, voff) do { _Pragma("unroll") for (int _i = 0; _i < 2; ++_i) \
;         __builtin_amdgcn_global_load_lds((const unsigned*)((const char*)(gbase) + (voff)[_i]), (LAS unsigned*)(lds + (bufoff) + ldsw + _i * 8192), 16, 0, 0); } while (0)
; #define PG8_MMA(ai, bj, At, Bt) do { __builtin_amdgcn_s_setprio(1); _Pragma("unroll") for (int m = 0; m < 4; ++m) _Pragma("unroll") for (int n = 0; n < 2; ++n) _Pragma("unroll") for (int k = 0; k < 2; ++k) \
;         acc[ai][bj][m][n] = __builtin_amdgcn_mfma_f32_16x16x32_bf16(Bt[n][k], At[m][k], acc[ai][bj][m][n], 0, 0, 0); __builtin_amdgcn_s_setprio(0); } while (0)
; #define PG8_WAIT_V(n) asm volatile("s_waitcnt vmcnt(" #n ")" ::: "memory")
; #define PG8_WAIT_L(n) asm volatile("s_waitcnt lgkmcnt(" #n ")" ::: "memory")
; #define PG8_BAR __builtin_amdgcn_s_barrier()
; #define PG8_SCHED __builtin_amdgcn_sched_barrier(0)
; template <class Epi>
; __device__ __forceinline__ void gemm_phase(LAS unsigned char* lds, const Gemm g, const StaticOrder& S, const Epi& E) {
;     ...
;             PG8_BAR; PG8_WAIT_L(0); PG8_MMA(1, 0, At, B0); PG8_BAR; PG8_SCHED;
;             PG8_STAGE(PG8_SB(1, 1), b3 + hstep, voffB);
;             PG8_WAIT_V(6); PG8_BAR; PG8_MMA(1, 1, At, B1); PG8_BAR;
;     __device__ __forceinline__ void operator()(const f32x4 (&acc)[2][2][4][2], const Unit& u, int wr, int wc, int fr, int fq) const {
;         const int row0 = u.pm * BM + wr * 64 + fr, col0 = u.pn * HALF + wc * 32 + 8 * fq;
; #pragma unroll
;         for (int ai = 0; ai < 2; ++ai)
; #pragma unroll
;             for (int m = 0; m < 4; ++m) { bf16_t* rowp = O + (size_t)(row0 + ai * HALF + m * 16) * DFF + col0;
;                 const float r = rs[row0 + ai * HALF + m * 16], r2 = r * r;
;                 f32x4 h0, h1;
; #pragma unroll
;                 for (int j = 0; j < 4; ++j) {
;                     const float g0 = acc[ai][0][m][0][j], g1 = acc[ai][0][m][1][j];
;                     h0[j] = g0 * r2 * fast_rcp(1.0f + fast_exp2(g0 * (-LOG2E * r))) * acc[ai][1][m][0][j];
;                     h1[j] = g1 * r2 * fast_rcp(1.0f + fast_exp2(g1 * (-LOG2E * r))) * acc[ai][1][m][1][j]; }
;                 *(u32x4*)rowp = pack8(h0, h1); }
	v_mfma_f32_16x16x32_bf16 v[60:63], v[144:147], v[172:175], v[60:63]
	v_mfma_f32_16x16x32_bf16 v[56:59], v[164:167], v[172:175], v[56:59]
	v_mfma_f32_16x16x32_bf16 v[44:47], v[144:147], v[180:183], v[44:47]
	v_mfma_f32_16x16x32_bf16 v[40:43], v[164:167], v[180:183], v[40:43]
	v_mfma_f32_16x16x32_bf16 v[28:31], v[144:147], v[188:191], v[28:31]
	v_mfma_f32_16x16x32_bf16 v[24:27], v[164:167], v[188:191], v[24:27]
	v_mfma_f32_16x16x32_bf16 v[12:15], v[144:147], v[196:199], v[12:15]
	v_mfma_f32_16x16x32_bf16 v[8:11], v[164:167], v[196:199], v[8:11]
	v_mfma_f32_16x16x32_bf16 v[60:63], v[160:163], v[176:179], v[60:63]
	v_mfma_f32_16x16x32_bf16 v[56:59], v[168:171], v[176:179], v[56:59]
	v_mfma_f32_16x16x32_bf16 v[44:47], v[160:163], v[184:187], v[44:47]
	v_mfma_f32_16x16x32_bf16 v[40:43], v[168:171], v[184:187], v[40:43]
	v_mfma_f32_16x16x32_bf16 v[28:31], v[160:163], v[192:195], v[28:31]
	v_mfma_f32_16x16x32_bf16 v[24:27], v[168:171], v[192:195], v[24:27]
	v_mfma_f32_16x16x32_bf16 v[12:15], v[160:163], v[200:203], v[12:15]
	v_mfma_f32_16x16x32_bf16 v[8:11], v[168:171], v[200:203], v[8:11]
	s_barrier
	s_add_u32 s44, s44, 0x80080
	s_addc_u32 s45, s45, 0
	s_add_i32 s46, s46, s10
	s_mov_b32 m0, s46
	s_nop 0
	global_load_lds_dwordx4 v132, s[44:45]
	s_add_i32 m0, s46, 0x2000
	s_nop 0
	global_load_lds_dwordx4 v128, s[44:45]
	s_waitcnt vmcnt(6)
	s_barrier
	v_mfma_f32_16x16x32_bf16 v[52:55], v[204:207], v[172:175], v[52:55]
	v_mfma_f32_16x16x32_bf16 v[48:51], v[212:215], v[172:175], v[48:51]
	v_mfma_f32_16x16x32_bf16 v[36:39], v[204:207], v[180:183], v[36:39]
	v_mfma_f32_16x16x32_bf16 v[32:35], v[212:215], v[180:183], v[32:35]
	v_mfma_f32_16x16x32_bf16 v[20:23], v[204:207], v[188:191], v[20:23]
	v_mfma_f32_16x16x32_bf16 v[16:19], v[212:215], v[188:191], v[16:19]
	v_mfma_f32_16x16x32_bf16 v[4:7], v[204:207], v[196:199], v[4:7]
	v_mfma_f32_16x16x32_bf16 v[0:3], v[212:215], v[196:199], v[0:3]
	v_mfma_f32_16x16x32_bf16 v[52:55], v[208:211], v[176:179], v[52:55]
	v_mfma_f32_16x16x32_bf16 v[48:51], v[216:219], v[176:179], v[48:51]
	v_mfma_f32_16x16x32_bf16 v[36:39], v[208:211], v[184:187], v[36:39]
	v_mfma_f32_16x16x32_bf16 v[32:35], v[216:219], v[184:187], v[32:35]
	v_mfma_f32_16x16x32_bf16 v[20:23], v[208:211], v[192:195], v[20:23]
	v_mfma_f32_16x16x32_bf16 v[16:19], v[216:219], v[192:195], v[16:19]
	v_mfma_f32_16x16x32_bf16 v[4:7], v[208:211], v[200:203], v[4:7]
	v_mfma_f32_16x16x32_bf16 v[0:3], v[216:219], v[200:203], v[0:3]
	s_add_i32 s54, s54, 2
	s_add_u32 s42, s42, 0x100
	s_addc_u32 s43, s43, 0
	s_add_u32 s52, s52, 0x100
	s_addc_u32 s53, s53, 0
	s_cmp_gt_u32 s54, 29
	s_barrier
	s_cbranch_scc0 .LBB0_203
	v_lshl_add_u32 v144, s40, 8, v150
	v_ashrrev_i32_e32 v145, 31, v144
	v_lshl_add_u64 v[148:149], v[144:145], 2, s[14:15]
	v_mov_b32_e32 v145, v224
	v_mov_b32_e32 v204, v225
	v_mov_b32_e32 v205, v226
	v_mov_b32_e32 v206, v227
	v_mov_b32_e32 v207, v228
	v_mov_b32_e32 v208, v229
	v_mov_b32_e32 v209, v230
	v_mov_b32_e32 v210, v231
	v_lshl_or_b32 v156, s34, 7, v152
	v_ashrrev_i32_e32 v157, 31, v156
	v_mov_b64_e32 v[146:147], s[20:21]
	v_mad_i64_i32 v[160:161], s[42:43], v144, s49, v[146:147]
	s_and_b64 vcc, exec, s[4:5]
	s_mov_b32 s34, s22
	s_mov_b32 s40, s24
	s_mov_b64 s[44:45], s[28:29]
	v_mul_f32_e32 v162, v145, v145
	v_mul_f32_e32 v145, 0xbfb8aa3b, v145
	v_mul_f32_e32 v163, v124, v162
	v_mul_f32_e32 v124, v124, v145
	v_exp_f32_e32 v124, v124
	s_nop 0
	v_add_f32_e32 v124, 1.0, v124
	v_rcp_f32_e32 v124, v124
	s_nop 0
	v_mul_f32_e32 v124, v163, v124
	v_mul_f32_e32 v116, v116, v124
	v_mul_f32_e32 v124, v120, v162
	v_mul_f32_e32 v120, v120, v145
	v_exp_f32_e32 v120, v120
	s_nop 0
	v_add_f32_e32 v120, 1.0, v120
	v_rcp_f32_e32 v120, v120
	s_nop 0
	v_mul_f32_e32 v120, v124, v120
	v_mul_f32_e32 v124, v125, v145
	v_exp_f32_e32 v124, v124
	v_mul_f32_e32 v120, v112, v120
	v_mul_f32_e32 v112, v125, v162
	v_add_f32_e32 v124, 1.0, v124
	v_rcp_f32_e32 v124, v124
	s_nop 0
	v_mul_f32_e32 v112, v112, v124
	v_mul_f32_e32 v117, v117, v112
	v_mul_f32_e32 v112, v121, v162
	v_mul_f32_e32 v121, v121, v145
	v_exp_f32_e32 v121, v121
	s_nop 0
	v_add_f32_e32 v121, 1.0, v121
	v_rcp_f32_e32 v121, v121
	s_nop 0
	v_mul_f32_e32 v112, v112, v121
	v_mul_f32_e32 v121, v113, v112
	v_mul_f32_e32 v113, v126, v145
	v_exp_f32_e32 v113, v113
	v_mul_f32_e32 v112, v126, v162
	v_add_f32_e32 v113, 1.0, v113
	v_rcp_f32_e32 v113, v113
	s_nop 0
	v_mul_f32_e32 v112, v112, v113
	v_mul_f32_e32 v113, v122, v145
	v_exp_f32_e32 v113, v113
	v_mul_f32_e32 v124, v118, v112
	v_mul_f32_e32 v112, v122, v162
	v_add_f32_e32 v113, 1.0, v113
	v_rcp_f32_e32 v113, v113
	s_nop 0
	v_mul_f32_e32 v112, v112, v113
	v_mul_f32_e32 v113, v127, v145
	v_exp_f32_e32 v113, v113
	v_mul_f32_e32 v122, v114, v112
	v_mul_f32_e32 v112, v127, v162
	v_cvt_pk_bf16_f32 v114, v116, v117
	v_add_f32_e32 v113, 1.0, v113
	v_rcp_f32_e32 v113, v113
	s_nop 0
	v_mul_f32_e32 v112, v112, v113
	v_mul_f32_e32 v113, v123, v145
	v_exp_f32_e32 v113, v113
	v_mul_f32_e32 v125, v119, v112
	v_mul_f32_e32 v112, v123, v162
	v_add_f32_e32 v113, 1.0, v113
	v_rcp_f32_e32 v113, v113
	s_nop 0
	v_mul_f32_e32 v112, v112, v113
	v_mul_f32_e32 v123, v115, v112
	v_lshlrev_b64 v[112:113], 1, v[156:157]
	v_lshl_add_u64 v[118:119], v[160:161], 0, v[112:113]
	v_cvt_pk_bf16_f32 v115, v124, v125
	v_cvt_pk_bf16_f32 v116, v120, v121
	v_cvt_pk_bf16_f32 v117, v122, v123
	global_store_dwordx4 v[118:119], v[114:117], off
	s_nop 1
	v_mov_b32_e32 v116, v204
	s_nop 0
	v_or_b32_e32 v114, 16, v144
	v_mad_i64_i32 v[114:115], s[42:43], v114, s49, v[146:147]
	v_mul_f32_e32 v117, v116, v116
	v_mul_f32_e32 v116, 0xbfb8aa3b, v116
	v_mul_f32_e32 v118, v108, v117
	v_mul_f32_e32 v108, v108, v116
; __device__ __forceinline__ float fast_rcp(float x) { return __builtin_amdgcn_rcpf(x); }
; __device__ __forceinline__ float fast_exp2(float x) { return __builtin_amdgcn_exp2f(x); }
; __device__ __forceinline__ u32x4 pack8(f32x4 v0, f32x4 v1) { u32x4 w; w.x = cvt_pk_bf16(v0[0], v0[1]); w.y = cvt_pk_bf16(v0[2], v0[3]); w.z = cvt_pk_bf16(v1[0], v1[1]); w.w = cvt_pk_bf16(v1[2], v1[3]); return w; }
;     __device__ __forceinline__ void operator()(const f32x4 (&acc)[2][2][4][2], const Unit& u, int wr, int wc, int fr, int fq) const {
;     ...
;             for (int m = 0; m < 4; ++m) { bf16_t* rowp = O + (size_t)(row0 + ai * HALF + m * 16) * DFF + col0;
;                 const float r = rs[row0 + ai * HALF + m * 16], r2 = r * r;
;                 f32x4 h0, h1;
; #pragma unroll
;                 for (int j = 0; j < 4; ++j) {
;                     const float g0 = acc[ai][0][m][0][j], g1 = acc[ai][0][m][1][j];
;                     h0[j] = g0 * r2 * fast_rcp(1.0f + fast_exp2(g0 * (-LOG2E * r))) * acc[ai][1][m][0][j];
;                     h1[j] = g1 * r2 * fast_rcp(1.0f + fast_exp2(g1 * (-LOG2E * r))) * acc[ai][1][m][1][j]; }
;                 *(u32x4*)rowp = pack8(h0, h1); }
	v_exp_f32_e32 v108, v108
	s_nop 0
	v_add_f32_e32 v108, 1.0, v108
	v_rcp_f32_e32 v108, v108
	s_nop 0
	v_mul_f32_e32 v108, v118, v108
	v_mul_f32_e32 v108, v100, v108
	v_mul_f32_e32 v100, v104, v117
	v_mul_f32_e32 v104, v104, v116
	v_exp_f32_e32 v104, v104
	s_nop 0
	v_add_f32_e32 v104, 1.0, v104
	v_rcp_f32_e32 v104, v104
	s_nop 0
	v_mul_f32_e32 v100, v100, v104
	v_mul_f32_e32 v104, v96, v100
	v_mul_f32_e32 v100, v109, v116
	v_exp_f32_e32 v100, v100
	v_mul_f32_e32 v96, v109, v117
	v_add_f32_e32 v100, 1.0, v100
	v_rcp_f32_e32 v100, v100
	s_nop 0
	v_mul_f32_e32 v96, v96, v100
	v_mul_f32_e32 v96, v101, v96
	v_mul_f32_e32 v101, v105, v116
	v_exp_f32_e32 v101, v101
	v_mul_f32_e32 v100, v105, v117
	v_cvt_pk_bf16_f32 v96, v108, v96
	v_add_f32_e32 v101, 1.0, v101
	v_rcp_f32_e32 v101, v101
	s_nop 0
	v_mul_f32_e32 v100, v100, v101
	v_mul_f32_e32 v105, v97, v100
	v_mul_f32_e32 v100, v110, v116
	v_exp_f32_e32 v100, v100
	v_mul_f32_e32 v101, v106, v116
	v_exp_f32_e32 v101, v101
	v_mul_f32_e32 v97, v110, v117
	v_add_f32_e32 v100, 1.0, v100
	v_rcp_f32_e32 v100, v100
	v_add_f32_e32 v101, 1.0, v101
	v_rcp_f32_e32 v101, v101
	v_mul_f32_e32 v97, v97, v100
	v_mul_f32_e32 v100, v106, v117
	v_mul_f32_e32 v100, v100, v101
	v_mul_f32_e32 v97, v102, v97
	v_mul_f32_e32 v102, v98, v100
	v_mul_f32_e32 v100, v111, v116
	v_exp_f32_e32 v100, v100
	v_mul_f32_e32 v101, v107, v116
	v_exp_f32_e32 v101, v101
	v_mul_f32_e32 v98, v111, v117
	v_add_f32_e32 v100, 1.0, v100
	v_rcp_f32_e32 v100, v100
	v_add_f32_e32 v101, 1.0, v101
	v_rcp_f32_e32 v101, v101
	v_mul_f32_e32 v98, v98, v100
	v_mul_f32_e32 v100, v107, v117
	v_mul_f32_e32 v100, v100, v101
	v_mul_f32_e32 v98, v103, v98
	v_mul_f32_e32 v99, v99, v100
	v_lshl_add_u64 v[100:101], v[114:115], 0, v[112:113]
	v_cvt_pk_bf16_f32 v97, v97, v98
	v_cvt_pk_bf16_f32 v98, v104, v105
	v_cvt_pk_bf16_f32 v99, v102, v99
	global_store_dwordx4 v[100:101], v[96:99], off
	s_nop 1
	v_mov_b32_e32 v98, v205
	s_nop 0
	v_or_b32_e32 v96, 32, v144
	v_mad_i64_i32 v[96:97], s[42:43], v96, s49, v[146:147]
	v_mul_f32_e32 v99, v98, v98
	v_mul_f32_e32 v98, 0xbfb8aa3b, v98
	v_mul_f32_e32 v100, v92, v99
	v_mul_f32_e32 v92, v92, v98
	v_exp_f32_e32 v92, v92
	s_nop 0
	v_add_f32_e32 v92, 1.0, v92
	v_rcp_f32_e32 v92, v92
	s_nop 0
	v_mul_f32_e32 v92, v100, v92
	v_mul_f32_e32 v92, v84, v92
	v_mul_f32_e32 v84, v88, v99
	v_mul_f32_e32 v88, v88, v98
	v_exp_f32_e32 v88, v88
	s_nop 0
	v_add_f32_e32 v88, 1.0, v88
	v_rcp_f32_e32 v88, v88
	s_nop 0
	v_mul_f32_e32 v84, v84, v88
	v_mul_f32_e32 v88, v80, v84
	v_mul_f32_e32 v84, v93, v98
	v_exp_f32_e32 v84, v84
	v_mul_f32_e32 v80, v93, v99
	v_add_f32_e32 v84, 1.0, v84
	v_rcp_f32_e32 v84, v84
	s_nop 0
	v_mul_f32_e32 v80, v80, v84
	v_mul_f32_e32 v80, v85, v80
	v_mul_f32_e32 v85, v89, v98
	v_exp_f32_e32 v85, v85
	v_mul_f32_e32 v84, v89, v99
	v_cvt_pk_bf16_f32 v80, v92, v80
	v_add_f32_e32 v85, 1.0, v85
	v_rcp_f32_e32 v85, v85
	s_nop 0
	v_mul_f32_e32 v84, v84, v85
	v_mul_f32_e32 v89, v81, v84
	v_mul_f32_e32 v84, v94, v98
	v_exp_f32_e32 v84, v84
	v_mul_f32_e32 v85, v90, v98
	v_exp_f32_e32 v85, v85
	v_mul_f32_e32 v81, v94, v99
	v_add_f32_e32 v84, 1.0, v84
	v_rcp_f32_e32 v84, v84
	v_add_f32_e32 v85, 1.0, v85
	v_rcp_f32_e32 v85, v85
	v_mul_f32_e32 v81, v81, v84
	v_mul_f32_e32 v84, v90, v99
	v_mul_f32_e32 v84, v84, v85
	v_mul_f32_e32 v81, v86, v81
	v_mul_f32_e32 v86, v82, v84
	v_mul_f32_e32 v84, v95, v98
	v_exp_f32_e32 v84, v84
	v_mul_f32_e32 v85, v91, v98
	v_exp_f32_e32 v85, v85
	v_mul_f32_e32 v82, v95, v99
	v_add_f32_e32 v84, 1.0, v84
	v_rcp_f32_e32 v84, v84
	v_add_f32_e32 v85, 1.0, v85
	v_rcp_f32_e32 v85, v85
	v_mul_f32_e32 v82, v82, v84
	v_mul_f32_e32 v84, v91, v99
	v_mul_f32_e32 v84, v84, v85
	v_mul_f32_e32 v82, v87, v82
	v_mul_f32_e32 v83, v83, v84
	v_lshl_add_u64 v[84:85], v[96:97], 0, v[112:113]
	v_cvt_pk_bf16_f32 v81, v81, v82
	v_cvt_pk_bf16_f32 v82, v88, v89
	v_cvt_pk_bf16_f32 v83, v86, v83
	global_store_dwordx4 v[84:85], v[80:83], off
	s_nop 1
	v_mov_b32_e32 v82, v206
	s_nop 0
	v_or_b32_e32 v80, 48, v144
	v_mad_i64_i32 v[80:81], s[42:43], v80, s49, v[146:147]
	v_mul_f32_e32 v83, v82, v82
	v_mul_f32_e32 v82, 0xbfb8aa3b, v82
	v_mul_f32_e32 v84, v76, v83
	v_mul_f32_e32 v76, v76, v82
	v_exp_f32_e32 v76, v76
	s_nop 0
	v_add_f32_e32 v76, 1.0, v76
	v_rcp_f32_e32 v76, v76
	s_nop 0
	v_mul_f32_e32 v76, v84, v76
	v_mul_f32_e32 v76, v68, v76
	v_mul_f32_e32 v68, v72, v83
	v_mul_f32_e32 v72, v72, v82
	v_exp_f32_e32 v72, v72
	s_nop 0
	v_add_f32_e32 v72, 1.0, v72
	v_rcp_f32_e32 v72, v72
	s_nop 0
	v_mul_f32_e32 v68, v68, v72
	v_mul_f32_e32 v72, v64, v68
	v_mul_f32_e32 v68, v77, v82
	v_exp_f32_e32 v68, v68
	v_mul_f32_e32 v64, v77, v83
	v_add_f32_e32 v68, 1.0, v68
	v_rcp_f32_e32 v68, v68
	s_nop 0
	v_mul_f32_e32 v64, v64, v68
	v_mul_f32_e32 v64, v69, v64
	v_mul_f32_e32 v69, v73, v82
	v_exp_f32_e32 v69, v69
	v_mul_f32_e32 v68, v73, v83
	v_cvt_pk_bf16_f32 v64, v76, v64
	v_add_f32_e32 v69, 1.0, v69
	v_rcp_f32_e32 v69, v69
	s_nop 0
	v_mul_f32_e32 v68, v68, v69
	v_mul_f32_e32 v73, v65, v68
	v_mul_f32_e32 v68, v78, v82
	v_exp_f32_e32 v68, v68
	v_mul_f32_e32 v69, v74, v82
	v_exp_f32_e32 v69, v69
	v_mul_f32_e32 v65, v78, v83
	v_add_f32_e32 v68, 1.0, v68
	v_rcp_f32_e32 v68, v68
	v_add_f32_e32 v69, 1.0, v69
	v_rcp_f32_e32 v69, v69
	v_mul_f32_e32 v65, v65, v68
	v_mul_f32_e32 v68, v74, v83
	v_mul_f32_e32 v68, v68, v69
	v_mul_f32_e32 v65, v70, v65
	v_mul_f32_e32 v70, v66, v68
	v_mul_f32_e32 v68, v79, v82
	v_exp_f32_e32 v68, v68
	v_mul_f32_e32 v69, v75, v82
	v_exp_f32_e32 v69, v69
	v_mul_f32_e32 v66, v79, v83
	v_add_f32_e32 v68, 1.0, v68
	v_rcp_f32_e32 v68, v68
	v_add_f32_e32 v69, 1.0, v69
	v_rcp_f32_e32 v69, v69
	v_mul_f32_e32 v66, v66, v68
	v_mul_f32_e32 v68, v75, v83
; __device__ __forceinline__ float fast_rcp(float x) { return __builtin_amdgcn_rcpf(x); }
; __device__ __forceinline__ float fast_exp2(float x) { return __builtin_amdgcn_exp2f(x); }
; __device__ __forceinline__ u32x4 pack8(f32x4 v0, f32x4 v1) { u32x4 w; w.x = cvt_pk_bf16(v0[0], v0[1]); w.y = cvt_pk_bf16(v0[2], v0[3]); w.z = cvt_pk_bf16(v1[0], v1[1]); w.w = cvt_pk_bf16(v1[2], v1[3]); return w; }
;     __device__ __forceinline__ void operator()(const f32x4 (&acc)[2][2][4][2], const Unit& u, int wr, int wc, int fr, int fq) const {
;     ...
;             for (int m = 0; m < 4; ++m) { bf16_t* rowp = O + (size_t)(row0 + ai * HALF + m * 16) * DFF + col0;
;                 const float r = rs[row0 + ai * HALF + m * 16], r2 = r * r;
;                 f32x4 h0, h1;
; #pragma unroll
;                 for (int j = 0; j < 4; ++j) {
;                     const float g0 = acc[ai][0][m][0][j], g1 = acc[ai][0][m][1][j];
;                     h0[j] = g0 * r2 * fast_rcp(1.0f + fast_exp2(g0 * (-LOG2E * r))) * acc[ai][1][m][0][j];
;                     h1[j] = g1 * r2 * fast_rcp(1.0f + fast_exp2(g1 * (-LOG2E * r))) * acc[ai][1][m][1][j]; }
;                 *(u32x4*)rowp = pack8(h0, h1); }
	v_mul_f32_e32 v68, v68, v69
	v_mul_f32_e32 v66, v71, v66
	v_mul_f32_e32 v67, v67, v68
	v_lshl_add_u64 v[68:69], v[80:81], 0, v[112:113]
	v_cvt_pk_bf16_f32 v65, v65, v66
	v_cvt_pk_bf16_f32 v66, v72, v73
	v_cvt_pk_bf16_f32 v67, v70, v67
	global_store_dwordx4 v[68:69], v[64:67], off
	s_nop 1
	v_mov_b32_e32 v66, v207
	s_nop 0
	v_add_u32_e32 v64, 0x80, v144
	v_mad_i64_i32 v[64:65], s[42:43], v64, s49, v[146:147]
	v_mul_f32_e32 v67, v66, v66
	v_mul_f32_e32 v66, 0xbfb8aa3b, v66
	v_mul_f32_e32 v68, v60, v67
	v_mul_f32_e32 v60, v60, v66
	v_exp_f32_e32 v60, v60
	s_nop 0
	v_add_f32_e32 v60, 1.0, v60
	v_rcp_f32_e32 v60, v60
	s_nop 0
	v_mul_f32_e32 v60, v68, v60
	v_mul_f32_e32 v60, v52, v60
	v_mul_f32_e32 v52, v56, v67
	v_mul_f32_e32 v56, v56, v66
	v_exp_f32_e32 v56, v56
	s_nop 0
	v_add_f32_e32 v56, 1.0, v56
	v_rcp_f32_e32 v56, v56
	s_nop 0
	v_mul_f32_e32 v52, v52, v56
	v_mul_f32_e32 v56, v48, v52
	v_mul_f32_e32 v52, v61, v66
	v_exp_f32_e32 v52, v52
	v_mul_f32_e32 v48, v61, v67
	v_add_f32_e32 v52, 1.0, v52
	v_rcp_f32_e32 v52, v52
	s_nop 0
	v_mul_f32_e32 v48, v48, v52
	v_mul_f32_e32 v48, v53, v48
	v_mul_f32_e32 v53, v57, v66
	v_exp_f32_e32 v53, v53
	v_mul_f32_e32 v52, v57, v67
	v_cvt_pk_bf16_f32 v48, v60, v48
	v_add_f32_e32 v53, 1.0, v53
	v_rcp_f32_e32 v53, v53
	s_nop 0
	v_mul_f32_e32 v52, v52, v53
	v_mul_f32_e32 v57, v49, v52
	v_mul_f32_e32 v52, v62, v66
	v_exp_f32_e32 v52, v52
	v_mul_f32_e32 v53, v58, v66
	v_exp_f32_e32 v53, v53
	v_mul_f32_e32 v49, v62, v67
	v_add_f32_e32 v52, 1.0, v52
	v_rcp_f32_e32 v52, v52
	v_add_f32_e32 v53, 1.0, v53
	v_rcp_f32_e32 v53, v53
	v_mul_f32_e32 v49, v49, v52
	v_mul_f32_e32 v52, v58, v67
	v_mul_f32_e32 v52, v52, v53
	v_mul_f32_e32 v49, v54, v49
	v_mul_f32_e32 v54, v50, v52
	v_mul_f32_e32 v52, v63, v66
	v_exp_f32_e32 v52, v52
	v_mul_f32_e32 v53, v59, v66
	v_exp_f32_e32 v53, v53
	v_mul_f32_e32 v50, v63, v67
	v_add_f32_e32 v52, 1.0, v52
	v_rcp_f32_e32 v52, v52
	v_add_f32_e32 v53, 1.0, v53
	v_rcp_f32_e32 v53, v53
	v_mul_f32_e32 v50, v50, v52
	v_mul_f32_e32 v52, v59, v67
	v_mul_f32_e32 v52, v52, v53
	v_mul_f32_e32 v50, v55, v50
	v_mul_f32_e32 v51, v51, v52
	v_lshl_add_u64 v[52:53], v[64:65], 0, v[112:113]
	v_cvt_pk_bf16_f32 v49, v49, v50
	v_cvt_pk_bf16_f32 v50, v56, v57
	v_cvt_pk_bf16_f32 v51, v54, v51
	global_store_dwordx4 v[52:53], v[48:51], off
	s_nop 1
	v_mov_b32_e32 v50, v208
	s_nop 0
	v_add_u32_e32 v48, 0x90, v144
	v_mad_i64_i32 v[48:49], s[42:43], v48, s49, v[146:147]
	v_mul_f32_e32 v51, v50, v50
	v_mul_f32_e32 v50, 0xbfb8aa3b, v50
	v_mul_f32_e32 v52, v44, v51
	v_mul_f32_e32 v44, v44, v50
	v_exp_f32_e32 v44, v44
	s_nop 0
	v_add_f32_e32 v44, 1.0, v44
	v_rcp_f32_e32 v44, v44
	s_nop 0
	v_mul_f32_e32 v44, v52, v44
	v_mul_f32_e32 v44, v36, v44
	v_mul_f32_e32 v36, v40, v51
	v_mul_f32_e32 v40, v40, v50
	v_exp_f32_e32 v40, v40
	s_nop 0
	v_add_f32_e32 v40, 1.0, v40
	v_rcp_f32_e32 v40, v40
	s_nop 0
	v_mul_f32_e32 v36, v36, v40
	v_mul_f32_e32 v40, v32, v36
	v_mul_f32_e32 v36, v45, v50
	v_exp_f32_e32 v36, v36
	v_mul_f32_e32 v32, v45, v51
	v_add_f32_e32 v36, 1.0, v36
	v_rcp_f32_e32 v36, v36
	s_nop 0
	v_mul_f32_e32 v32, v32, v36
	v_mul_f32_e32 v32, v37, v32
	v_mul_f32_e32 v37, v41, v50
	v_exp_f32_e32 v37, v37
	v_mul_f32_e32 v36, v41, v51
	v_cvt_pk_bf16_f32 v32, v44, v32
	v_add_f32_e32 v37, 1.0, v37
	v_rcp_f32_e32 v37, v37
	s_nop 0
	v_mul_f32_e32 v36, v36, v37
	v_mul_f32_e32 v41, v33, v36
	v_mul_f32_e32 v36, v46, v50
	v_exp_f32_e32 v36, v36
	v_mul_f32_e32 v37, v42, v50
	v_exp_f32_e32 v37, v37
	v_mul_f32_e32 v33, v46, v51
	v_add_f32_e32 v36, 1.0, v36
	v_rcp_f32_e32 v36, v36
	v_add_f32_e32 v37, 1.0, v37
	v_rcp_f32_e32 v37, v37
	v_mul_f32_e32 v33, v33, v36
	v_mul_f32_e32 v36, v42, v51
	v_mul_f32_e32 v36, v36, v37
	v_mul_f32_e32 v33, v38, v33
	v_mul_f32_e32 v38, v34, v36
	v_mul_f32_e32 v36, v47, v50
	v_exp_f32_e32 v36, v36
	v_mul_f32_e32 v37, v43, v50
	v_exp_f32_e32 v37, v37
	v_mul_f32_e32 v34, v47, v51
	v_add_f32_e32 v36, 1.0, v36
	v_rcp_f32_e32 v36, v36
	v_add_f32_e32 v37, 1.0, v37
	v_rcp_f32_e32 v37, v37
	v_mul_f32_e32 v34, v34, v36
	v_mul_f32_e32 v36, v43, v51
	v_mul_f32_e32 v36, v36, v37
	v_mul_f32_e32 v34, v39, v34
	v_mul_f32_e32 v35, v35, v36
	v_lshl_add_u64 v[36:37], v[48:49], 0, v[112:113]
; __device__ __forceinline__ float fast_rcp(float x) { return __builtin_amdgcn_rcpf(x); }
; __device__ __forceinline__ float fast_exp2(float x) { return __builtin_amdgcn_exp2f(x); }
; #define PG8_WAIT_V(n) asm volatile("s_waitcnt vmcnt(" #n ")" ::: "memory")
; #define PG8_BAR __builtin_amdgcn_s_barrier()
; __device__ __forceinline__ u32x4 pack8(f32x4 v0, f32x4 v1) { u32x4 w; w.x = cvt_pk_bf16(v0[0], v0[1]); w.y = cvt_pk_bf16(v0[2], v0[3]); w.z = cvt_pk_bf16(v1[0], v1[1]); w.w = cvt_pk_bf16(v1[2], v1[3]); return w; }
; template <class Epi>
; __device__ __forceinline__ void gemm_phase(LAS unsigned char* lds, const Gemm g, const StaticOrder& S, const Epi& E) {
;     ...
;         if (!has_next) break;
; #pragma unroll
;         for (int a = 0; a < 2; ++a)
; #pragma unroll
;             for (int b = 0; b < 2; ++b)
; #pragma unroll
;                 for (int m = 0; m < 4; ++m)
; #pragma unroll
;                     for (int n = 0; n < 2; ++n) acc[a][b][m][n] = (f32x4){0.f, 0.f, 0.f, 0.f};
;         cur = nxt; cA = nA; cB = nB; ++ui;
;     }
;     PG8_WAIT_V(0);
;     if (wr == 0) PG8_BAR;
;     PG8_BAR;
;     __device__ __forceinline__ void operator()(const f32x4 (&acc)[2][2][4][2], const Unit& u, int wr, int wc, int fr, int fq) const {
;     ...
;             for (int m = 0; m < 4; ++m) { bf16_t* rowp = O + (size_t)(row0 + ai * HALF + m * 16) * DFF + col0;
;                 const float r = rs[row0 + ai * HALF + m * 16], r2 = r * r;
;                 f32x4 h0, h1;
; #pragma unroll
;                 for (int j = 0; j < 4; ++j) {
;                     const float g0 = acc[ai][0][m][0][j], g1 = acc[ai][0][m][1][j];
;                     h0[j] = g0 * r2 * fast_rcp(1.0f + fast_exp2(g0 * (-LOG2E * r))) * acc[ai][1][m][0][j];
;                     h1[j] = g1 * r2 * fast_rcp(1.0f + fast_exp2(g1 * (-LOG2E * r))) * acc[ai][1][m][1][j]; }
;                 *(u32x4*)rowp = pack8(h0, h1); }
	v_cvt_pk_bf16_f32 v33, v33, v34
	v_cvt_pk_bf16_f32 v34, v40, v41
	v_cvt_pk_bf16_f32 v35, v38, v35
	global_store_dwordx4 v[36:37], v[32:35], off
	s_nop 1
	v_mov_b32_e32 v34, v209
	s_nop 0
	v_add_u32_e32 v32, 0xa0, v144
	v_mad_i64_i32 v[32:33], s[42:43], v32, s49, v[146:147]
	v_mul_f32_e32 v35, v34, v34
	v_mul_f32_e32 v34, 0xbfb8aa3b, v34
	v_mul_f32_e32 v36, v28, v35
	v_mul_f32_e32 v28, v28, v34
	v_exp_f32_e32 v28, v28
	s_nop 0
	v_add_f32_e32 v28, 1.0, v28
	v_rcp_f32_e32 v28, v28
	s_nop 0
	v_mul_f32_e32 v28, v36, v28
	v_mul_f32_e32 v28, v20, v28
	v_mul_f32_e32 v20, v24, v35
	v_mul_f32_e32 v24, v24, v34
	v_exp_f32_e32 v24, v24
	s_nop 0
	v_add_f32_e32 v24, 1.0, v24
	v_rcp_f32_e32 v24, v24
	s_nop 0
	v_mul_f32_e32 v20, v20, v24
	v_mul_f32_e32 v24, v16, v20
	v_mul_f32_e32 v20, v29, v34
	v_exp_f32_e32 v20, v20
	v_mul_f32_e32 v16, v29, v35
	v_add_f32_e32 v20, 1.0, v20
	v_rcp_f32_e32 v20, v20
	s_nop 0
	v_mul_f32_e32 v16, v16, v20
	v_mul_f32_e32 v16, v21, v16
	v_mul_f32_e32 v21, v25, v34
	v_exp_f32_e32 v21, v21
	v_mul_f32_e32 v20, v25, v35
	v_cvt_pk_bf16_f32 v16, v28, v16
	v_add_f32_e32 v21, 1.0, v21
	v_rcp_f32_e32 v21, v21
	s_nop 0
	v_mul_f32_e32 v20, v20, v21
	v_mul_f32_e32 v25, v17, v20
	v_mul_f32_e32 v20, v30, v34
	v_exp_f32_e32 v20, v20
	v_mul_f32_e32 v21, v26, v34
	v_exp_f32_e32 v21, v21
	v_mul_f32_e32 v17, v30, v35
	v_add_f32_e32 v20, 1.0, v20
	v_rcp_f32_e32 v20, v20
	v_add_f32_e32 v21, 1.0, v21
	v_rcp_f32_e32 v21, v21
	v_mul_f32_e32 v17, v17, v20
	v_mul_f32_e32 v20, v26, v35
	v_mul_f32_e32 v20, v20, v21
	v_mul_f32_e32 v17, v22, v17
	v_mul_f32_e32 v22, v18, v20
	v_mul_f32_e32 v20, v31, v34
	v_exp_f32_e32 v20, v20
	v_mul_f32_e32 v21, v27, v34
	v_exp_f32_e32 v21, v21
	v_mul_f32_e32 v18, v31, v35
	v_add_f32_e32 v20, 1.0, v20
	v_rcp_f32_e32 v20, v20
	v_add_f32_e32 v21, 1.0, v21
	v_rcp_f32_e32 v21, v21
	v_mul_f32_e32 v18, v18, v20
	v_mul_f32_e32 v20, v27, v35
	v_mul_f32_e32 v20, v20, v21
	v_mul_f32_e32 v18, v23, v18
	v_mul_f32_e32 v19, v19, v20
	v_lshl_add_u64 v[20:21], v[32:33], 0, v[112:113]
	v_cvt_pk_bf16_f32 v17, v17, v18
	v_cvt_pk_bf16_f32 v18, v24, v25
	v_cvt_pk_bf16_f32 v19, v22, v19
	global_store_dwordx4 v[20:21], v[16:19], off
	s_nop 1
	v_mov_b32_e32 v18, v210
	s_nop 0
	v_add_u32_e32 v16, 0xb0, v144
	v_mad_i64_i32 v[16:17], s[42:43], v16, s49, v[146:147]
	s_mov_b64 s[42:43], s[26:27]
	v_mul_f32_e32 v19, v18, v18
	v_mul_f32_e32 v18, 0xbfb8aa3b, v18
	v_mul_f32_e32 v20, v12, v19
	v_mul_f32_e32 v12, v12, v18
	v_exp_f32_e32 v12, v12
	s_nop 0
	v_add_f32_e32 v12, 1.0, v12
	v_rcp_f32_e32 v12, v12
	s_nop 0
	v_mul_f32_e32 v12, v20, v12
	v_mul_f32_e32 v12, v4, v12
	v_mul_f32_e32 v4, v8, v19
	v_mul_f32_e32 v8, v8, v18
	v_exp_f32_e32 v8, v8
	s_nop 0
	v_add_f32_e32 v8, 1.0, v8
	v_rcp_f32_e32 v8, v8
	s_nop 0
	v_mul_f32_e32 v4, v4, v8
	v_mul_f32_e32 v8, v0, v4
	v_mul_f32_e32 v4, v13, v18
	v_exp_f32_e32 v4, v4
	v_mul_f32_e32 v0, v13, v19
	v_add_f32_e32 v4, 1.0, v4
	v_rcp_f32_e32 v4, v4
	s_nop 0
	v_mul_f32_e32 v0, v0, v4
	v_mul_f32_e32 v0, v5, v0
	v_mul_f32_e32 v5, v9, v18
	v_exp_f32_e32 v5, v5
	v_mul_f32_e32 v4, v9, v19
	v_cvt_pk_bf16_f32 v0, v12, v0
	v_add_f32_e32 v5, 1.0, v5
	v_rcp_f32_e32 v5, v5
	s_nop 0
	v_mul_f32_e32 v4, v4, v5
	v_mul_f32_e32 v9, v1, v4
	v_mul_f32_e32 v4, v14, v18
	v_exp_f32_e32 v4, v4
	v_mul_f32_e32 v5, v10, v18
	v_exp_f32_e32 v5, v5
	v_mul_f32_e32 v1, v14, v19
	v_add_f32_e32 v4, 1.0, v4
	v_rcp_f32_e32 v4, v4
	v_add_f32_e32 v5, 1.0, v5
	v_rcp_f32_e32 v5, v5
	v_mul_f32_e32 v1, v1, v4
	v_mul_f32_e32 v4, v10, v19
	v_mul_f32_e32 v4, v4, v5
	v_mul_f32_e32 v1, v6, v1
	v_mul_f32_e32 v6, v2, v4
	v_mul_f32_e32 v4, v15, v18
	v_exp_f32_e32 v4, v4
	v_mul_f32_e32 v5, v11, v18
	v_exp_f32_e32 v5, v5
	v_mul_f32_e32 v2, v15, v19
	v_add_f32_e32 v4, 1.0, v4
	v_rcp_f32_e32 v4, v4
	v_add_f32_e32 v5, 1.0, v5
	v_rcp_f32_e32 v5, v5
	v_mul_f32_e32 v2, v2, v4
	v_mul_f32_e32 v4, v11, v19
	v_mul_f32_e32 v4, v4, v5
	v_mul_f32_e32 v2, v7, v2
	v_mul_f32_e32 v3, v3, v4
	v_lshl_add_u64 v[4:5], v[16:17], 0, v[112:113]
	v_cvt_pk_bf16_f32 v1, v1, v2
	v_cvt_pk_bf16_f32 v2, v8, v9
	v_cvt_pk_bf16_f32 v3, v6, v3
	global_store_dwordx4 v[4:5], v[0:3], off
	s_cbranch_vccz .LBB0_200
	s_waitcnt vmcnt(0)
	s_cmpk_gt_u32 s3, 0xff
	s_cbranch_scc1 .LBB0_207
	s_barrier

; #define PG8_STAGE(bufoff, gbase, voff) do { _Pragma("unroll") for (int _i = 0; _i < 2; ++_i) \
;         __builtin_amdgcn_global_load_lds((const unsigned*)((const char*)(gbase) + (voff)[_i]), (LAS unsigned*)(lds + (bufoff) + ldsw + _i * 8192), 16, 0, 0); } while (0)
; #define PG8_LDA(dst, b, h) do { _Pragma("unroll") for (int m = 0; m < 4; ++m) _Pragma("unroll") for (int k = 0; k < 2; ++k) dst[m][k] = *(const LAS bf16x8*)(lds + PG8_SA(b, h) + aoff + m * 2048 + k * 1024); } while (0)
; #define PG8_LDB(dst, b, h) do { _Pragma("unroll") for (int n = 0; n < 2; ++n) _Pragma("unroll") for (int k = 0; k < 2; ++k) dst[n][k] = *(const LAS bf16x8*)(lds + PG8_SB(b, h) + boff + n * 2048 + k * 1024); } while (0)
; #define PG8_WAIT_V(n) asm volatile("s_waitcnt vmcnt(" #n ")" ::: "memory")
; #define PG8_WAIT_L(n) asm volatile("s_waitcnt lgkmcnt(" #n ")" ::: "memory")
; #define PG8_BAR __builtin_amdgcn_s_barrier()
; #define PG8_SCHED __builtin_amdgcn_sched_barrier(0)
; template <class Epi>
; __device__ __forceinline__ void gemm_phase(LAS unsigned char* lds, const Gemm g, const StaticOrder& S, const Epi& E) {
;     ...
;         const bool has_next = S.next(ui + 1, nxt);
;         const char* nA = has_next ? (const char*)g.A + (size_t)nxt.pm * tstep : cA; const char* nB = has_next ? (const char*)g.Bt + (size_t)nxt.pn * tstep : cB;
;         for (int t = 0; t < nt; t += 2) {
;             const bool last = (t == nt - 2);
;             const char* a1 = cA + (size_t)(t + 1) * kstep;
;             const char* a2 = last ? nA : cA + (size_t)(t + 2) * kstep; const char* b2 = last ? nB : cB + (size_t)(t + 2) * kstep;
;             const char* a3 = a2 + kstep; const char* b3 = b2 + kstep;
;             PG8_LDB(B0, 0, 0); PG8_SCHED; PG8_LDA(At, 0, 0); PG8_STAGE(PG8_SA(1, 1), a1 + hstep, voffA);
;             PG8_WAIT_L(8); PG8_BAR; PG8_WAIT_L(0); PG8_MMA(0, 0, At, B0); PG8_BAR; PG8_SCHED;
;             PG8_LDB(B1, 0, 1); PG8_STAGE(PG8_SB(0, 0), b2, voffB);
;             PG8_BAR; PG8_WAIT_L(0); PG8_MMA(0, 1, At, B1); PG8_BAR;
;             PG8_LDA(At, 0, 1); PG8_STAGE(PG8_SA(0, 0), a2, voffA);
;             PG8_BAR; PG8_WAIT_L(0); PG8_MMA(1, 0, At, B0); PG8_BAR; PG8_SCHED;
;             PG8_STAGE(PG8_SB(0, 1), b2 + hstep, voffB);
;             PG8_WAIT_V(6); PG8_BAR; PG8_MMA(1, 1, At, B1); PG8_BAR;
.LBB0_283:
	ds_read_b128 v[148:151], v145
	ds_read_b128 v[152:155], v145 offset:1024
	ds_read_b128 v[160:163], v145 offset:2048
	ds_read_b128 v[164:167], v145 offset:3072
	s_add_u32 s50, s48, 0x100
	s_addc_u32 s51, s49, 0
	s_cmpk_eq_i32 s65, 0x54
	s_cselect_b32 s55, s47, s51
	s_cselect_b32 s54, s46, s50
	s_cselect_b32 s53, s5, s64
	s_cselect_b32 s52, s4, s63
	s_add_i32 m0, s23, 0xc000
	ds_read_b128 v[168:171], v146
	ds_read_b128 v[172:175], v146 offset:1024
	ds_read_b128 v[176:179], v146 offset:2048
	ds_read_b128 v[180:183], v146 offset:3072
	ds_read_b128 v[184:187], v146 offset:4096
	ds_read_b128 v[188:191], v146 offset:5120
	ds_read_b128 v[192:195], v146 offset:6144
	ds_read_b128 v[196:199], v146 offset:7168
	global_load_lds_dwordx4 v136, s[48:49]
	s_add_i32 m0, s23, 0xe000
	s_nop 0
	global_load_lds_dwordx4 v138, s[48:49]
	s_waitcnt lgkmcnt(8)
	s_barrier
	s_waitcnt lgkmcnt(0)
	v_mfma_f32_16x16x32_bf16 v[124:127], v[148:151], v[168:171], v[124:127]
	v_mfma_f32_16x16x32_bf16 v[120:123], v[160:163], v[168:171], v[120:123]
	v_mfma_f32_16x16x32_bf16 v[112:115], v[148:151], v[176:179], v[112:115]
	v_mfma_f32_16x16x32_bf16 v[104:107], v[160:163], v[176:179], v[104:107]
	v_mfma_f32_16x16x32_bf16 v[96:99], v[148:151], v[184:187], v[96:99]
	v_mfma_f32_16x16x32_bf16 v[88:91], v[160:163], v[184:187], v[88:91]
	v_mfma_f32_16x16x32_bf16 v[80:83], v[148:151], v[192:195], v[80:83]
	v_mfma_f32_16x16x32_bf16 v[72:75], v[160:163], v[192:195], v[72:75]
	v_mfma_f32_16x16x32_bf16 v[124:127], v[152:155], v[172:175], v[124:127]
	v_mfma_f32_16x16x32_bf16 v[120:123], v[164:167], v[172:175], v[120:123]
	v_mfma_f32_16x16x32_bf16 v[112:115], v[152:155], v[180:183], v[112:115]
	v_mfma_f32_16x16x32_bf16 v[104:107], v[164:167], v[180:183], v[104:107]
	v_mfma_f32_16x16x32_bf16 v[96:99], v[152:155], v[188:191], v[96:99]
	v_mfma_f32_16x16x32_bf16 v[88:91], v[164:167], v[188:191], v[88:91]
	v_mfma_f32_16x16x32_bf16 v[80:83], v[152:155], v[196:199], v[80:83]
	v_mfma_f32_16x16x32_bf16 v[72:75], v[164:167], v[196:199], v[72:75]
	s_barrier
	s_add_i32 s48, s39, s13
	s_add_u32 s98, s52, s6
	s_addc_u32 s99, s53, s7
	s_mov_b32 m0, s48
	ds_read_b128 v[200:203], v147
	ds_read_b128 v[204:207], v147 offset:1024
	ds_read_b128 v[208:211], v147 offset:2048
	ds_read_b128 v[212:215], v147 offset:3072
	global_load_lds_dwordx4 v132, s[52:53]
	s_add_i32 m0, s48, 0x2000
	s_nop 0
	global_load_lds_dwordx4 v128, s[52:53]
	s_waitcnt lgkmcnt(0)
	s_barrier
	v_mfma_f32_16x16x32_bf16 v[116:119], v[200:203], v[168:171], v[116:119]
	v_mfma_f32_16x16x32_bf16 v[108:111], v[208:211], v[168:171], v[108:111]
	v_mfma_f32_16x16x32_bf16 v[100:103], v[200:203], v[176:179], v[100:103]
	v_mfma_f32_16x16x32_bf16 v[92:95], v[208:211], v[176:179], v[92:95]
	v_mfma_f32_16x16x32_bf16 v[84:87], v[200:203], v[184:187], v[84:87]
	v_mfma_f32_16x16x32_bf16 v[76:79], v[208:211], v[184:187], v[76:79]
	v_mfma_f32_16x16x32_bf16 v[68:71], v[200:203], v[192:195], v[68:71]
	v_mfma_f32_16x16x32_bf16 v[64:67], v[208:211], v[192:195], v[64:67]
	v_mfma_f32_16x16x32_bf16 v[116:119], v[204:207], v[172:175], v[116:119]
	v_mfma_f32_16x16x32_bf16 v[108:111], v[212:215], v[172:175], v[108:111]
	v_mfma_f32_16x16x32_bf16 v[100:103], v[204:207], v[180:183], v[100:103]
	v_mfma_f32_16x16x32_bf16 v[92:95], v[212:215], v[180:183], v[92:95]
	v_mfma_f32_16x16x32_bf16 v[84:87], v[204:207], v[188:191], v[84:87]
	v_mfma_f32_16x16x32_bf16 v[76:79], v[212:215], v[188:191], v[76:79]
	v_mfma_f32_16x16x32_bf16 v[68:71], v[204:207], v[196:199], v[68:71]
	v_mfma_f32_16x16x32_bf16 v[64:67], v[212:215], v[196:199], v[64:67]
	s_mov_b32 m0, s23
	s_add_u32 s100, s54, s6
	s_addc_u32 s101, s55, s7
	s_barrier
	ds_read_b128 v[168:171], v146 offset:16384
	ds_read_b128 v[172:175], v146 offset:17408
	ds_read_b128 v[176:179], v146 offset:18432
	ds_read_b128 v[180:183], v146 offset:19456
	ds_read_b128 v[184:187], v146 offset:20480
	ds_read_b128 v[188:191], v146 offset:21504
	ds_read_b128 v[192:195], v146 offset:22528
	ds_read_b128 v[196:199], v146 offset:23552
	global_load_lds_dwordx4 v134, s[54:55]
	s_mov_b32 m0, s30
	s_nop 0
	global_load_lds_dwordx4 v130, s[54:55]
	s_waitcnt lgkmcnt(0)
	s_barrier
	v_mfma_f32_16x16x32_bf16 v[60:63], v[148:151], v[168:171], v[60:63]
	v_mfma_f32_16x16x32_bf16 v[56:59], v[160:163], v[168:171], v[56:59]
	v_mfma_f32_16x16x32_bf16 v[52:55], v[148:151], v[176:179], v[52:55]
	v_mfma_f32_16x16x32_bf16 v[44:47], v[160:163], v[176:179], v[44:47]
	v_mfma_f32_16x16x32_bf16 v[36:39], v[148:151], v[184:187], v[36:39]
	v_mfma_f32_16x16x32_bf16 v[28:31], v[160:163], v[184:187], v[28:31]
	v_mfma_f32_16x16x32_bf16 v[20:23], v[148:151], v[192:195], v[20:23]
	v_mfma_f32_16x16x32_bf16 v[12:15], v[160:163], v[192:195], v[12:15]
	v_mfma_f32_16x16x32_bf16 v[60:63], v[152:155], v[172:175], v[60:63]
	v_mfma_f32_16x16x32_bf16 v[56:59], v[164:167], v[172:175], v[56:59]
	v_mfma_f32_16x16x32_bf16 v[52:55], v[152:155], v[180:183], v[52:55]
	v_mfma_f32_16x16x32_bf16 v[44:47], v[164:167], v[180:183], v[44:47]
	v_mfma_f32_16x16x32_bf16 v[36:39], v[152:155], v[188:191], v[36:39]
	v_mfma_f32_16x16x32_bf16 v[28:31], v[164:167], v[188:191], v[28:31]
	v_mfma_f32_16x16x32_bf16 v[20:23], v[152:155], v[196:199], v[20:23]
	v_mfma_f32_16x16x32_bf16 v[12:15], v[164:167], v[196:199], v[12:15]
	s_barrier
	s_add_u32 s48, s52, 0x160000
	s_addc_u32 s49, s53, 0
	s_add_i32 s66, s40, s13
	s_mov_b32 m0, s66
	s_nop 0
	global_load_lds_dwordx4 v132, s[48:49]
	s_add_i32 m0, s66, 0x2000
	s_nop 0
	global_load_lds_dwordx4 v128, s[48:49]
	s_waitcnt vmcnt(6)
	s_barrier
; #define PG8_STAGE(bufoff, gbase, voff) do { _Pragma("unroll") for (int _i = 0; _i < 2; ++_i) \
;         __builtin_amdgcn_global_load_lds((const unsigned*)((const char*)(gbase) + (voff)[_i]), (LAS unsigned*)(lds + (bufoff) + ldsw + _i * 8192), 16, 0, 0); } while (0)
; #define PG8_LDA(dst, b, h) do { _Pragma("unroll") for (int m = 0; m < 4; ++m) _Pragma("unroll") for (int k = 0; k < 2; ++k) dst[m][k] = *(const LAS bf16x8*)(lds + PG8_SA(b, h) + aoff + m * 2048 + k * 1024); } while (0)
; #define PG8_LDB(dst, b, h) do { _Pragma("unroll") for (int n = 0; n < 2; ++n) _Pragma("unroll") for (int k = 0; k < 2; ++k) dst[n][k] = *(const LAS bf16x8*)(lds + PG8_SB(b, h) + boff + n * 2048 + k * 1024); } while (0)
; #define PG8_MMA(ai, bj, At, Bt) do { __builtin_amdgcn_s_setprio(1); _Pragma("unroll") for (int m = 0; m < 4; ++m) _Pragma("unroll") for (int n = 0; n < 2; ++n) _Pragma("unroll") for (int k = 0; k < 2; ++k) \
;         acc[ai][bj][m][n] = __builtin_amdgcn_mfma_f32_16x16x32_bf16(Bt[n][k], At[m][k], acc[ai][bj][m][n], 0, 0, 0); __builtin_amdgcn_s_setprio(0); } while (0)
; #define PG8_WAIT_V(n) asm volatile("s_waitcnt vmcnt(" #n ")" ::: "memory")
; #define PG8_WAIT_L(n) asm volatile("s_waitcnt lgkmcnt(" #n ")" ::: "memory")
; #define PG8_BAR __builtin_amdgcn_s_barrier()
; #define PG8_SCHED __builtin_amdgcn_sched_barrier(0)
; template <class Epi>
; __device__ __forceinline__ void gemm_phase(LAS unsigned char* lds, const Gemm g, const StaticOrder& S, const Epi& E) {
;     ...
;             PG8_WAIT_V(6); PG8_BAR; PG8_MMA(1, 1, At, B1); PG8_BAR;
;             PG8_LDB(B0, 1, 0); PG8_SCHED; PG8_LDA(At, 1, 0); PG8_STAGE(PG8_SA(0, 1), a2 + hstep, voffA);
;             PG8_WAIT_L(8); PG8_BAR; PG8_WAIT_L(0); PG8_MMA(0, 0, At, B0); PG8_BAR; PG8_SCHED;
;             PG8_LDB(B1, 1, 1); PG8_STAGE(PG8_SB(1, 0), b3, voffB);
;             PG8_BAR; PG8_WAIT_L(0); PG8_MMA(0, 1, At, B1); PG8_BAR;
;             PG8_LDA(At, 1, 1); PG8_STAGE(PG8_SA(1, 0), a3, voffA);
;             PG8_BAR; PG8_WAIT_L(0); PG8_MMA(1, 0, At, B0); PG8_BAR; PG8_SCHED;
	v_mfma_f32_16x16x32_bf16 v[48:51], v[200:203], v[168:171], v[48:51]
	v_mfma_f32_16x16x32_bf16 v[40:43], v[208:211], v[168:171], v[40:43]
	v_mfma_f32_16x16x32_bf16 v[32:35], v[200:203], v[176:179], v[32:35]
	v_mfma_f32_16x16x32_bf16 v[24:27], v[208:211], v[176:179], v[24:27]
	v_mfma_f32_16x16x32_bf16 v[16:19], v[200:203], v[184:187], v[16:19]
	v_mfma_f32_16x16x32_bf16 v[8:11], v[208:211], v[184:187], v[8:11]
	v_mfma_f32_16x16x32_bf16 v[4:7], v[200:203], v[192:195], v[4:7]
	v_mfma_f32_16x16x32_bf16 v[0:3], v[208:211], v[192:195], v[0:3]
	v_mfma_f32_16x16x32_bf16 v[48:51], v[204:207], v[172:175], v[48:51]
	v_mfma_f32_16x16x32_bf16 v[40:43], v[212:215], v[172:175], v[40:43]
	v_mfma_f32_16x16x32_bf16 v[32:35], v[204:207], v[180:183], v[32:35]
	v_mfma_f32_16x16x32_bf16 v[24:27], v[212:215], v[180:183], v[24:27]
	v_mfma_f32_16x16x32_bf16 v[16:19], v[204:207], v[188:191], v[16:19]
	v_mfma_f32_16x16x32_bf16 v[8:11], v[212:215], v[188:191], v[8:11]
	v_mfma_f32_16x16x32_bf16 v[4:7], v[204:207], v[196:199], v[4:7]
	v_mfma_f32_16x16x32_bf16 v[0:3], v[212:215], v[196:199], v[0:3]
	s_add_i32 s66, 0, 0x18000
	v_add_u32_e32 v164, s66, v143
	s_barrier
	ds_read_b128 v[148:151], v164
	ds_read_b128 v[152:155], v164 offset:1024
	ds_read_b128 v[160:163], v164 offset:2048
	ds_read_b128 v[164:167], v164 offset:3072
	s_add_u32 s48, s54, 0x160000
	s_addc_u32 s49, s55, 0
	s_mov_b32 m0, s31
	ds_read_b128 v[168:171], v146 offset:32768
	ds_read_b128 v[172:175], v146 offset:33792
	ds_read_b128 v[176:179], v146 offset:34816
	ds_read_b128 v[180:183], v146 offset:35840
	ds_read_b128 v[184:187], v146 offset:36864
	ds_read_b128 v[188:191], v146 offset:37888
	ds_read_b128 v[192:195], v146 offset:38912
	ds_read_b128 v[196:199], v146 offset:39936
	global_load_lds_dwordx4 v134, s[48:49]
	s_mov_b32 m0, s33
	s_nop 0
	global_load_lds_dwordx4 v130, s[48:49]
	s_waitcnt lgkmcnt(8)
	s_barrier
	s_waitcnt lgkmcnt(0)
	v_mfma_f32_16x16x32_bf16 v[124:127], v[148:151], v[168:171], v[124:127]
	v_mfma_f32_16x16x32_bf16 v[120:123], v[160:163], v[168:171], v[120:123]
	v_mfma_f32_16x16x32_bf16 v[112:115], v[148:151], v[176:179], v[112:115]
	v_mfma_f32_16x16x32_bf16 v[104:107], v[160:163], v[176:179], v[104:107]
	v_mfma_f32_16x16x32_bf16 v[96:99], v[148:151], v[184:187], v[96:99]
	v_mfma_f32_16x16x32_bf16 v[88:91], v[160:163], v[184:187], v[88:91]
	v_mfma_f32_16x16x32_bf16 v[80:83], v[148:151], v[192:195], v[80:83]
	v_mfma_f32_16x16x32_bf16 v[72:75], v[160:163], v[192:195], v[72:75]
	v_mfma_f32_16x16x32_bf16 v[124:127], v[152:155], v[172:175], v[124:127]
	v_mfma_f32_16x16x32_bf16 v[120:123], v[164:167], v[172:175], v[120:123]
	v_mfma_f32_16x16x32_bf16 v[112:115], v[152:155], v[180:183], v[112:115]
	v_mfma_f32_16x16x32_bf16 v[104:107], v[164:167], v[180:183], v[104:107]
	v_mfma_f32_16x16x32_bf16 v[96:99], v[152:155], v[188:191], v[96:99]
	v_mfma_f32_16x16x32_bf16 v[88:91], v[164:167], v[188:191], v[88:91]
	v_mfma_f32_16x16x32_bf16 v[80:83], v[152:155], v[196:199], v[80:83]
	v_mfma_f32_16x16x32_bf16 v[72:75], v[164:167], v[196:199], v[72:75]
	s_barrier
	s_add_i32 s54, 0, 0x1c000
	s_add_i32 s48, s66, s13
	v_add_u32_e32 v212, s54, v143
	s_mov_b32 m0, s48
	ds_read_b128 v[200:203], v212
	ds_read_b128 v[204:207], v212 offset:1024
	ds_read_b128 v[208:211], v212 offset:2048
	ds_read_b128 v[212:215], v212 offset:3072
	global_load_lds_dwordx4 v132, s[98:99]
	s_add_i32 m0, s48, 0x2000
	s_nop 0
	global_load_lds_dwordx4 v128, s[98:99]
	s_waitcnt lgkmcnt(0)
	s_barrier
	v_mfma_f32_16x16x32_bf16 v[116:119], v[200:203], v[168:171], v[116:119]
	v_mfma_f32_16x16x32_bf16 v[108:111], v[208:211], v[168:171], v[108:111]
	v_mfma_f32_16x16x32_bf16 v[100:103], v[200:203], v[176:179], v[100:103]
	v_mfma_f32_16x16x32_bf16 v[92:95], v[208:211], v[176:179], v[92:95]
	v_mfma_f32_16x16x32_bf16 v[84:87], v[200:203], v[184:187], v[84:87]
	v_mfma_f32_16x16x32_bf16 v[76:79], v[208:211], v[184:187], v[76:79]
	v_mfma_f32_16x16x32_bf16 v[68:71], v[200:203], v[192:195], v[68:71]
	v_mfma_f32_16x16x32_bf16 v[64:67], v[208:211], v[192:195], v[64:67]
	v_mfma_f32_16x16x32_bf16 v[116:119], v[204:207], v[172:175], v[116:119]
	v_mfma_f32_16x16x32_bf16 v[108:111], v[212:215], v[172:175], v[108:111]
	v_mfma_f32_16x16x32_bf16 v[100:103], v[204:207], v[180:183], v[100:103]
	v_mfma_f32_16x16x32_bf16 v[92:95], v[212:215], v[180:183], v[92:95]
	v_mfma_f32_16x16x32_bf16 v[84:87], v[204:207], v[188:191], v[84:87]
	v_mfma_f32_16x16x32_bf16 v[76:79], v[212:215], v[188:191], v[76:79]
	v_mfma_f32_16x16x32_bf16 v[68:71], v[204:207], v[196:199], v[68:71]
	v_mfma_f32_16x16x32_bf16 v[64:67], v[212:215], v[196:199], v[64:67]
	s_mov_b32 m0, s34
	s_barrier
	ds_read_b128 v[168:171], v146 offset:49152
	ds_read_b128 v[172:175], v146 offset:50176
	ds_read_b128 v[176:179], v146 offset:51200
	ds_read_b128 v[180:183], v146 offset:52224
	ds_read_b128 v[184:187], v146 offset:53248
	ds_read_b128 v[188:191], v146 offset:54272
	ds_read_b128 v[192:195], v146 offset:55296
	ds_read_b128 v[196:199], v146 offset:56320
	global_load_lds_dwordx4 v134, s[100:101]
	s_mov_b32 m0, s36
	s_nop 0
	global_load_lds_dwordx4 v130, s[100:101]
	s_waitcnt lgkmcnt(0)
	s_barrier
; #define PG8_STAGE(bufoff, gbase, voff) do { _Pragma("unroll") for (int _i = 0; _i < 2; ++_i) \
;         __builtin_amdgcn_global_load_lds((const unsigned*)((const char*)(gbase) + (voff)[_i]), (LAS unsigned*)(lds + (bufoff) + ldsw + _i * 8192), 16, 0, 0); } while (0)
; #define PG8_MMA(ai, bj, At, Bt) do { __builtin_amdgcn_s_setprio(1); _Pragma("unroll") for (int m = 0; m < 4; ++m) _Pragma("unroll") for (int n = 0; n < 2; ++n) _Pragma("unroll") for (int k = 0; k < 2; ++k) \
;         acc[ai][bj][m][n] = __builtin_amdgcn_mfma_f32_16x16x32_bf16(Bt[n][k], At[m][k], acc[ai][bj][m][n], 0, 0, 0); __builtin_amdgcn_s_setprio(0); } while (0)
; #define PG8_WAIT_V(n) asm volatile("s_waitcnt vmcnt(" #n ")" ::: "memory")
; #define PG8_WAIT_L(n) asm volatile("s_waitcnt lgkmcnt(" #n ")" ::: "memory")
; #define PG8_BAR __builtin_amdgcn_s_barrier()
; #define PG8_SCHED __builtin_amdgcn_sched_barrier(0)
; template <class Epi>
; __device__ __forceinline__ void gemm_phase(LAS unsigned char* lds, const Gemm g, const StaticOrder& S, const Epi& E) {
;     ...
;         for (int t = 0; t < nt; t += 2) {
;     ...
;             PG8_BAR; PG8_WAIT_L(0); PG8_MMA(1, 0, At, B0); PG8_BAR; PG8_SCHED;
;             PG8_STAGE(PG8_SB(1, 1), b3 + hstep, voffB);
;             PG8_WAIT_V(6); PG8_BAR; PG8_MMA(1, 1, At, B1); PG8_BAR;
	v_mfma_f32_16x16x32_bf16 v[60:63], v[148:151], v[168:171], v[60:63]
	v_mfma_f32_16x16x32_bf16 v[56:59], v[160:163], v[168:171], v[56:59]
	v_mfma_f32_16x16x32_bf16 v[52:55], v[148:151], v[176:179], v[52:55]
	v_mfma_f32_16x16x32_bf16 v[44:47], v[160:163], v[176:179], v[44:47]
	v_mfma_f32_16x16x32_bf16 v[36:39], v[148:151], v[184:187], v[36:39]
	v_mfma_f32_16x16x32_bf16 v[28:31], v[160:163], v[184:187], v[28:31]
	v_mfma_f32_16x16x32_bf16 v[20:23], v[148:151], v[192:195], v[20:23]
	v_mfma_f32_16x16x32_bf16 v[12:15], v[160:163], v[192:195], v[12:15]
	v_mfma_f32_16x16x32_bf16 v[60:63], v[152:155], v[172:175], v[60:63]
	v_mfma_f32_16x16x32_bf16 v[56:59], v[164:167], v[172:175], v[56:59]
	v_mfma_f32_16x16x32_bf16 v[52:55], v[152:155], v[180:183], v[52:55]
	v_mfma_f32_16x16x32_bf16 v[44:47], v[164:167], v[180:183], v[44:47]
	v_mfma_f32_16x16x32_bf16 v[36:39], v[152:155], v[188:191], v[36:39]
	v_mfma_f32_16x16x32_bf16 v[28:31], v[164:167], v[188:191], v[28:31]
	v_mfma_f32_16x16x32_bf16 v[20:23], v[152:155], v[196:199], v[20:23]
	v_mfma_f32_16x16x32_bf16 v[12:15], v[164:167], v[196:199], v[12:15]
	s_barrier
	s_add_u32 s48, s52, 0x160080
	s_addc_u32 s49, s53, 0
	s_add_i32 s52, s54, s13
	s_mov_b32 m0, s52
	s_nop 0
	global_load_lds_dwordx4 v132, s[48:49]
	s_add_i32 m0, s52, 0x2000
	s_nop 0
	global_load_lds_dwordx4 v128, s[48:49]
	s_waitcnt vmcnt(6)
	s_barrier
	v_mfma_f32_16x16x32_bf16 v[48:51], v[200:203], v[168:171], v[48:51]
	v_mfma_f32_16x16x32_bf16 v[40:43], v[208:211], v[168:171], v[40:43]
	v_mfma_f32_16x16x32_bf16 v[32:35], v[200:203], v[176:179], v[32:35]
	v_mfma_f32_16x16x32_bf16 v[24:27], v[208:211], v[176:179], v[24:27]
	v_mfma_f32_16x16x32_bf16 v[16:19], v[200:203], v[184:187], v[16:19]
	v_mfma_f32_16x16x32_bf16 v[8:11], v[208:211], v[184:187], v[8:11]
	v_mfma_f32_16x16x32_bf16 v[4:7], v[200:203], v[192:195], v[4:7]
	v_mfma_f32_16x16x32_bf16 v[0:3], v[208:211], v[192:195], v[0:3]
	v_mfma_f32_16x16x32_bf16 v[48:51], v[204:207], v[172:175], v[48:51]
	v_mfma_f32_16x16x32_bf16 v[40:43], v[212:215], v[172:175], v[40:43]
	v_mfma_f32_16x16x32_bf16 v[32:35], v[204:207], v[180:183], v[32:35]
	v_mfma_f32_16x16x32_bf16 v[24:27], v[212:215], v[180:183], v[24:27]
	v_mfma_f32_16x16x32_bf16 v[16:19], v[204:207], v[188:191], v[16:19]
	v_mfma_f32_16x16x32_bf16 v[8:11], v[212:215], v[188:191], v[8:11]
	v_mfma_f32_16x16x32_bf16 v[4:7], v[204:207], v[196:199], v[4:7]
	v_mfma_f32_16x16x32_bf16 v[0:3], v[212:215], v[196:199], v[0:3]
	s_add_i32 s65, s65, 2
	s_add_u32 s63, s63, 0x100
	s_addc_u32 s64, s64, 0
	s_cmpk_gt_u32 s65, 0x55
	s_mov_b64 s[48:49], s[50:51]
	s_barrier
	s_cbranch_scc0 .LBB0_283
; #define PG8_WAIT_V(n) asm volatile("s_waitcnt vmcnt(" #n ")" ::: "memory")
; #define PG8_BAR __builtin_amdgcn_s_barrier()
; __device__ __forceinline__ u32x4 pack8(f32x4 v0, f32x4 v1) { u32x4 w; w.x = cvt_pk_bf16(v0[0], v0[1]); w.y = cvt_pk_bf16(v0[2], v0[3]); w.z = cvt_pk_bf16(v1[0], v1[1]); w.w = cvt_pk_bf16(v1[2], v1[3]); return w; }
; template <class Epi>
; __device__ __forceinline__ void gemm_phase(LAS unsigned char* lds, const Gemm g, const StaticOrder& S, const Epi& E) {
;     ...
;         if (!has_next) break;
; #pragma unroll
;         for (int a = 0; a < 2; ++a)
; #pragma unroll
;             for (int b = 0; b < 2; ++b)
; #pragma unroll
;                 for (int m = 0; m < 4; ++m)
; #pragma unroll
;                     for (int n = 0; n < 2; ++n) acc[a][b][m][n] = (f32x4){0.f, 0.f, 0.f, 0.f};
;         cur = nxt; cA = nA; cB = nB; ++ui;
;     }
;     PG8_WAIT_V(0);
;     if (wr == 0) PG8_BAR;
;     PG8_BAR;
;     __device__ __forceinline__ void operator()(const f32x4 (&acc)[2][2][4][2], const Unit& u, int wr, int wc, int fr, int fq) const {
;         const int row0 = u.pm * BM + wr * 64 + fr, col0 = u.pn * BM + wc * 32 + 8 * fq;
; #pragma unroll
;         for (int ai = 0; ai < 2; ++ai)
; #pragma unroll
;             for (int m = 0; m < 4; ++m) { bf16_t* rowp = O + (size_t)(row0 + ai * HALF + m * 16) * ldc + col0;
; #pragma unroll
;                 for (int bj = 0; bj < 2; ++bj) *(u32x4*)(rowp + bj * HALF) = pack8(acc[ai][bj][m][0], acc[ai][bj][m][1]); }
	v_lshl_add_u32 v148, s61, 8, v142
	v_lshl_or_b32 v140, s62, 8, v144
	v_ashrrev_i32_e32 v149, 31, v148
	v_ashrrev_i32_e32 v141, 31, v140
	v_lshlrev_b64 v[150:151], 12, v[148:149]
	v_lshl_add_u64 v[150:151], s[24:25], 0, v[150:151]
	v_lshlrev_b64 v[152:153], 1, v[140:141]
	v_lshl_add_u64 v[140:141], v[150:151], 0, v[152:153]
	v_cvt_pk_bf16_f32 v124, v124, v125
	v_cvt_pk_bf16_f32 v125, v126, v127
	v_cvt_pk_bf16_f32 v126, v120, v121
	v_cvt_pk_bf16_f32 v127, v122, v123
	global_store_dwordx4 v[140:141], v[124:127], off
	v_cvt_pk_bf16_f32 v116, v116, v117
	v_cvt_pk_bf16_f32 v117, v118, v119
	v_cvt_pk_bf16_f32 v118, v108, v109
	v_or_b32_e32 v108, 16, v148
	v_ashrrev_i32_e32 v109, 31, v108
	v_lshlrev_b64 v[108:109], 12, v[108:109]
	v_lshl_add_u64 v[108:109], s[24:25], 0, v[108:109]
	v_cvt_pk_bf16_f32 v119, v110, v111
	global_store_dwordx4 v[140:141], v[116:119], off offset:256
	s_mov_b32 s62, s59
	s_mov_b32 s61, s60
	v_lshl_add_u64 v[116:117], v[108:109], 0, v[152:153]
	v_cvt_pk_bf16_f32 v108, v112, v113
	v_cvt_pk_bf16_f32 v109, v114, v115
	v_cvt_pk_bf16_f32 v110, v104, v105
	v_cvt_pk_bf16_f32 v111, v106, v107
	global_store_dwordx4 v[116:117], v[108:111], off
	v_cvt_pk_bf16_f32 v100, v100, v101
	v_cvt_pk_bf16_f32 v101, v102, v103
	v_cvt_pk_bf16_f32 v102, v92, v93
	v_or_b32_e32 v92, 32, v148
	v_ashrrev_i32_e32 v93, 31, v92
	v_lshlrev_b64 v[92:93], 12, v[92:93]
	v_lshl_add_u64 v[92:93], s[24:25], 0, v[92:93]
	v_cvt_pk_bf16_f32 v103, v94, v95
	global_store_dwordx4 v[116:117], v[100:103], off offset:256
	s_mov_b64 s[50:51], s[4:5]
	s_mov_b64 s[48:49], s[46:47]
	v_lshl_add_u64 v[100:101], v[92:93], 0, v[152:153]
	v_cvt_pk_bf16_f32 v92, v96, v97
	v_cvt_pk_bf16_f32 v93, v98, v99
	v_cvt_pk_bf16_f32 v94, v88, v89
	v_cvt_pk_bf16_f32 v95, v90, v91
	global_store_dwordx4 v[100:101], v[92:95], off
	v_cvt_pk_bf16_f32 v84, v84, v85
	v_cvt_pk_bf16_f32 v85, v86, v87
	v_cvt_pk_bf16_f32 v86, v76, v77
	v_or_b32_e32 v76, 48, v148
	v_ashrrev_i32_e32 v77, 31, v76
	v_lshlrev_b64 v[76:77], 12, v[76:77]
	v_lshl_add_u64 v[76:77], s[24:25], 0, v[76:77]
	v_cvt_pk_bf16_f32 v87, v78, v79
	global_store_dwordx4 v[100:101], v[84:87], off offset:256
	s_nop 1
	v_lshl_add_u64 v[84:85], v[76:77], 0, v[152:153]
	v_cvt_pk_bf16_f32 v76, v80, v81
	v_cvt_pk_bf16_f32 v77, v82, v83
	v_cvt_pk_bf16_f32 v78, v72, v73
	v_cvt_pk_bf16_f32 v79, v74, v75
	global_store_dwordx4 v[84:85], v[76:79], off
	v_cvt_pk_bf16_f32 v68, v68, v69
	v_cvt_pk_bf16_f32 v69, v70, v71
	v_cvt_pk_bf16_f32 v70, v64, v65
	v_cvt_pk_bf16_f32 v71, v66, v67
	global_store_dwordx4 v[84:85], v[68:71], off offset:256
	v_cvt_pk_bf16_f32 v60, v60, v61
	v_cvt_pk_bf16_f32 v61, v62, v63
	v_cvt_pk_bf16_f32 v62, v56, v57
	v_add_co_u32_e32 v56, vcc, s41, v140
	v_lshl_add_u64 v[64:65], v[140:141], 0, s[8:9]
	s_nop 0
	v_addc_co_u32_e32 v57, vcc, 0, v141, vcc
	v_cvt_pk_bf16_f32 v63, v58, v59
	global_store_dwordx4 v[56:57], v[60:63], off
	v_cvt_pk_bf16_f32 v48, v48, v49
	v_cvt_pk_bf16_f32 v49, v50, v51
	v_cvt_pk_bf16_f32 v50, v40, v41
	v_cvt_pk_bf16_f32 v51, v42, v43
	global_store_dwordx4 v[64:65], v[48:51], off offset:256
	v_cvt_pk_bf16_f32 v40, v52, v53
	v_cvt_pk_bf16_f32 v41, v54, v55
	v_cvt_pk_bf16_f32 v42, v44, v45
	v_add_co_u32_e32 v44, vcc, s56, v140
	s_nop 0
	v_lshl_add_u64 v[48:49], v[140:141], 0, s[26:27]
	v_addc_co_u32_e32 v45, vcc, 0, v141, vcc
	v_cvt_pk_bf16_f32 v43, v46, v47
	global_store_dwordx4 v[44:45], v[40:43], off
	v_cvt_pk_bf16_f32 v32, v32, v33
	v_cvt_pk_bf16_f32 v33, v34, v35
	v_cvt_pk_bf16_f32 v34, v24, v25
	v_cvt_pk_bf16_f32 v35, v26, v27
	global_store_dwordx4 v[48:49], v[32:35], off offset:256
	v_cvt_pk_bf16_f32 v24, v36, v37
	v_cvt_pk_bf16_f32 v25, v38, v39
	v_cvt_pk_bf16_f32 v26, v28, v29
	v_add_co_u32_e32 v28, vcc, s57, v140
	s_nop 0
	v_lshl_add_u64 v[32:33], v[140:141], 0, s[28:29]
	v_addc_co_u32_e32 v29, vcc, 0, v141, vcc
	v_cvt_pk_bf16_f32 v27, v30, v31
	global_store_dwordx4 v[28:29], v[24:27], off
	v_cvt_pk_bf16_f32 v16, v16, v17
	v_cvt_pk_bf16_f32 v17, v18, v19
	v_cvt_pk_bf16_f32 v18, v8, v9
	v_cvt_pk_bf16_f32 v19, v10, v11
	global_store_dwordx4 v[32:33], v[16:19], off offset:256
	v_cvt_pk_bf16_f32 v8, v20, v21
	v_cvt_pk_bf16_f32 v9, v22, v23
	v_cvt_pk_bf16_f32 v10, v12, v13
	v_add_co_u32_e32 v12, vcc, s58, v140
	s_nop 0
	v_lshl_add_u64 v[16:17], v[140:141], 0, s[42:43]
	v_addc_co_u32_e32 v13, vcc, 0, v141, vcc
	s_and_b64 vcc, exec, s[44:45]
	v_cvt_pk_bf16_f32 v11, v14, v15
	global_store_dwordx4 v[12:13], v[8:11], off
	v_cvt_pk_bf16_f32 v4, v4, v5
	v_cvt_pk_bf16_f32 v5, v6, v7
	v_cvt_pk_bf16_f32 v6, v0, v1
	v_cvt_pk_bf16_f32 v7, v2, v3
	global_store_dwordx4 v[16:17], v[4:7], off offset:256
	s_cbranch_vccz .LBB0_276
	s_waitcnt vmcnt(0)
	s_cmpk_gt_u32 s3, 0xff
	v_readlane_b32 s62, v232, 20
	s_cbranch_scc1 .LBB0_287
	s_barrier

; #define PG8_STAGE(bufoff, gbase, voff) do { _Pragma("unroll") for (int _i = 0; _i < 2; ++_i) \
;         __builtin_amdgcn_global_load_lds((const unsigned*)((const char*)(gbase) + (voff)[_i]), (LAS unsigned*)(lds + (bufoff) + ldsw + _i * 8192), 16, 0, 0); } while (0)
; #define PG8_LDA(dst, b, h) do { _Pragma("unroll") for (int m = 0; m < 4; ++m) _Pragma("unroll") for (int k = 0; k < 2; ++k) dst[m][k] = *(const LAS bf16x8*)(lds + PG8_SA(b, h) + aoff + m * 2048 + k * 1024); } while (0)
; #define PG8_LDB(dst, b, h) do { _Pragma("unroll") for (int n = 0; n < 2; ++n) _Pragma("unroll") for (int k = 0; k < 2; ++k) dst[n][k] = *(const LAS bf16x8*)(lds + PG8_SB(b, h) + boff + n * 2048 + k * 1024); } while (0)
; #define PG8_WAIT_V(n) asm volatile("s_waitcnt vmcnt(" #n ")" ::: "memory")
; #define PG8_WAIT_L(n) asm volatile("s_waitcnt lgkmcnt(" #n ")" ::: "memory")
; #define PG8_BAR __builtin_amdgcn_s_barrier()
; #define PG8_SCHED __builtin_amdgcn_sched_barrier(0)
; template <class Epi>
; __device__ __forceinline__ void gemm_phase(LAS unsigned char* lds, const Gemm g, const StaticOrder& S, const Epi& E) {
;     ...
;         const bool has_next = S.next(ui + 1, nxt);
;         const char* nA = has_next ? (const char*)g.A + (size_t)nxt.pm * tstep : cA; const char* nB = has_next ? (const char*)g.Bt + (size_t)nxt.pn * tstep : cB;
;         for (int t = 0; t < nt; t += 2) {
;             const bool last = (t == nt - 2);
;             const char* a1 = cA + (size_t)(t + 1) * kstep;
;             const char* a2 = last ? nA : cA + (size_t)(t + 2) * kstep; const char* b2 = last ? nB : cB + (size_t)(t + 2) * kstep;
;             const char* a3 = a2 + kstep; const char* b3 = b2 + kstep;
;             PG8_LDB(B0, 0, 0); PG8_SCHED; PG8_LDA(At, 0, 0); PG8_STAGE(PG8_SA(1, 1), a1 + hstep, voffA);
;             PG8_WAIT_L(8); PG8_BAR; PG8_WAIT_L(0); PG8_MMA(0, 0, At, B0); PG8_BAR; PG8_SCHED;
;             PG8_LDB(B1, 0, 1); PG8_STAGE(PG8_SB(0, 0), b2, voffB);
;             PG8_BAR; PG8_WAIT_L(0); PG8_MMA(0, 1, At, B1); PG8_BAR;
;             PG8_LDA(At, 0, 1); PG8_STAGE(PG8_SA(0, 0), a2, voffA);
;             PG8_BAR; PG8_WAIT_L(0); PG8_MMA(1, 0, At, B0); PG8_BAR; PG8_SCHED;
;             PG8_STAGE(PG8_SB(0, 1), b2 + hstep, voffB);
;             PG8_WAIT_V(6); PG8_BAR; PG8_MMA(1, 1, At, B1); PG8_BAR;
.LBB0_407:
	ds_read_b128 v[150:153], v164
	ds_read_b128 v[154:157], v164 offset:1024
	ds_read_b128 v[168:171], v164 offset:2048
	ds_read_b128 v[172:175], v164 offset:3072
	s_add_u32 s48, s46, 0xfff80080
	s_addc_u32 s49, s47, -1
	s_cmp_eq_u32 s57, 28
	s_cselect_b32 s51, s9, s49
	s_cselect_b32 s50, s45, s48
	s_cselect_b32 s49, s7, s56
	s_cselect_b32 s48, s54, s55
	s_add_i32 m0, s27, 0xc000
	ds_read_b128 v[176:179], v165
	ds_read_b128 v[180:183], v165 offset:1024
	ds_read_b128 v[184:187], v165 offset:2048
	ds_read_b128 v[188:191], v165 offset:3072
	ds_read_b128 v[192:195], v165 offset:4096
	ds_read_b128 v[196:199], v165 offset:5120
	ds_read_b128 v[200:203], v165 offset:6144
	ds_read_b128 v[204:207], v165 offset:7168
	global_load_lds_dwordx4 v142, s[46:47]
	s_add_i32 m0, s27, 0xe000
	s_nop 0
	global_load_lds_dwordx4 v144, s[46:47]
	s_waitcnt lgkmcnt(8)
	s_barrier
	s_waitcnt lgkmcnt(0)
	v_mfma_f32_16x16x32_bf16 v[124:127], v[150:153], v[176:179], v[124:127]
	v_mfma_f32_16x16x32_bf16 v[120:123], v[168:171], v[176:179], v[120:123]
	v_mfma_f32_16x16x32_bf16 v[108:111], v[150:153], v[184:187], v[108:111]
	v_mfma_f32_16x16x32_bf16 v[104:107], v[168:171], v[184:187], v[104:107]
	v_mfma_f32_16x16x32_bf16 v[92:95], v[150:153], v[192:195], v[92:95]
	v_mfma_f32_16x16x32_bf16 v[88:91], v[168:171], v[192:195], v[88:91]
	v_mfma_f32_16x16x32_bf16 v[76:79], v[150:153], v[200:203], v[76:79]
	v_mfma_f32_16x16x32_bf16 v[72:75], v[168:171], v[200:203], v[72:75]
	v_mfma_f32_16x16x32_bf16 v[124:127], v[154:157], v[180:183], v[124:127]
	v_mfma_f32_16x16x32_bf16 v[120:123], v[172:175], v[180:183], v[120:123]
	v_mfma_f32_16x16x32_bf16 v[108:111], v[154:157], v[188:191], v[108:111]
	v_mfma_f32_16x16x32_bf16 v[104:107], v[172:175], v[188:191], v[104:107]
	v_mfma_f32_16x16x32_bf16 v[92:95], v[154:157], v[196:199], v[92:95]
	v_mfma_f32_16x16x32_bf16 v[88:91], v[172:175], v[196:199], v[88:91]
	v_mfma_f32_16x16x32_bf16 v[76:79], v[154:157], v[204:207], v[76:79]
	v_mfma_f32_16x16x32_bf16 v[72:75], v[172:175], v[204:207], v[72:75]
	s_barrier
	s_add_i32 s58, s41, s23
	s_add_u32 s98, s48, s2
	s_addc_u32 s99, s49, s3
	s_mov_b32 m0, s58
	ds_read_b128 v[208:211], v166
	ds_read_b128 v[212:215], v166 offset:1024
	ds_read_b128 v[216:219], v166 offset:2048
	ds_read_b128 v[220:223], v166 offset:3072
	global_load_lds_dwordx4 v132, s[48:49]
	s_add_i32 m0, s58, 0x2000
	s_nop 0
	global_load_lds_dwordx4 v128, s[48:49]
	s_waitcnt lgkmcnt(0)
	s_barrier
	v_mfma_f32_16x16x32_bf16 v[116:119], v[208:211], v[176:179], v[116:119]
	v_mfma_f32_16x16x32_bf16 v[112:115], v[216:219], v[176:179], v[112:115]
	v_mfma_f32_16x16x32_bf16 v[100:103], v[208:211], v[184:187], v[100:103]
	v_mfma_f32_16x16x32_bf16 v[96:99], v[216:219], v[184:187], v[96:99]
	v_mfma_f32_16x16x32_bf16 v[84:87], v[208:211], v[192:195], v[84:87]
	v_mfma_f32_16x16x32_bf16 v[80:83], v[216:219], v[192:195], v[80:83]
	v_mfma_f32_16x16x32_bf16 v[68:71], v[208:211], v[200:203], v[68:71]
	v_mfma_f32_16x16x32_bf16 v[64:67], v[216:219], v[200:203], v[64:67]
	v_mfma_f32_16x16x32_bf16 v[116:119], v[212:215], v[180:183], v[116:119]
	v_mfma_f32_16x16x32_bf16 v[112:115], v[220:223], v[180:183], v[112:115]
	v_mfma_f32_16x16x32_bf16 v[100:103], v[212:215], v[188:191], v[100:103]
	v_mfma_f32_16x16x32_bf16 v[96:99], v[220:223], v[188:191], v[96:99]
	v_mfma_f32_16x16x32_bf16 v[84:87], v[212:215], v[196:199], v[84:87]
	v_mfma_f32_16x16x32_bf16 v[80:83], v[220:223], v[196:199], v[80:83]
	v_mfma_f32_16x16x32_bf16 v[68:71], v[212:215], v[204:207], v[68:71]
	v_mfma_f32_16x16x32_bf16 v[64:67], v[220:223], v[204:207], v[64:67]
	s_mov_b32 m0, s27
	s_add_u32 s100, s50, s2
	s_addc_u32 s101, s51, s3
	s_barrier
	ds_read_b128 v[176:179], v165 offset:16384
	ds_read_b128 v[180:183], v165 offset:17408
	ds_read_b128 v[184:187], v165 offset:18432
	ds_read_b128 v[188:191], v165 offset:19456
	ds_read_b128 v[192:195], v165 offset:20480
	ds_read_b128 v[196:199], v165 offset:21504
	ds_read_b128 v[200:203], v165 offset:22528
	ds_read_b128 v[204:207], v165 offset:23552
	global_load_lds_dwordx4 v134, s[50:51]
	s_mov_b32 m0, s30
	s_nop 0
	global_load_lds_dwordx4 v130, s[50:51]
	s_waitcnt lgkmcnt(0)
	s_barrier
	v_mfma_f32_16x16x32_bf16 v[60:63], v[150:153], v[176:179], v[60:63]
	v_mfma_f32_16x16x32_bf16 v[56:59], v[168:171], v[176:179], v[56:59]
	v_mfma_f32_16x16x32_bf16 v[44:47], v[150:153], v[184:187], v[44:47]
	v_mfma_f32_16x16x32_bf16 v[40:43], v[168:171], v[184:187], v[40:43]
	v_mfma_f32_16x16x32_bf16 v[28:31], v[150:153], v[192:195], v[28:31]
	v_mfma_f32_16x16x32_bf16 v[24:27], v[168:171], v[192:195], v[24:27]
	v_mfma_f32_16x16x32_bf16 v[12:15], v[150:153], v[200:203], v[12:15]
	v_mfma_f32_16x16x32_bf16 v[8:11], v[168:171], v[200:203], v[8:11]
	v_mfma_f32_16x16x32_bf16 v[60:63], v[154:157], v[180:183], v[60:63]
	v_mfma_f32_16x16x32_bf16 v[56:59], v[172:175], v[180:183], v[56:59]
	v_mfma_f32_16x16x32_bf16 v[44:47], v[154:157], v[188:191], v[44:47]
	v_mfma_f32_16x16x32_bf16 v[40:43], v[172:175], v[188:191], v[40:43]
	v_mfma_f32_16x16x32_bf16 v[28:31], v[154:157], v[196:199], v[28:31]
	v_mfma_f32_16x16x32_bf16 v[24:27], v[172:175], v[196:199], v[24:27]
	v_mfma_f32_16x16x32_bf16 v[12:15], v[154:157], v[204:207], v[12:15]
	v_mfma_f32_16x16x32_bf16 v[8:11], v[172:175], v[204:207], v[8:11]
	s_barrier
	s_add_u32 s58, s48, 0x80000
	s_addc_u32 s59, s49, 0
	s_add_i32 s60, s52, s23
	s_mov_b32 m0, s60
	s_nop 0
	global_load_lds_dwordx4 v132, s[58:59]
	s_add_i32 m0, s60, 0x2000
	s_nop 0
	global_load_lds_dwordx4 v128, s[58:59]
	s_waitcnt vmcnt(6)
	s_barrier
; #define PG8_STAGE(bufoff, gbase, voff) do { _Pragma("unroll") for (int _i = 0; _i < 2; ++_i) \
;         __builtin_amdgcn_global_load_lds((const unsigned*)((const char*)(gbase) + (voff)[_i]), (LAS unsigned*)(lds + (bufoff) + ldsw + _i * 8192), 16, 0, 0); } while (0)
; #define PG8_LDA(dst, b, h) do { _Pragma("unroll") for (int m = 0; m < 4; ++m) _Pragma("unroll") for (int k = 0; k < 2; ++k) dst[m][k] = *(const LAS bf16x8*)(lds + PG8_SA(b, h) + aoff + m * 2048 + k * 1024); } while (0)
; #define PG8_LDB(dst, b, h) do { _Pragma("unroll") for (int n = 0; n < 2; ++n) _Pragma("unroll") for (int k = 0; k < 2; ++k) dst[n][k] = *(const LAS bf16x8*)(lds + PG8_SB(b, h) + boff + n * 2048 + k * 1024); } while (0)
; #define PG8_MMA(ai, bj, At, Bt) do { __builtin_amdgcn_s_setprio(1); _Pragma("unroll") for (int m = 0; m < 4; ++m) _Pragma("unroll") for (int n = 0; n < 2; ++n) _Pragma("unroll") for (int k = 0; k < 2; ++k) \
;         acc[ai][bj][m][n] = __builtin_amdgcn_mfma_f32_16x16x32_bf16(Bt[n][k], At[m][k], acc[ai][bj][m][n], 0, 0, 0); __builtin_amdgcn_s_setprio(0); } while (0)
; #define PG8_WAIT_V(n) asm volatile("s_waitcnt vmcnt(" #n ")" ::: "memory")
; #define PG8_WAIT_L(n) asm volatile("s_waitcnt lgkmcnt(" #n ")" ::: "memory")
; #define PG8_BAR __builtin_amdgcn_s_barrier()
; #define PG8_SCHED __builtin_amdgcn_sched_barrier(0)
; template <class Epi>
; __device__ __forceinline__ void gemm_phase(LAS unsigned char* lds, const Gemm g, const StaticOrder& S, const Epi& E) {
;     ...
;             PG8_WAIT_V(6); PG8_BAR; PG8_MMA(1, 1, At, B1); PG8_BAR;
;             PG8_LDB(B0, 1, 0); PG8_SCHED; PG8_LDA(At, 1, 0); PG8_STAGE(PG8_SA(0, 1), a2 + hstep, voffA);
;             PG8_WAIT_L(8); PG8_BAR; PG8_WAIT_L(0); PG8_MMA(0, 0, At, B0); PG8_BAR; PG8_SCHED;
;             PG8_LDB(B1, 1, 1); PG8_STAGE(PG8_SB(1, 0), b3, voffB);
;             PG8_BAR; PG8_WAIT_L(0); PG8_MMA(0, 1, At, B1); PG8_BAR;
;             PG8_LDA(At, 1, 1); PG8_STAGE(PG8_SA(1, 0), a3, voffA);
;             PG8_BAR; PG8_WAIT_L(0); PG8_MMA(1, 0, At, B0); PG8_BAR; PG8_SCHED;
	v_mfma_f32_16x16x32_bf16 v[52:55], v[208:211], v[176:179], v[52:55]
	v_mfma_f32_16x16x32_bf16 v[48:51], v[216:219], v[176:179], v[48:51]
	v_mfma_f32_16x16x32_bf16 v[36:39], v[208:211], v[184:187], v[36:39]
	v_mfma_f32_16x16x32_bf16 v[32:35], v[216:219], v[184:187], v[32:35]
	v_mfma_f32_16x16x32_bf16 v[20:23], v[208:211], v[192:195], v[20:23]
	v_mfma_f32_16x16x32_bf16 v[16:19], v[216:219], v[192:195], v[16:19]
	v_mfma_f32_16x16x32_bf16 v[4:7], v[208:211], v[200:203], v[4:7]
	v_mfma_f32_16x16x32_bf16 v[0:3], v[216:219], v[200:203], v[0:3]
	v_mfma_f32_16x16x32_bf16 v[52:55], v[212:215], v[180:183], v[52:55]
	v_mfma_f32_16x16x32_bf16 v[48:51], v[220:223], v[180:183], v[48:51]
	v_mfma_f32_16x16x32_bf16 v[36:39], v[212:215], v[188:191], v[36:39]
	v_mfma_f32_16x16x32_bf16 v[32:35], v[220:223], v[188:191], v[32:35]
	v_mfma_f32_16x16x32_bf16 v[20:23], v[212:215], v[196:199], v[20:23]
	v_mfma_f32_16x16x32_bf16 v[16:19], v[220:223], v[196:199], v[16:19]
	v_mfma_f32_16x16x32_bf16 v[4:7], v[212:215], v[204:207], v[4:7]
	v_mfma_f32_16x16x32_bf16 v[0:3], v[220:223], v[204:207], v[0:3]
	s_add_i32 s58, 0, 0x18000
	v_add_u32_e32 v136, s58, v161
	s_barrier
	ds_read_b128 v[150:153], v136
	ds_read_b128 v[154:157], v136 offset:1024
	ds_read_b128 v[168:171], v136 offset:2048
	ds_read_b128 v[172:175], v136 offset:3072
	s_add_u32 s50, s50, 0x80000
	s_addc_u32 s51, s51, 0
	s_mov_b32 m0, s31
	ds_read_b128 v[176:179], v165 offset:32768
	ds_read_b128 v[180:183], v165 offset:33792
	ds_read_b128 v[184:187], v165 offset:34816
	ds_read_b128 v[188:191], v165 offset:35840
	ds_read_b128 v[192:195], v165 offset:36864
	ds_read_b128 v[196:199], v165 offset:37888
	ds_read_b128 v[200:203], v165 offset:38912
	ds_read_b128 v[204:207], v165 offset:39936
	global_load_lds_dwordx4 v134, s[50:51]
	s_mov_b32 m0, s33
	s_nop 0
	global_load_lds_dwordx4 v130, s[50:51]
	s_waitcnt lgkmcnt(8)
	s_barrier
	s_waitcnt lgkmcnt(0)
	v_mfma_f32_16x16x32_bf16 v[124:127], v[150:153], v[176:179], v[124:127]
	v_mfma_f32_16x16x32_bf16 v[120:123], v[168:171], v[176:179], v[120:123]
	v_mfma_f32_16x16x32_bf16 v[108:111], v[150:153], v[184:187], v[108:111]
	v_mfma_f32_16x16x32_bf16 v[104:107], v[168:171], v[184:187], v[104:107]
	v_mfma_f32_16x16x32_bf16 v[92:95], v[150:153], v[192:195], v[92:95]
	v_mfma_f32_16x16x32_bf16 v[88:91], v[168:171], v[192:195], v[88:91]
	v_mfma_f32_16x16x32_bf16 v[76:79], v[150:153], v[200:203], v[76:79]
	v_mfma_f32_16x16x32_bf16 v[72:75], v[168:171], v[200:203], v[72:75]
	v_mfma_f32_16x16x32_bf16 v[124:127], v[154:157], v[180:183], v[124:127]
	v_mfma_f32_16x16x32_bf16 v[120:123], v[172:175], v[180:183], v[120:123]
	v_mfma_f32_16x16x32_bf16 v[108:111], v[154:157], v[188:191], v[108:111]
	v_mfma_f32_16x16x32_bf16 v[104:107], v[172:175], v[188:191], v[104:107]
	v_mfma_f32_16x16x32_bf16 v[92:95], v[154:157], v[196:199], v[92:95]
	v_mfma_f32_16x16x32_bf16 v[88:91], v[172:175], v[196:199], v[88:91]
	v_mfma_f32_16x16x32_bf16 v[76:79], v[154:157], v[204:207], v[76:79]
	v_mfma_f32_16x16x32_bf16 v[72:75], v[172:175], v[204:207], v[72:75]
	s_barrier
	s_add_i32 s50, 0, 0x1c000
	s_add_i32 s51, s58, s23
	v_add_u32_e32 v136, s50, v161
	s_mov_b32 m0, s51
	ds_read_b128 v[208:211], v136
	ds_read_b128 v[212:215], v136 offset:1024
	ds_read_b128 v[216:219], v136 offset:2048
	ds_read_b128 v[220:223], v136 offset:3072
	global_load_lds_dwordx4 v132, s[98:99]
	s_add_i32 m0, s51, 0x2000
	s_nop 0
	global_load_lds_dwordx4 v128, s[98:99]
	s_waitcnt lgkmcnt(0)
	s_barrier
	v_mfma_f32_16x16x32_bf16 v[116:119], v[208:211], v[176:179], v[116:119]
	v_mfma_f32_16x16x32_bf16 v[112:115], v[216:219], v[176:179], v[112:115]
	v_mfma_f32_16x16x32_bf16 v[100:103], v[208:211], v[184:187], v[100:103]
	v_mfma_f32_16x16x32_bf16 v[96:99], v[216:219], v[184:187], v[96:99]
	v_mfma_f32_16x16x32_bf16 v[84:87], v[208:211], v[192:195], v[84:87]
	v_mfma_f32_16x16x32_bf16 v[80:83], v[216:219], v[192:195], v[80:83]
	v_mfma_f32_16x16x32_bf16 v[68:71], v[208:211], v[200:203], v[68:71]
	v_mfma_f32_16x16x32_bf16 v[64:67], v[216:219], v[200:203], v[64:67]
	v_mfma_f32_16x16x32_bf16 v[116:119], v[212:215], v[180:183], v[116:119]
	v_mfma_f32_16x16x32_bf16 v[112:115], v[220:223], v[180:183], v[112:115]
	v_mfma_f32_16x16x32_bf16 v[100:103], v[212:215], v[188:191], v[100:103]
	v_mfma_f32_16x16x32_bf16 v[96:99], v[220:223], v[188:191], v[96:99]
	v_mfma_f32_16x16x32_bf16 v[84:87], v[212:215], v[196:199], v[84:87]
	v_mfma_f32_16x16x32_bf16 v[80:83], v[220:223], v[196:199], v[80:83]
	v_mfma_f32_16x16x32_bf16 v[68:71], v[212:215], v[204:207], v[68:71]
	v_mfma_f32_16x16x32_bf16 v[64:67], v[220:223], v[204:207], v[64:67]
	s_mov_b32 m0, s37
	s_barrier
	ds_read_b128 v[176:179], v165 offset:49152
	ds_read_b128 v[180:183], v165 offset:50176
	ds_read_b128 v[184:187], v165 offset:51200
	ds_read_b128 v[188:191], v165 offset:52224
	ds_read_b128 v[192:195], v165 offset:53248
	ds_read_b128 v[196:199], v165 offset:54272
	ds_read_b128 v[200:203], v165 offset:55296
	ds_read_b128 v[204:207], v165 offset:56320
	global_load_lds_dwordx4 v134, s[100:101]
	s_mov_b32 m0, s38
	s_nop 0
	global_load_lds_dwordx4 v130, s[100:101]
	s_waitcnt lgkmcnt(0)
	s_barrier
; #define PG8_WAIT_V(n) asm volatile("s_waitcnt vmcnt(" #n ")" ::: "memory")
; #define PG8_BAR __builtin_amdgcn_s_barrier()
; template <class Epi>
; __device__ __forceinline__ void gemm_phase(LAS unsigned char* lds, const Gemm g, const StaticOrder& S, const Epi& E) {
;     ...
;             PG8_BAR; PG8_WAIT_L(0); PG8_MMA(1, 0, At, B0); PG8_BAR; PG8_SCHED;
;             PG8_STAGE(PG8_SB(1, 1), b3 + hstep, voffB);
;             PG8_WAIT_V(6); PG8_BAR; PG8_MMA(1, 1, At, B1); PG8_BAR;
;     __device__ __forceinline__ void operator()(const f32x4 (&acc)[2][2][4][2], const Unit& u, int wr, int wc, int fr, int fq) const {
;         const int row0 = u.pm * BM + wr * 64 + fr;
;         if (u.pn >= 6 && u.pn < 18) {
;             const int d0 = 32 * (wc & 1) + 8 * fq, col1 = u.pn * BM + HALF * (wc >> 1) + d0;
;             const float sc = (u.pn < 12) ? QSCALE : 1.0f;
; #pragma unroll
;             for (int ai = 0; ai < 2; ++ai)
; #pragma unroll
;                 for (int m = 0; m < 4; ++m) { const int row = row0 + ai * HALF + m * 16; const int pos = (row + pos0) & (SEQ - 1); const float scr_ = sc * rowsc[row];
;                     const f32x4 c0 = *(const f32x4*)(rc + pos * 64 + d0), c1 = *(const f32x4*)(rc + pos * 64 + d0 + 4);
;                     const f32x4 s0 = *(const f32x4*)(rs + pos * 64 + d0), s1 = *(const f32x4*)(rs + pos * 64 + d0 + 4);
;                     const f32x4 a0 = acc[ai][0][m][0], a1 = acc[ai][0][m][1], b0 = acc[ai][1][m][0], b1 = acc[ai][1][m][1];
;                     const f32x4 o10 = (a0 * c0 - b0 * s0) * scr_, o11 = (a1 * c1 - b1 * s1) * scr_;
;                     const f32x4 o20 = (b0 * c0 + a0 * s0) * scr_, o21 = (b1 * c1 + a1 * s1) * scr_;
;                     bf16_t* rowp = O + (size_t)row * NQKV + col1;
;                     *(u32x4*)rowp = pack8(o10, o11); *(u32x4*)(rowp + 64) = pack8(o20, o21); }
;         } else {
;             const int col0 = u.pn * BM + wc * 32 + 8 * fq; const float sc = (u.pn < 2) ? QSCALE : 1.0f;
; #pragma unroll
;             for (int ai = 0; ai < 2; ++ai)
; #pragma unroll
;                 for (int m = 0; m < 4; ++m) { bf16_t* rowp = O + (size_t)(row0 + ai * HALF + m * 16) * NQKV + col0; const float scr_ = sc * rowsc[row0 + ai * HALF + m * 16];
; #pragma unroll
;                     for (int bj = 0; bj < 2; ++bj) *(u32x4*)(rowp + bj * HALF) = pack8(acc[ai][bj][m][0] * scr_, acc[ai][bj][m][1] * scr_); }
	v_mfma_f32_16x16x32_bf16 v[60:63], v[150:153], v[176:179], v[60:63]
	v_mfma_f32_16x16x32_bf16 v[56:59], v[168:171], v[176:179], v[56:59]
	v_mfma_f32_16x16x32_bf16 v[44:47], v[150:153], v[184:187], v[44:47]
	v_mfma_f32_16x16x32_bf16 v[40:43], v[168:171], v[184:187], v[40:43]
	v_mfma_f32_16x16x32_bf16 v[28:31], v[150:153], v[192:195], v[28:31]
	v_mfma_f32_16x16x32_bf16 v[24:27], v[168:171], v[192:195], v[24:27]
	v_mfma_f32_16x16x32_bf16 v[12:15], v[150:153], v[200:203], v[12:15]
	v_mfma_f32_16x16x32_bf16 v[8:11], v[168:171], v[200:203], v[8:11]
	v_mfma_f32_16x16x32_bf16 v[60:63], v[154:157], v[180:183], v[60:63]
	v_mfma_f32_16x16x32_bf16 v[56:59], v[172:175], v[180:183], v[56:59]
	v_mfma_f32_16x16x32_bf16 v[44:47], v[154:157], v[188:191], v[44:47]
	v_mfma_f32_16x16x32_bf16 v[40:43], v[172:175], v[188:191], v[40:43]
	v_mfma_f32_16x16x32_bf16 v[28:31], v[154:157], v[196:199], v[28:31]
	v_mfma_f32_16x16x32_bf16 v[24:27], v[172:175], v[196:199], v[24:27]
	v_mfma_f32_16x16x32_bf16 v[12:15], v[154:157], v[204:207], v[12:15]
	v_mfma_f32_16x16x32_bf16 v[8:11], v[172:175], v[204:207], v[8:11]
	s_barrier
	s_add_u32 s48, s48, 0x80080
	s_addc_u32 s49, s49, 0
	s_add_i32 s50, s50, s23
	s_mov_b32 m0, s50
	s_nop 0
	global_load_lds_dwordx4 v132, s[48:49]
	s_add_i32 m0, s50, 0x2000
	s_nop 0
	global_load_lds_dwordx4 v128, s[48:49]
	s_waitcnt vmcnt(6)
	s_barrier
	v_mfma_f32_16x16x32_bf16 v[52:55], v[208:211], v[176:179], v[52:55]
	v_mfma_f32_16x16x32_bf16 v[48:51], v[216:219], v[176:179], v[48:51]
	v_mfma_f32_16x16x32_bf16 v[36:39], v[208:211], v[184:187], v[36:39]
	v_mfma_f32_16x16x32_bf16 v[32:35], v[216:219], v[184:187], v[32:35]
	v_mfma_f32_16x16x32_bf16 v[20:23], v[208:211], v[192:195], v[20:23]
	v_mfma_f32_16x16x32_bf16 v[16:19], v[216:219], v[192:195], v[16:19]
	v_mfma_f32_16x16x32_bf16 v[4:7], v[208:211], v[200:203], v[4:7]
	v_mfma_f32_16x16x32_bf16 v[0:3], v[216:219], v[200:203], v[0:3]
	v_mfma_f32_16x16x32_bf16 v[52:55], v[212:215], v[180:183], v[52:55]
	v_mfma_f32_16x16x32_bf16 v[48:51], v[220:223], v[180:183], v[48:51]
	v_mfma_f32_16x16x32_bf16 v[36:39], v[212:215], v[188:191], v[36:39]
	v_mfma_f32_16x16x32_bf16 v[32:35], v[220:223], v[188:191], v[32:35]
	v_mfma_f32_16x16x32_bf16 v[20:23], v[212:215], v[196:199], v[20:23]
	v_mfma_f32_16x16x32_bf16 v[16:19], v[220:223], v[196:199], v[16:19]
	v_mfma_f32_16x16x32_bf16 v[4:7], v[212:215], v[204:207], v[4:7]
	v_mfma_f32_16x16x32_bf16 v[0:3], v[220:223], v[204:207], v[0:3]
	s_add_i32 s57, s57, 2
	s_add_u32 s46, s46, 0x100
	s_addc_u32 s47, s47, 0
	s_add_u32 s55, s55, 0x100
	s_addc_u32 s56, s56, 0
	s_cmp_gt_u32 s57, 29
	s_barrier
	s_cbranch_scc0 .LBB0_407
	v_lshl_add_u32 v154, s44, 8, v160
	s_add_i32 s9, s34, -6
	s_lshl_b32 s7, s34, 8
	s_cmp_gt_u32 s9, 11
	s_mov_b64 s[44:45], -1
	v_ashrrev_i32_e32 v155, 31, v154
	v_or_b32_e32 v174, 16, v154
	v_or_b32_e32 v173, 32, v154
	v_or_b32_e32 v172, 48, v154
	v_add_u32_e32 v171, 0x80, v154
	v_add_u32_e32 v170, 0x90, v154
	v_add_u32_e32 v169, 0xa0, v154
	v_add_u32_e32 v168, 0xb0, v154
	s_cbranch_scc0 .LBB0_410
	v_lshl_add_u64 v[150:151], v[154:155], 2, s[14:15]
	global_load_dword v136, v[150:151], off
	global_load_dword v204, v[150:151], off offset:64
	global_load_dword v205, v[150:151], off offset:128
	global_load_dword v206, v[150:151], off offset:192
	global_load_dword v207, v[150:151], off offset:512
	global_load_dword v208, v[150:151], off offset:576
	global_load_dword v209, v[150:151], off offset:640
	global_load_dword v210, v[150:151], off offset:704
	s_cmp_lt_i32 s34, 2
	v_or_b32_e32 v156, s7, v162
	s_cselect_b64 vcc, -1, 0
	v_mov_b64_e32 v[152:153], s[20:21]
	v_cndmask_b32_e32 v175, 1.0, v167, vcc
	v_ashrrev_i32_e32 v157, 31, v156
	v_mad_i64_i32 v[176:177], s[44:45], v154, s53, v[152:153]
	v_lshlrev_b64 v[156:157], 1, v[156:157]
	v_lshl_add_u64 v[180:181], v[176:177], 0, v[156:157]
	s_waitcnt vmcnt(0)
	v_mul_f32_e32 v136, v175, v136
	v_pk_mul_f32 v[178:179], v[126:127], v[136:137] op_sel_hi:[1,0]
	v_pk_mul_f32 v[176:177], v[124:125], v[136:137] op_sel_hi:[1,0]
	v_pk_mul_f32 v[182:183], v[122:123], v[136:137] op_sel_hi:[1,0]
	v_pk_mul_f32 v[184:185], v[120:121], v[136:137] op_sel_hi:[1,0]
	v_cvt_pk_bf16_f32 v176, v176, v177
	v_cvt_pk_bf16_f32 v177, v178, v179
	v_pk_mul_f32 v[186:187], v[118:119], v[136:137] op_sel_hi:[1,0]
	v_cvt_pk_bf16_f32 v178, v184, v185
	v_cvt_pk_bf16_f32 v179, v182, v183
	v_pk_mul_f32 v[188:189], v[116:117], v[136:137] op_sel_hi:[1,0]
	v_pk_mul_f32 v[190:191], v[114:115], v[136:137] op_sel_hi:[1,0]
	v_pk_mul_f32 v[192:193], v[112:113], v[136:137] op_sel_hi:[1,0]
	global_store_dwordx4 v[180:181], v[176:179], off
	s_nop 1
	v_cvt_pk_bf16_f32 v176, v188, v189
	v_cvt_pk_bf16_f32 v177, v186, v187
	v_cvt_pk_bf16_f32 v178, v192, v193
	v_cvt_pk_bf16_f32 v179, v190, v191
	global_store_dwordx4 v[180:181], v[176:179], off offset:256
	s_nop 1
	v_mov_b32_e32 v136, v204
	v_mul_f32_e32 v136, v175, v136
	v_mad_i64_i32 v[176:177], s[44:45], v174, s53, v[152:153]
	v_lshl_add_u64 v[180:181], v[176:177], 0, v[156:157]
	v_pk_mul_f32 v[178:179], v[110:111], v[136:137] op_sel_hi:[1,0]
	v_pk_mul_f32 v[176:177], v[108:109], v[136:137] op_sel_hi:[1,0]
	v_pk_mul_f32 v[182:183], v[106:107], v[136:137] op_sel_hi:[1,0]
	v_pk_mul_f32 v[184:185], v[104:105], v[136:137] op_sel_hi:[1,0]
	v_cvt_pk_bf16_f32 v176, v176, v177
	v_cvt_pk_bf16_f32 v177, v178, v179
	v_pk_mul_f32 v[186:187], v[102:103], v[136:137] op_sel_hi:[1,0]
	v_cvt_pk_bf16_f32 v178, v184, v185
	v_cvt_pk_bf16_f32 v179, v182, v183
	v_pk_mul_f32 v[188:189], v[100:101], v[136:137] op_sel_hi:[1,0]
	v_pk_mul_f32 v[190:191], v[98:99], v[136:137] op_sel_hi:[1,0]
	v_pk_mul_f32 v[192:193], v[96:97], v[136:137] op_sel_hi:[1,0]
; __device__ __forceinline__ u32x4 pack8(f32x4 v0, f32x4 v1) { u32x4 w; w.x = cvt_pk_bf16(v0[0], v0[1]); w.y = cvt_pk_bf16(v0[2], v0[3]); w.z = cvt_pk_bf16(v1[0], v1[1]); w.w = cvt_pk_bf16(v1[2], v1[3]); return w; }
;     __device__ __forceinline__ void operator()(const f32x4 (&acc)[2][2][4][2], const Unit& u, int wr, int wc, int fr, int fq) const {
;     ...
;             const int col0 = u.pn * BM + wc * 32 + 8 * fq; const float sc = (u.pn < 2) ? QSCALE : 1.0f;
; #pragma unroll
;             for (int ai = 0; ai < 2; ++ai)
; #pragma unroll
;                 for (int m = 0; m < 4; ++m) { bf16_t* rowp = O + (size_t)(row0 + ai * HALF + m * 16) * NQKV + col0; const float scr_ = sc * rowsc[row0 + ai * HALF + m * 16];
; #pragma unroll
;                     for (int bj = 0; bj < 2; ++bj) *(u32x4*)(rowp + bj * HALF) = pack8(acc[ai][bj][m][0] * scr_, acc[ai][bj][m][1] * scr_); }
	global_store_dwordx4 v[180:181], v[176:179], off
	s_nop 1
	v_cvt_pk_bf16_f32 v176, v188, v189
	v_cvt_pk_bf16_f32 v177, v186, v187
	v_cvt_pk_bf16_f32 v178, v192, v193
	v_cvt_pk_bf16_f32 v179, v190, v191
	global_store_dwordx4 v[180:181], v[176:179], off offset:256
	s_nop 1
	v_mov_b32_e32 v136, v205
	v_mul_f32_e32 v136, v175, v136
	v_mad_i64_i32 v[176:177], s[44:45], v173, s53, v[152:153]
	v_lshl_add_u64 v[180:181], v[176:177], 0, v[156:157]
	v_pk_mul_f32 v[178:179], v[94:95], v[136:137] op_sel_hi:[1,0]
	v_pk_mul_f32 v[176:177], v[92:93], v[136:137] op_sel_hi:[1,0]
	v_pk_mul_f32 v[182:183], v[90:91], v[136:137] op_sel_hi:[1,0]
	v_pk_mul_f32 v[184:185], v[88:89], v[136:137] op_sel_hi:[1,0]
	v_cvt_pk_bf16_f32 v176, v176, v177
	v_cvt_pk_bf16_f32 v177, v178, v179
	v_pk_mul_f32 v[186:187], v[86:87], v[136:137] op_sel_hi:[1,0]
	v_cvt_pk_bf16_f32 v178, v184, v185
	v_cvt_pk_bf16_f32 v179, v182, v183
	v_pk_mul_f32 v[188:189], v[84:85], v[136:137] op_sel_hi:[1,0]
	v_pk_mul_f32 v[190:191], v[82:83], v[136:137] op_sel_hi:[1,0]
	v_pk_mul_f32 v[192:193], v[80:81], v[136:137] op_sel_hi:[1,0]
	global_store_dwordx4 v[180:181], v[176:179], off
	s_nop 1
	v_cvt_pk_bf16_f32 v176, v188, v189
	v_cvt_pk_bf16_f32 v177, v186, v187
	v_cvt_pk_bf16_f32 v178, v192, v193
	v_cvt_pk_bf16_f32 v179, v190, v191
	global_store_dwordx4 v[180:181], v[176:179], off offset:256
	s_nop 1
	v_mov_b32_e32 v136, v206
	v_mul_f32_e32 v136, v175, v136
	v_mad_i64_i32 v[176:177], s[44:45], v172, s53, v[152:153]
	v_lshl_add_u64 v[180:181], v[176:177], 0, v[156:157]
	v_pk_mul_f32 v[178:179], v[78:79], v[136:137] op_sel_hi:[1,0]
	v_pk_mul_f32 v[176:177], v[76:77], v[136:137] op_sel_hi:[1,0]
	v_pk_mul_f32 v[182:183], v[74:75], v[136:137] op_sel_hi:[1,0]
	v_pk_mul_f32 v[184:185], v[72:73], v[136:137] op_sel_hi:[1,0]
	v_cvt_pk_bf16_f32 v176, v176, v177
	v_cvt_pk_bf16_f32 v177, v178, v179
	v_pk_mul_f32 v[186:187], v[70:71], v[136:137] op_sel_hi:[1,0]
	v_cvt_pk_bf16_f32 v178, v184, v185
	v_cvt_pk_bf16_f32 v179, v182, v183
	v_pk_mul_f32 v[188:189], v[68:69], v[136:137] op_sel_hi:[1,0]
	v_pk_mul_f32 v[190:191], v[66:67], v[136:137] op_sel_hi:[1,0]
	v_pk_mul_f32 v[192:193], v[64:65], v[136:137] op_sel_hi:[1,0]
	global_store_dwordx4 v[180:181], v[176:179], off
	s_nop 1
	v_cvt_pk_bf16_f32 v176, v188, v189
	v_cvt_pk_bf16_f32 v177, v186, v187
	v_cvt_pk_bf16_f32 v178, v192, v193
	v_cvt_pk_bf16_f32 v179, v190, v191
	global_store_dwordx4 v[180:181], v[176:179], off offset:256
	s_nop 1
	v_mov_b32_e32 v136, v207
	v_mul_f32_e32 v136, v175, v136
	v_mad_i64_i32 v[176:177], s[44:45], v171, s53, v[152:153]
	v_lshl_add_u64 v[180:181], v[176:177], 0, v[156:157]
	v_pk_mul_f32 v[178:179], v[62:63], v[136:137] op_sel_hi:[1,0]
	v_pk_mul_f32 v[176:177], v[60:61], v[136:137] op_sel_hi:[1,0]
	v_pk_mul_f32 v[182:183], v[58:59], v[136:137] op_sel_hi:[1,0]
	v_pk_mul_f32 v[184:185], v[56:57], v[136:137] op_sel_hi:[1,0]
	v_cvt_pk_bf16_f32 v176, v176, v177
	v_cvt_pk_bf16_f32 v177, v178, v179
	v_pk_mul_f32 v[186:187], v[54:55], v[136:137] op_sel_hi:[1,0]
	v_cvt_pk_bf16_f32 v178, v184, v185
	v_cvt_pk_bf16_f32 v179, v182, v183
	v_pk_mul_f32 v[188:189], v[52:53], v[136:137] op_sel_hi:[1,0]
	v_pk_mul_f32 v[190:191], v[50:51], v[136:137] op_sel_hi:[1,0]
	v_pk_mul_f32 v[192:193], v[48:49], v[136:137] op_sel_hi:[1,0]
	global_store_dwordx4 v[180:181], v[176:179], off
	s_nop 1
	v_cvt_pk_bf16_f32 v176, v188, v189
	v_cvt_pk_bf16_f32 v177, v186, v187
	v_cvt_pk_bf16_f32 v178, v192, v193
	v_cvt_pk_bf16_f32 v179, v190, v191
	global_store_dwordx4 v[180:181], v[176:179], off offset:256
	s_nop 1
	v_mov_b32_e32 v136, v208
	v_mul_f32_e32 v136, v175, v136
	v_mad_i64_i32 v[176:177], s[44:45], v170, s53, v[152:153]
	v_lshl_add_u64 v[180:181], v[176:177], 0, v[156:157]
	v_pk_mul_f32 v[178:179], v[46:47], v[136:137] op_sel_hi:[1,0]
	v_pk_mul_f32 v[176:177], v[44:45], v[136:137] op_sel_hi:[1,0]
	v_pk_mul_f32 v[182:183], v[42:43], v[136:137] op_sel_hi:[1,0]
	v_pk_mul_f32 v[184:185], v[40:41], v[136:137] op_sel_hi:[1,0]
	v_cvt_pk_bf16_f32 v176, v176, v177
	v_cvt_pk_bf16_f32 v177, v178, v179
	v_pk_mul_f32 v[186:187], v[38:39], v[136:137] op_sel_hi:[1,0]
	v_cvt_pk_bf16_f32 v178, v184, v185
	v_cvt_pk_bf16_f32 v179, v182, v183
	v_pk_mul_f32 v[188:189], v[36:37], v[136:137] op_sel_hi:[1,0]
	v_pk_mul_f32 v[190:191], v[34:35], v[136:137] op_sel_hi:[1,0]
	v_pk_mul_f32 v[192:193], v[32:33], v[136:137] op_sel_hi:[1,0]
	global_store_dwordx4 v[180:181], v[176:179], off
	s_nop 1
	v_cvt_pk_bf16_f32 v176, v188, v189
	v_cvt_pk_bf16_f32 v177, v186, v187
	v_cvt_pk_bf16_f32 v178, v192, v193
	v_cvt_pk_bf16_f32 v179, v190, v191
	global_store_dwordx4 v[180:181], v[176:179], off offset:256
	s_nop 1
	v_mov_b32_e32 v136, v209
	v_mul_f32_e32 v136, v175, v136
	v_mad_i64_i32 v[176:177], s[44:45], v169, s53, v[152:153]
	v_lshl_add_u64 v[180:181], v[176:177], 0, v[156:157]
	v_pk_mul_f32 v[178:179], v[30:31], v[136:137] op_sel_hi:[1,0]
	v_pk_mul_f32 v[176:177], v[28:29], v[136:137] op_sel_hi:[1,0]
	v_pk_mul_f32 v[182:183], v[26:27], v[136:137] op_sel_hi:[1,0]
	v_pk_mul_f32 v[184:185], v[24:25], v[136:137] op_sel_hi:[1,0]
	v_cvt_pk_bf16_f32 v176, v176, v177
	v_cvt_pk_bf16_f32 v177, v178, v179
	v_pk_mul_f32 v[186:187], v[22:23], v[136:137] op_sel_hi:[1,0]
	v_cvt_pk_bf16_f32 v178, v184, v185
	v_cvt_pk_bf16_f32 v179, v182, v183
	v_pk_mul_f32 v[188:189], v[20:21], v[136:137] op_sel_hi:[1,0]
	v_pk_mul_f32 v[190:191], v[18:19], v[136:137] op_sel_hi:[1,0]
	v_pk_mul_f32 v[192:193], v[16:17], v[136:137] op_sel_hi:[1,0]
	global_store_dwordx4 v[180:181], v[176:179], off
	s_nop 1
	v_cvt_pk_bf16_f32 v176, v188, v189
	v_cvt_pk_bf16_f32 v177, v186, v187
	v_cvt_pk_bf16_f32 v178, v192, v193
	v_cvt_pk_bf16_f32 v179, v190, v191
	global_store_dwordx4 v[180:181], v[176:179], off offset:256
	s_nop 1
	v_mov_b32_e32 v136, v210
	v_mad_i64_i32 v[150:151], s[44:45], v168, s53, v[152:153]
	v_lshl_add_u64 v[156:157], v[150:151], 0, v[156:157]
	s_mov_b64 s[44:45], 0
	v_mul_f32_e32 v136, v175, v136
	v_pk_mul_f32 v[152:153], v[14:15], v[136:137] op_sel_hi:[1,0]
	v_pk_mul_f32 v[150:151], v[12:13], v[136:137] op_sel_hi:[1,0]
	v_pk_mul_f32 v[176:177], v[10:11], v[136:137] op_sel_hi:[1,0]
	v_pk_mul_f32 v[178:179], v[8:9], v[136:137] op_sel_hi:[1,0]
	v_cvt_pk_bf16_f32 v150, v150, v151
	v_cvt_pk_bf16_f32 v151, v152, v153
	v_pk_mul_f32 v[180:181], v[6:7], v[136:137] op_sel_hi:[1,0]
	v_cvt_pk_bf16_f32 v152, v178, v179
	v_cvt_pk_bf16_f32 v153, v176, v177
	v_pk_mul_f32 v[182:183], v[4:5], v[136:137] op_sel_hi:[1,0]
	v_pk_mul_f32 v[184:185], v[2:3], v[136:137] op_sel_hi:[1,0]
	v_pk_mul_f32 v[186:187], v[0:1], v[136:137] op_sel_hi:[1,0]
	global_store_dwordx4 v[156:157], v[150:153], off
	s_nop 1
	v_cvt_pk_bf16_f32 v150, v182, v183
	v_cvt_pk_bf16_f32 v151, v180, v181
	v_cvt_pk_bf16_f32 v152, v186, v187
	v_cvt_pk_bf16_f32 v153, v184, v185
	global_store_dwordx4 v[156:157], v[150:153], off offset:256

; #define PG8_STAGE(bufoff, gbase, voff) do { _Pragma("unroll") for (int _i = 0; _i < 2; ++_i) \
;         __builtin_amdgcn_global_load_lds((const unsigned*)((const char*)(gbase) + (voff)[_i]), (LAS unsigned*)(lds + (bufoff) + ldsw + _i * 8192), 16, 0, 0); } while (0)
; #define PG8_LDA(dst, b, h) do { _Pragma("unroll") for (int m = 0; m < 4; ++m) _Pragma("unroll") for (int k = 0; k < 2; ++k) dst[m][k] = *(const LAS bf16x8*)(lds + PG8_SA(b, h) + aoff + m * 2048 + k * 1024); } while (0)
; #define PG8_LDB(dst, b, h) do { _Pragma("unroll") for (int n = 0; n < 2; ++n) _Pragma("unroll") for (int k = 0; k < 2; ++k) dst[n][k] = *(const LAS bf16x8*)(lds + PG8_SB(b, h) + boff + n * 2048 + k * 1024); } while (0)
; #define PG8_WAIT_V(n) asm volatile("s_waitcnt vmcnt(" #n ")" ::: "memory")
; #define PG8_WAIT_L(n) asm volatile("s_waitcnt lgkmcnt(" #n ")" ::: "memory")
; #define PG8_BAR __builtin_amdgcn_s_barrier()
; #define PG8_SCHED __builtin_amdgcn_sched_barrier(0)
; template <class Epi>
; __device__ __forceinline__ void gemm_phase(LAS unsigned char* lds, const Gemm g, const StaticOrder& S, const Epi& E) {
;     ...
;         const bool has_next = S.next(ui + 1, nxt);
;         const char* nA = has_next ? (const char*)g.A + (size_t)nxt.pm * tstep : cA; const char* nB = has_next ? (const char*)g.Bt + (size_t)nxt.pn * tstep : cB;
;         for (int t = 0; t < nt; t += 2) {
;             const bool last = (t == nt - 2);
;             const char* a1 = cA + (size_t)(t + 1) * kstep;
;             const char* a2 = last ? nA : cA + (size_t)(t + 2) * kstep; const char* b2 = last ? nB : cB + (size_t)(t + 2) * kstep;
;             const char* a3 = a2 + kstep; const char* b3 = b2 + kstep;
;             PG8_LDB(B0, 0, 0); PG8_SCHED; PG8_LDA(At, 0, 0); PG8_STAGE(PG8_SA(1, 1), a1 + hstep, voffA);
;             PG8_WAIT_L(8); PG8_BAR; PG8_WAIT_L(0); PG8_MMA(0, 0, At, B0); PG8_BAR; PG8_SCHED;
;             PG8_LDB(B1, 0, 1); PG8_STAGE(PG8_SB(0, 0), b2, voffB);
;             PG8_BAR; PG8_WAIT_L(0); PG8_MMA(0, 1, At, B1); PG8_BAR;
;             PG8_LDA(At, 0, 1); PG8_STAGE(PG8_SA(0, 0), a2, voffA);
;             PG8_BAR; PG8_WAIT_L(0); PG8_MMA(1, 0, At, B0); PG8_BAR; PG8_SCHED;
;             PG8_STAGE(PG8_SB(0, 1), b2 + hstep, voffB);
;             PG8_WAIT_V(6); PG8_BAR; PG8_MMA(1, 1, At, B1); PG8_BAR;
.LBB0_673:
	ds_read_b128 v[148:151], v145
	ds_read_b128 v[152:155], v145 offset:1024
	ds_read_b128 v[160:163], v145 offset:2048
	ds_read_b128 v[164:167], v145 offset:3072
	s_add_u32 s52, s50, 0xfff80080
	s_addc_u32 s53, s51, -1
	s_cmp_eq_u32 s69, 28
	s_cselect_b32 s55, s43, s53
	s_cselect_b32 s54, s65, s52
	s_cselect_b32 s53, s41, s68
	s_cselect_b32 s52, s66, s67
	s_add_i32 m0, s28, 0xc000
	ds_read_b128 v[168:171], v146
	ds_read_b128 v[172:175], v146 offset:1024
	ds_read_b128 v[176:179], v146 offset:2048
	ds_read_b128 v[180:183], v146 offset:3072
	ds_read_b128 v[184:187], v146 offset:4096
	ds_read_b128 v[188:191], v146 offset:5120
	ds_read_b128 v[192:195], v146 offset:6144
	ds_read_b128 v[196:199], v146 offset:7168
	global_load_lds_dwordx4 v136, s[50:51]
	s_add_i32 m0, s28, 0xe000
	s_nop 0
	global_load_lds_dwordx4 v138, s[50:51]
	s_waitcnt lgkmcnt(8)
	s_barrier
	s_waitcnt lgkmcnt(0)
	v_mfma_f32_16x16x32_bf16 v[124:127], v[148:151], v[168:171], v[124:127]
	v_mfma_f32_16x16x32_bf16 v[120:123], v[160:163], v[168:171], v[120:123]
	v_mfma_f32_16x16x32_bf16 v[112:115], v[148:151], v[176:179], v[112:115]
	v_mfma_f32_16x16x32_bf16 v[104:107], v[160:163], v[176:179], v[104:107]
	v_mfma_f32_16x16x32_bf16 v[96:99], v[148:151], v[184:187], v[96:99]
	v_mfma_f32_16x16x32_bf16 v[88:91], v[160:163], v[184:187], v[88:91]
	v_mfma_f32_16x16x32_bf16 v[80:83], v[148:151], v[192:195], v[80:83]
	v_mfma_f32_16x16x32_bf16 v[72:75], v[160:163], v[192:195], v[72:75]
	v_mfma_f32_16x16x32_bf16 v[124:127], v[152:155], v[172:175], v[124:127]
	v_mfma_f32_16x16x32_bf16 v[120:123], v[164:167], v[172:175], v[120:123]
	v_mfma_f32_16x16x32_bf16 v[112:115], v[152:155], v[180:183], v[112:115]
	v_mfma_f32_16x16x32_bf16 v[104:107], v[164:167], v[180:183], v[104:107]
	v_mfma_f32_16x16x32_bf16 v[96:99], v[152:155], v[188:191], v[96:99]
	v_mfma_f32_16x16x32_bf16 v[88:91], v[164:167], v[188:191], v[88:91]
	v_mfma_f32_16x16x32_bf16 v[80:83], v[152:155], v[196:199], v[80:83]
	v_mfma_f32_16x16x32_bf16 v[72:75], v[164:167], v[196:199], v[72:75]
	s_barrier
	s_add_i32 s70, s58, s23
	s_add_u32 s98, s52, s6
	s_addc_u32 s99, s53, s7
	s_mov_b32 m0, s70
	ds_read_b128 v[200:203], v147
	ds_read_b128 v[204:207], v147 offset:1024
	ds_read_b128 v[208:211], v147 offset:2048
	ds_read_b128 v[212:215], v147 offset:3072
	global_load_lds_dwordx4 v132, s[52:53]
	s_add_i32 m0, s70, 0x2000
	s_nop 0
	global_load_lds_dwordx4 v128, s[52:53]
	s_waitcnt lgkmcnt(0)
	s_barrier
	v_mfma_f32_16x16x32_bf16 v[116:119], v[200:203], v[168:171], v[116:119]
	v_mfma_f32_16x16x32_bf16 v[108:111], v[208:211], v[168:171], v[108:111]
	v_mfma_f32_16x16x32_bf16 v[100:103], v[200:203], v[176:179], v[100:103]
	v_mfma_f32_16x16x32_bf16 v[92:95], v[208:211], v[176:179], v[92:95]
	v_mfma_f32_16x16x32_bf16 v[84:87], v[200:203], v[184:187], v[84:87]
	v_mfma_f32_16x16x32_bf16 v[76:79], v[208:211], v[184:187], v[76:79]
	v_mfma_f32_16x16x32_bf16 v[68:71], v[200:203], v[192:195], v[68:71]
	v_mfma_f32_16x16x32_bf16 v[64:67], v[208:211], v[192:195], v[64:67]
	v_mfma_f32_16x16x32_bf16 v[116:119], v[204:207], v[172:175], v[116:119]
	v_mfma_f32_16x16x32_bf16 v[108:111], v[212:215], v[172:175], v[108:111]
	v_mfma_f32_16x16x32_bf16 v[100:103], v[204:207], v[180:183], v[100:103]
	v_mfma_f32_16x16x32_bf16 v[92:95], v[212:215], v[180:183], v[92:95]
	v_mfma_f32_16x16x32_bf16 v[84:87], v[204:207], v[188:191], v[84:87]
	v_mfma_f32_16x16x32_bf16 v[76:79], v[212:215], v[188:191], v[76:79]
	v_mfma_f32_16x16x32_bf16 v[68:71], v[204:207], v[196:199], v[68:71]
	v_mfma_f32_16x16x32_bf16 v[64:67], v[212:215], v[196:199], v[64:67]
	s_mov_b32 m0, s28
	s_add_u32 s100, s54, s6
	s_addc_u32 s101, s55, s7
	s_barrier
	ds_read_b128 v[168:171], v146 offset:16384
	ds_read_b128 v[172:175], v146 offset:17408
	ds_read_b128 v[176:179], v146 offset:18432
	ds_read_b128 v[180:183], v146 offset:19456
	ds_read_b128 v[184:187], v146 offset:20480
	ds_read_b128 v[188:191], v146 offset:21504
	ds_read_b128 v[192:195], v146 offset:22528
	ds_read_b128 v[196:199], v146 offset:23552
	global_load_lds_dwordx4 v134, s[54:55]
	s_mov_b32 m0, s29
	s_nop 0
	global_load_lds_dwordx4 v130, s[54:55]
	s_waitcnt lgkmcnt(0)
	s_barrier
	v_mfma_f32_16x16x32_bf16 v[60:63], v[148:151], v[168:171], v[60:63]
	v_mfma_f32_16x16x32_bf16 v[56:59], v[160:163], v[168:171], v[56:59]
	v_mfma_f32_16x16x32_bf16 v[52:55], v[148:151], v[176:179], v[52:55]
	v_mfma_f32_16x16x32_bf16 v[44:47], v[160:163], v[176:179], v[44:47]
	v_mfma_f32_16x16x32_bf16 v[36:39], v[148:151], v[184:187], v[36:39]
	v_mfma_f32_16x16x32_bf16 v[28:31], v[160:163], v[184:187], v[28:31]
	v_mfma_f32_16x16x32_bf16 v[20:23], v[148:151], v[192:195], v[20:23]
	v_mfma_f32_16x16x32_bf16 v[12:15], v[160:163], v[192:195], v[12:15]
	v_mfma_f32_16x16x32_bf16 v[60:63], v[152:155], v[172:175], v[60:63]
	v_mfma_f32_16x16x32_bf16 v[56:59], v[164:167], v[172:175], v[56:59]
	v_mfma_f32_16x16x32_bf16 v[52:55], v[152:155], v[180:183], v[52:55]
	v_mfma_f32_16x16x32_bf16 v[44:47], v[164:167], v[180:183], v[44:47]
	v_mfma_f32_16x16x32_bf16 v[36:39], v[152:155], v[188:191], v[36:39]
	v_mfma_f32_16x16x32_bf16 v[28:31], v[164:167], v[188:191], v[28:31]
	v_mfma_f32_16x16x32_bf16 v[20:23], v[152:155], v[196:199], v[20:23]
	v_mfma_f32_16x16x32_bf16 v[12:15], v[164:167], v[196:199], v[12:15]
	s_barrier
	s_add_u32 s70, s52, 0x80000
	s_addc_u32 s71, s53, 0
	s_add_i32 s72, s59, s23
	s_mov_b32 m0, s72
	s_nop 0
	global_load_lds_dwordx4 v132, s[70:71]
	s_add_i32 m0, s72, 0x2000
	s_nop 0
	global_load_lds_dwordx4 v128, s[70:71]
	s_waitcnt vmcnt(6)
	s_barrier
; #define PG8_STAGE(bufoff, gbase, voff) do { _Pragma("unroll") for (int _i = 0; _i < 2; ++_i) \
;         __builtin_amdgcn_global_load_lds((const unsigned*)((const char*)(gbase) + (voff)[_i]), (LAS unsigned*)(lds + (bufoff) + ldsw + _i * 8192), 16, 0, 0); } while (0)
; #define PG8_LDA(dst, b, h) do { _Pragma("unroll") for (int m = 0; m < 4; ++m) _Pragma("unroll") for (int k = 0; k < 2; ++k) dst[m][k] = *(const LAS bf16x8*)(lds + PG8_SA(b, h) + aoff + m * 2048 + k * 1024); } while (0)
; #define PG8_LDB(dst, b, h) do { _Pragma("unroll") for (int n = 0; n < 2; ++n) _Pragma("unroll") for (int k = 0; k < 2; ++k) dst[n][k] = *(const LAS bf16x8*)(lds + PG8_SB(b, h) + boff + n * 2048 + k * 1024); } while (0)
; #define PG8_MMA(ai, bj, At, Bt) do { __builtin_amdgcn_s_setprio(1); _Pragma("unroll") for (int m = 0; m < 4; ++m) _Pragma("unroll") for (int n = 0; n < 2; ++n) _Pragma("unroll") for (int k = 0; k < 2; ++k) \
;         acc[ai][bj][m][n] = __builtin_amdgcn_mfma_f32_16x16x32_bf16(Bt[n][k], At[m][k], acc[ai][bj][m][n], 0, 0, 0); __builtin_amdgcn_s_setprio(0); } while (0)
; #define PG8_WAIT_V(n) asm volatile("s_waitcnt vmcnt(" #n ")" ::: "memory")
; #define PG8_WAIT_L(n) asm volatile("s_waitcnt lgkmcnt(" #n ")" ::: "memory")
; #define PG8_BAR __builtin_amdgcn_s_barrier()
; #define PG8_SCHED __builtin_amdgcn_sched_barrier(0)
; template <class Epi>
; __device__ __forceinline__ void gemm_phase(LAS unsigned char* lds, const Gemm g, const StaticOrder& S, const Epi& E) {
;     ...
;             PG8_WAIT_V(6); PG8_BAR; PG8_MMA(1, 1, At, B1); PG8_BAR;
;             PG8_LDB(B0, 1, 0); PG8_SCHED; PG8_LDA(At, 1, 0); PG8_STAGE(PG8_SA(0, 1), a2 + hstep, voffA);
;             PG8_WAIT_L(8); PG8_BAR; PG8_WAIT_L(0); PG8_MMA(0, 0, At, B0); PG8_BAR; PG8_SCHED;
;             PG8_LDB(B1, 1, 1); PG8_STAGE(PG8_SB(1, 0), b3, voffB);
;             PG8_BAR; PG8_WAIT_L(0); PG8_MMA(0, 1, At, B1); PG8_BAR;
;             PG8_LDA(At, 1, 1); PG8_STAGE(PG8_SA(1, 0), a3, voffA);
;             PG8_BAR; PG8_WAIT_L(0); PG8_MMA(1, 0, At, B0); PG8_BAR; PG8_SCHED;
	v_mfma_f32_16x16x32_bf16 v[48:51], v[200:203], v[168:171], v[48:51]
	v_mfma_f32_16x16x32_bf16 v[40:43], v[208:211], v[168:171], v[40:43]
	v_mfma_f32_16x16x32_bf16 v[32:35], v[200:203], v[176:179], v[32:35]
	v_mfma_f32_16x16x32_bf16 v[24:27], v[208:211], v[176:179], v[24:27]
	v_mfma_f32_16x16x32_bf16 v[16:19], v[200:203], v[184:187], v[16:19]
	v_mfma_f32_16x16x32_bf16 v[8:11], v[208:211], v[184:187], v[8:11]
	v_mfma_f32_16x16x32_bf16 v[4:7], v[200:203], v[192:195], v[4:7]
	v_mfma_f32_16x16x32_bf16 v[0:3], v[208:211], v[192:195], v[0:3]
	v_mfma_f32_16x16x32_bf16 v[48:51], v[204:207], v[172:175], v[48:51]
	v_mfma_f32_16x16x32_bf16 v[40:43], v[212:215], v[172:175], v[40:43]
	v_mfma_f32_16x16x32_bf16 v[32:35], v[204:207], v[180:183], v[32:35]
	v_mfma_f32_16x16x32_bf16 v[24:27], v[212:215], v[180:183], v[24:27]
	v_mfma_f32_16x16x32_bf16 v[16:19], v[204:207], v[188:191], v[16:19]
	v_mfma_f32_16x16x32_bf16 v[8:11], v[212:215], v[188:191], v[8:11]
	v_mfma_f32_16x16x32_bf16 v[4:7], v[204:207], v[196:199], v[4:7]
	v_mfma_f32_16x16x32_bf16 v[0:3], v[212:215], v[196:199], v[0:3]
	s_add_i32 s70, 0, 0x18000
	v_add_u32_e32 v164, s70, v143
	s_barrier
	ds_read_b128 v[148:151], v164
	ds_read_b128 v[152:155], v164 offset:1024
	ds_read_b128 v[160:163], v164 offset:2048
	ds_read_b128 v[164:167], v164 offset:3072
	s_add_u32 s54, s54, 0x80000
	s_addc_u32 s55, s55, 0
	s_mov_b32 m0, s33
	ds_read_b128 v[168:171], v146 offset:32768
	ds_read_b128 v[172:175], v146 offset:33792
	ds_read_b128 v[176:179], v146 offset:34816
	ds_read_b128 v[180:183], v146 offset:35840
	ds_read_b128 v[184:187], v146 offset:36864
	ds_read_b128 v[188:191], v146 offset:37888
	ds_read_b128 v[192:195], v146 offset:38912
	ds_read_b128 v[196:199], v146 offset:39936
	global_load_lds_dwordx4 v134, s[54:55]
	s_mov_b32 m0, s36
	s_nop 0
	global_load_lds_dwordx4 v130, s[54:55]
	s_waitcnt lgkmcnt(8)
	s_barrier
	s_waitcnt lgkmcnt(0)
	v_mfma_f32_16x16x32_bf16 v[124:127], v[148:151], v[168:171], v[124:127]
	v_mfma_f32_16x16x32_bf16 v[120:123], v[160:163], v[168:171], v[120:123]
	v_mfma_f32_16x16x32_bf16 v[112:115], v[148:151], v[176:179], v[112:115]
	v_mfma_f32_16x16x32_bf16 v[104:107], v[160:163], v[176:179], v[104:107]
	v_mfma_f32_16x16x32_bf16 v[96:99], v[148:151], v[184:187], v[96:99]
	v_mfma_f32_16x16x32_bf16 v[88:91], v[160:163], v[184:187], v[88:91]
	v_mfma_f32_16x16x32_bf16 v[80:83], v[148:151], v[192:195], v[80:83]
	v_mfma_f32_16x16x32_bf16 v[72:75], v[160:163], v[192:195], v[72:75]
	v_mfma_f32_16x16x32_bf16 v[124:127], v[152:155], v[172:175], v[124:127]
	v_mfma_f32_16x16x32_bf16 v[120:123], v[164:167], v[172:175], v[120:123]
	v_mfma_f32_16x16x32_bf16 v[112:115], v[152:155], v[180:183], v[112:115]
	v_mfma_f32_16x16x32_bf16 v[104:107], v[164:167], v[180:183], v[104:107]
	v_mfma_f32_16x16x32_bf16 v[96:99], v[152:155], v[188:191], v[96:99]
	v_mfma_f32_16x16x32_bf16 v[88:91], v[164:167], v[188:191], v[88:91]
	v_mfma_f32_16x16x32_bf16 v[80:83], v[152:155], v[196:199], v[80:83]
	v_mfma_f32_16x16x32_bf16 v[72:75], v[164:167], v[196:199], v[72:75]
	s_barrier
	s_add_i32 s54, 0, 0x1c000
	s_add_i32 s55, s70, s23
	v_add_u32_e32 v212, s54, v143
	s_mov_b32 m0, s55
	ds_read_b128 v[200:203], v212
	ds_read_b128 v[204:207], v212 offset:1024
	ds_read_b128 v[208:211], v212 offset:2048
	ds_read_b128 v[212:215], v212 offset:3072
	global_load_lds_dwordx4 v132, s[98:99]
	s_add_i32 m0, s55, 0x2000
	s_nop 0
	global_load_lds_dwordx4 v128, s[98:99]
	s_waitcnt lgkmcnt(0)
	s_barrier
	v_mfma_f32_16x16x32_bf16 v[116:119], v[200:203], v[168:171], v[116:119]
	v_mfma_f32_16x16x32_bf16 v[108:111], v[208:211], v[168:171], v[108:111]
	v_mfma_f32_16x16x32_bf16 v[100:103], v[200:203], v[176:179], v[100:103]
	v_mfma_f32_16x16x32_bf16 v[92:95], v[208:211], v[176:179], v[92:95]
	v_mfma_f32_16x16x32_bf16 v[84:87], v[200:203], v[184:187], v[84:87]
	v_mfma_f32_16x16x32_bf16 v[76:79], v[208:211], v[184:187], v[76:79]
	v_mfma_f32_16x16x32_bf16 v[68:71], v[200:203], v[192:195], v[68:71]
	v_mfma_f32_16x16x32_bf16 v[64:67], v[208:211], v[192:195], v[64:67]
	v_mfma_f32_16x16x32_bf16 v[116:119], v[204:207], v[172:175], v[116:119]
	v_mfma_f32_16x16x32_bf16 v[108:111], v[212:215], v[172:175], v[108:111]
	v_mfma_f32_16x16x32_bf16 v[100:103], v[204:207], v[180:183], v[100:103]
	v_mfma_f32_16x16x32_bf16 v[92:95], v[212:215], v[180:183], v[92:95]
	v_mfma_f32_16x16x32_bf16 v[84:87], v[204:207], v[188:191], v[84:87]
	v_mfma_f32_16x16x32_bf16 v[76:79], v[212:215], v[188:191], v[76:79]
	v_mfma_f32_16x16x32_bf16 v[68:71], v[204:207], v[196:199], v[68:71]
	v_mfma_f32_16x16x32_bf16 v[64:67], v[212:215], v[196:199], v[64:67]
	s_mov_b32 m0, s49
	s_barrier
	ds_read_b128 v[168:171], v146 offset:49152
	ds_read_b128 v[172:175], v146 offset:50176
	ds_read_b128 v[176:179], v146 offset:51200
	ds_read_b128 v[180:183], v146 offset:52224
	ds_read_b128 v[184:187], v146 offset:53248
	ds_read_b128 v[188:191], v146 offset:54272
	ds_read_b128 v[192:195], v146 offset:55296
	ds_read_b128 v[196:199], v146 offset:56320
	global_load_lds_dwordx4 v134, s[100:101]
	s_mov_b32 m0, s56
	s_nop 0
	global_load_lds_dwordx4 v130, s[100:101]
	s_waitcnt lgkmcnt(0)
	s_barrier
; #define PG8_STAGE(bufoff, gbase, voff) do { _Pragma("unroll") for (int _i = 0; _i < 2; ++_i) \
;         __builtin_amdgcn_global_load_lds((const unsigned*)((const char*)(gbase) + (voff)[_i]), (LAS unsigned*)(lds + (bufoff) + ldsw + _i * 8192), 16, 0, 0); } while (0)
; #define PG8_MMA(ai, bj, At, Bt) do { __builtin_amdgcn_s_setprio(1); _Pragma("unroll") for (int m = 0; m < 4; ++m) _Pragma("unroll") for (int n = 0; n < 2; ++n) _Pragma("unroll") for (int k = 0; k < 2; ++k) \
;         acc[ai][bj][m][n] = __builtin_amdgcn_mfma_f32_16x16x32_bf16(Bt[n][k], At[m][k], acc[ai][bj][m][n], 0, 0, 0); __builtin_amdgcn_s_setprio(0); } while (0)
; #define PG8_WAIT_V(n) asm volatile("s_waitcnt vmcnt(" #n ")" ::: "memory")
; #define PG8_WAIT_L(n) asm volatile("s_waitcnt lgkmcnt(" #n ")" ::: "memory")
; #define PG8_BAR __builtin_amdgcn_s_barrier()
; #define PG8_SCHED __builtin_amdgcn_sched_barrier(0)
; template <class Epi>
; __device__ __forceinline__ void gemm_phase(LAS unsigned char* lds, const Gemm g, const StaticOrder& S, const Epi& E) {
;     ...
;         for (int t = 0; t < nt; t += 2) {
;     ...
;             PG8_BAR; PG8_WAIT_L(0); PG8_MMA(1, 0, At, B0); PG8_BAR; PG8_SCHED;
;             PG8_STAGE(PG8_SB(1, 1), b3 + hstep, voffB);
;             PG8_WAIT_V(6); PG8_BAR; PG8_MMA(1, 1, At, B1); PG8_BAR;
	v_mfma_f32_16x16x32_bf16 v[60:63], v[148:151], v[168:171], v[60:63]
	v_mfma_f32_16x16x32_bf16 v[56:59], v[160:163], v[168:171], v[56:59]
	v_mfma_f32_16x16x32_bf16 v[52:55], v[148:151], v[176:179], v[52:55]
	v_mfma_f32_16x16x32_bf16 v[44:47], v[160:163], v[176:179], v[44:47]
	v_mfma_f32_16x16x32_bf16 v[36:39], v[148:151], v[184:187], v[36:39]
	v_mfma_f32_16x16x32_bf16 v[28:31], v[160:163], v[184:187], v[28:31]
	v_mfma_f32_16x16x32_bf16 v[20:23], v[148:151], v[192:195], v[20:23]
	v_mfma_f32_16x16x32_bf16 v[12:15], v[160:163], v[192:195], v[12:15]
	v_mfma_f32_16x16x32_bf16 v[60:63], v[152:155], v[172:175], v[60:63]
	v_mfma_f32_16x16x32_bf16 v[56:59], v[164:167], v[172:175], v[56:59]
	v_mfma_f32_16x16x32_bf16 v[52:55], v[152:155], v[180:183], v[52:55]
	v_mfma_f32_16x16x32_bf16 v[44:47], v[164:167], v[180:183], v[44:47]
	v_mfma_f32_16x16x32_bf16 v[36:39], v[152:155], v[188:191], v[36:39]
	v_mfma_f32_16x16x32_bf16 v[28:31], v[164:167], v[188:191], v[28:31]
	v_mfma_f32_16x16x32_bf16 v[20:23], v[152:155], v[196:199], v[20:23]
	v_mfma_f32_16x16x32_bf16 v[12:15], v[164:167], v[196:199], v[12:15]
	s_barrier
	s_add_u32 s52, s52, 0x80080
	s_addc_u32 s53, s53, 0
	s_add_i32 s54, s54, s23
	s_mov_b32 m0, s54
	s_nop 0
	global_load_lds_dwordx4 v132, s[52:53]
	s_add_i32 m0, s54, 0x2000
	s_nop 0
	global_load_lds_dwordx4 v128, s[52:53]
	s_waitcnt vmcnt(6)
	s_barrier
	v_mfma_f32_16x16x32_bf16 v[48:51], v[200:203], v[168:171], v[48:51]
	v_mfma_f32_16x16x32_bf16 v[40:43], v[208:211], v[168:171], v[40:43]
	v_mfma_f32_16x16x32_bf16 v[32:35], v[200:203], v[176:179], v[32:35]
	v_mfma_f32_16x16x32_bf16 v[24:27], v[208:211], v[176:179], v[24:27]
	v_mfma_f32_16x16x32_bf16 v[16:19], v[200:203], v[184:187], v[16:19]
	v_mfma_f32_16x16x32_bf16 v[8:11], v[208:211], v[184:187], v[8:11]
	v_mfma_f32_16x16x32_bf16 v[4:7], v[200:203], v[192:195], v[4:7]
	v_mfma_f32_16x16x32_bf16 v[0:3], v[208:211], v[192:195], v[0:3]
	v_mfma_f32_16x16x32_bf16 v[48:51], v[204:207], v[172:175], v[48:51]
	v_mfma_f32_16x16x32_bf16 v[40:43], v[212:215], v[172:175], v[40:43]
	v_mfma_f32_16x16x32_bf16 v[32:35], v[204:207], v[180:183], v[32:35]
	v_mfma_f32_16x16x32_bf16 v[24:27], v[212:215], v[180:183], v[24:27]
	v_mfma_f32_16x16x32_bf16 v[16:19], v[204:207], v[188:191], v[16:19]
	v_mfma_f32_16x16x32_bf16 v[8:11], v[212:215], v[188:191], v[8:11]
	v_mfma_f32_16x16x32_bf16 v[4:7], v[204:207], v[196:199], v[4:7]
	v_mfma_f32_16x16x32_bf16 v[0:3], v[212:215], v[196:199], v[0:3]
	s_add_i32 s69, s69, 2
	s_add_u32 s50, s50, 0x100
	s_addc_u32 s51, s51, 0
	s_add_u32 s67, s67, 0x100
	s_addc_u32 s68, s68, 0
	s_cmp_gt_u32 s69, 29
	s_barrier
	s_cbranch_scc0 .LBB0_673
; #define PG8_WAIT_V(n) asm volatile("s_waitcnt vmcnt(" #n ")" ::: "memory")
; #define PG8_BAR __builtin_amdgcn_s_barrier()
; __device__ __forceinline__ u32x4 pack8(f32x4 v0, f32x4 v1) { u32x4 w; w.x = cvt_pk_bf16(v0[0], v0[1]); w.y = cvt_pk_bf16(v0[2], v0[3]); w.z = cvt_pk_bf16(v1[0], v1[1]); w.w = cvt_pk_bf16(v1[2], v1[3]); return w; }
; template <class Epi>
; __device__ __forceinline__ void gemm_phase(LAS unsigned char* lds, const Gemm g, const StaticOrder& S, const Epi& E) {
;     ...
;         cur = nxt; cA = nA; cB = nB; ++ui;
;     }
;     PG8_WAIT_V(0);
;     if (wr == 0) PG8_BAR;
;     PG8_BAR;
;     __device__ __forceinline__ void operator()(const f32x4 (&acc)[2][2][4][2], const Unit& u, int wr, int wc, int fr, int fq) const {
;         const int row0 = u.pm * BM + wr * 64 + fr, col0 = u.pn * BM + wc * 32 + 8 * fq;
; #pragma unroll
;         for (int ai = 0; ai < 2; ++ai)
; #pragma unroll
;             for (int m = 0; m < 4; ++m) { bf16_t* rowp = O + (size_t)(row0 + ai * HALF + m * 16) * ldc + col0;
; #pragma unroll
;                 for (int bj = 0; bj < 2; ++bj) *(u32x4*)(rowp + bj * HALF) = pack8(acc[ai][bj][m][0], acc[ai][bj][m][1]); }
	v_lshl_add_u32 v148, s48, 8, v142
	v_lshl_or_b32 v140, s64, 8, v144
	v_ashrrev_i32_e32 v149, 31, v148
	v_ashrrev_i32_e32 v141, 31, v140
	v_lshlrev_b64 v[150:151], 12, v[148:149]
	v_lshl_add_u64 v[150:151], s[24:25], 0, v[150:151]
	v_lshlrev_b64 v[152:153], 1, v[140:141]
	v_lshl_add_u64 v[140:141], v[150:151], 0, v[152:153]
	v_cvt_pk_bf16_f32 v124, v124, v125
	v_cvt_pk_bf16_f32 v125, v126, v127
	v_cvt_pk_bf16_f32 v126, v120, v121
	v_cvt_pk_bf16_f32 v127, v122, v123
	global_store_dwordx4 v[140:141], v[124:127], off
	v_cvt_pk_bf16_f32 v116, v116, v117
	v_cvt_pk_bf16_f32 v117, v118, v119
	v_cvt_pk_bf16_f32 v118, v108, v109
	v_or_b32_e32 v108, 16, v148
	v_ashrrev_i32_e32 v109, 31, v108
	v_lshlrev_b64 v[108:109], 12, v[108:109]
	v_lshl_add_u64 v[108:109], s[24:25], 0, v[108:109]
	v_cvt_pk_bf16_f32 v119, v110, v111
	global_store_dwordx4 v[140:141], v[116:119], off offset:256
	s_mov_b32 s64, s40
	s_mov_b32 s48, s42
	v_lshl_add_u64 v[116:117], v[108:109], 0, v[152:153]
	v_cvt_pk_bf16_f32 v108, v112, v113
	v_cvt_pk_bf16_f32 v109, v114, v115
	v_cvt_pk_bf16_f32 v110, v104, v105
	v_cvt_pk_bf16_f32 v111, v106, v107
	global_store_dwordx4 v[116:117], v[108:111], off
	v_cvt_pk_bf16_f32 v100, v100, v101
	v_cvt_pk_bf16_f32 v101, v102, v103
	v_cvt_pk_bf16_f32 v102, v92, v93
	v_or_b32_e32 v92, 32, v148
	v_ashrrev_i32_e32 v93, 31, v92
	v_lshlrev_b64 v[92:93], 12, v[92:93]
	v_lshl_add_u64 v[92:93], s[24:25], 0, v[92:93]
	v_cvt_pk_bf16_f32 v103, v94, v95
	global_store_dwordx4 v[116:117], v[100:103], off offset:256
	s_mov_b64 s[52:53], s[46:47]
	s_mov_b64 s[50:51], s[44:45]
	v_lshl_add_u64 v[100:101], v[92:93], 0, v[152:153]
	v_cvt_pk_bf16_f32 v92, v96, v97
	v_cvt_pk_bf16_f32 v93, v98, v99
	v_cvt_pk_bf16_f32 v94, v88, v89
	v_cvt_pk_bf16_f32 v95, v90, v91
	global_store_dwordx4 v[100:101], v[92:95], off
	v_cvt_pk_bf16_f32 v84, v84, v85
	v_cvt_pk_bf16_f32 v85, v86, v87
	v_cvt_pk_bf16_f32 v86, v76, v77
	v_or_b32_e32 v76, 48, v148
	v_ashrrev_i32_e32 v77, 31, v76
	v_lshlrev_b64 v[76:77], 12, v[76:77]
	v_lshl_add_u64 v[76:77], s[24:25], 0, v[76:77]
	v_cvt_pk_bf16_f32 v87, v78, v79
	global_store_dwordx4 v[100:101], v[84:87], off offset:256
	s_nop 1
	v_lshl_add_u64 v[84:85], v[76:77], 0, v[152:153]
	v_cvt_pk_bf16_f32 v76, v80, v81
	v_cvt_pk_bf16_f32 v77, v82, v83
	v_cvt_pk_bf16_f32 v78, v72, v73
	v_cvt_pk_bf16_f32 v79, v74, v75
	global_store_dwordx4 v[84:85], v[76:79], off
	v_cvt_pk_bf16_f32 v68, v68, v69
	v_cvt_pk_bf16_f32 v69, v70, v71
	v_cvt_pk_bf16_f32 v70, v64, v65
	v_cvt_pk_bf16_f32 v71, v66, v67
	global_store_dwordx4 v[84:85], v[68:71], off offset:256
	v_cvt_pk_bf16_f32 v60, v60, v61
	v_cvt_pk_bf16_f32 v61, v62, v63
	v_cvt_pk_bf16_f32 v62, v56, v57
	v_add_co_u32_e32 v56, vcc, s60, v140
	v_lshl_add_u64 v[64:65], v[140:141], 0, s[2:3]
	s_nop 0
	v_addc_co_u32_e32 v57, vcc, 0, v141, vcc
	v_cvt_pk_bf16_f32 v63, v58, v59
	global_store_dwordx4 v[56:57], v[60:63], off
	v_cvt_pk_bf16_f32 v48, v48, v49
	v_cvt_pk_bf16_f32 v49, v50, v51
	v_cvt_pk_bf16_f32 v50, v40, v41
	v_cvt_pk_bf16_f32 v51, v42, v43
	global_store_dwordx4 v[64:65], v[48:51], off offset:256
	v_cvt_pk_bf16_f32 v40, v52, v53
	v_cvt_pk_bf16_f32 v41, v54, v55
	v_cvt_pk_bf16_f32 v42, v44, v45
	v_add_co_u32_e32 v44, vcc, s61, v140
	s_nop 0
	v_lshl_add_u64 v[48:49], v[140:141], 0, s[8:9]
	v_addc_co_u32_e32 v45, vcc, 0, v141, vcc
	v_cvt_pk_bf16_f32 v43, v46, v47
	global_store_dwordx4 v[44:45], v[40:43], off
	v_cvt_pk_bf16_f32 v32, v32, v33
	v_cvt_pk_bf16_f32 v33, v34, v35
	v_cvt_pk_bf16_f32 v34, v24, v25
	v_cvt_pk_bf16_f32 v35, v26, v27
	global_store_dwordx4 v[48:49], v[32:35], off offset:256
	v_cvt_pk_bf16_f32 v24, v36, v37
	v_cvt_pk_bf16_f32 v25, v38, v39
	v_cvt_pk_bf16_f32 v26, v28, v29
	v_add_co_u32_e32 v28, vcc, s62, v140
	s_nop 0
	v_lshl_add_u64 v[32:33], v[140:141], 0, s[30:31]
	v_addc_co_u32_e32 v29, vcc, 0, v141, vcc
	v_cvt_pk_bf16_f32 v27, v30, v31
	global_store_dwordx4 v[28:29], v[24:27], off
	v_cvt_pk_bf16_f32 v16, v16, v17
	v_cvt_pk_bf16_f32 v17, v18, v19
	v_cvt_pk_bf16_f32 v18, v8, v9
	v_cvt_pk_bf16_f32 v19, v10, v11
	global_store_dwordx4 v[32:33], v[16:19], off offset:256
	v_cvt_pk_bf16_f32 v8, v20, v21
	v_cvt_pk_bf16_f32 v9, v22, v23
	v_cvt_pk_bf16_f32 v10, v12, v13
	v_add_co_u32_e32 v12, vcc, s63, v140
	s_nop 0
	v_lshl_add_u64 v[16:17], v[140:141], 0, s[34:35]
	v_addc_co_u32_e32 v13, vcc, 0, v141, vcc
	s_and_b64 vcc, exec, s[38:39]
	v_cvt_pk_bf16_f32 v11, v14, v15
	global_store_dwordx4 v[12:13], v[8:11], off
	v_cvt_pk_bf16_f32 v4, v4, v5
	v_cvt_pk_bf16_f32 v5, v6, v7
	v_cvt_pk_bf16_f32 v6, v0, v1
	v_cvt_pk_bf16_f32 v7, v2, v3
	global_store_dwordx4 v[16:17], v[4:7], off offset:256
	s_cbranch_vccz .LBB0_670
	s_waitcnt vmcnt(0)
	s_cmpk_gt_u32 s10, 0xff
	v_readlane_b32 s62, v232, 20
	v_readlane_b32 s61, v232, 21
	s_cbranch_scc1 .LBB0_677
	s_barrier

; #define PG8_STAGE(bufoff, gbase, voff) do { _Pragma("unroll") for (int _i = 0; _i < 2; ++_i) \
;         __builtin_amdgcn_global_load_lds((const unsigned*)((const char*)(gbase) + (voff)[_i]), (LAS unsigned*)(lds + (bufoff) + ldsw + _i * 8192), 16, 0, 0); } while (0)
; #define PG8_LDA(dst, b, h) do { _Pragma("unroll") for (int m = 0; m < 4; ++m) _Pragma("unroll") for (int k = 0; k < 2; ++k) dst[m][k] = *(const LAS bf16x8*)(lds + PG8_SA(b, h) + aoff + m * 2048 + k * 1024); } while (0)
; #define PG8_LDB(dst, b, h) do { _Pragma("unroll") for (int n = 0; n < 2; ++n) _Pragma("unroll") for (int k = 0; k < 2; ++k) dst[n][k] = *(const LAS bf16x8*)(lds + PG8_SB(b, h) + boff + n * 2048 + k * 1024); } while (0)
; #define PG8_WAIT_V(n) asm volatile("s_waitcnt vmcnt(" #n ")" ::: "memory")
; #define PG8_WAIT_L(n) asm volatile("s_waitcnt lgkmcnt(" #n ")" ::: "memory")
; #define PG8_BAR __builtin_amdgcn_s_barrier()
; #define PG8_SCHED __builtin_amdgcn_sched_barrier(0)
; template <class Epi>
; __device__ __forceinline__ void gemm_phase(LAS unsigned char* lds, const Gemm g, const StaticOrder& S, const Epi& E) {
;     ...
;         for (int t = 0; t < nt; t += 2) {
;             const bool last = (t == nt - 2);
;             const char* a1 = cA + (size_t)(t + 1) * kstep;
;             const char* a2 = last ? nA : cA + (size_t)(t + 2) * kstep; const char* b2 = last ? nB : cB + (size_t)(t + 2) * kstep;
;             const char* a3 = a2 + kstep; const char* b3 = b2 + kstep;
;             PG8_LDB(B0, 0, 0); PG8_SCHED; PG8_LDA(At, 0, 0); PG8_STAGE(PG8_SA(1, 1), a1 + hstep, voffA);
;             PG8_WAIT_L(8); PG8_BAR; PG8_WAIT_L(0); PG8_MMA(0, 0, At, B0); PG8_BAR; PG8_SCHED;
;             PG8_LDB(B1, 0, 1); PG8_STAGE(PG8_SB(0, 0), b2, voffB);
;             PG8_BAR; PG8_WAIT_L(0); PG8_MMA(0, 1, At, B1); PG8_BAR;
;             PG8_LDA(At, 0, 1); PG8_STAGE(PG8_SA(0, 0), a2, voffA);
;             PG8_BAR; PG8_WAIT_L(0); PG8_MMA(1, 0, At, B0); PG8_BAR; PG8_SCHED;
;             PG8_STAGE(PG8_SB(0, 1), b2 + hstep, voffB);
;             PG8_WAIT_V(6); PG8_BAR; PG8_MMA(1, 1, At, B1); PG8_BAR;
;             PG8_LDB(B0, 1, 0); PG8_SCHED; PG8_LDA(At, 1, 0); PG8_STAGE(PG8_SA(0, 1), a2 + hstep, voffA);
;             PG8_WAIT_L(8); PG8_BAR; PG8_WAIT_L(0); PG8_MMA(0, 0, At, B0); PG8_BAR; PG8_SCHED;
.LBB0_796:
	ds_read_b128 v[144:147], v155
	ds_read_b128 v[148:151], v155 offset:1024
	ds_read_b128 v[160:163], v155 offset:2048
	ds_read_b128 v[164:167], v155 offset:3072
	s_add_u32 s42, s40, 0xfff80080
	s_addc_u32 s43, s41, -1
	s_cmp_eq_u32 s58, 28
	s_cselect_b32 s45, s31, s43
	s_cselect_b32 s44, s54, s42
	s_cselect_b32 s43, s9, s57
	s_cselect_b32 s42, s55, s56
	s_add_i32 m0, s27, 0xc000
	ds_read_b128 v[168:171], v156
	ds_read_b128 v[172:175], v156 offset:1024
	ds_read_b128 v[176:179], v156 offset:2048
	ds_read_b128 v[180:183], v156 offset:3072
	ds_read_b128 v[184:187], v156 offset:4096
	ds_read_b128 v[188:191], v156 offset:5120
	ds_read_b128 v[192:195], v156 offset:6144
	ds_read_b128 v[196:199], v156 offset:7168
	global_load_lds_dwordx4 v136, s[40:41]
	s_add_i32 m0, s27, 0xe000
	s_nop 0
	global_load_lds_dwordx4 v138, s[40:41]
	s_waitcnt lgkmcnt(8)
	s_barrier
	s_waitcnt lgkmcnt(0)
	v_mfma_f32_16x16x32_bf16 v[124:127], v[144:147], v[168:171], v[124:127]
	v_mfma_f32_16x16x32_bf16 v[120:123], v[160:163], v[168:171], v[120:123]
	v_mfma_f32_16x16x32_bf16 v[108:111], v[144:147], v[176:179], v[108:111]
	v_mfma_f32_16x16x32_bf16 v[104:107], v[160:163], v[176:179], v[104:107]
	v_mfma_f32_16x16x32_bf16 v[92:95], v[144:147], v[184:187], v[92:95]
	v_mfma_f32_16x16x32_bf16 v[88:91], v[160:163], v[184:187], v[88:91]
	v_mfma_f32_16x16x32_bf16 v[76:79], v[144:147], v[192:195], v[76:79]
	v_mfma_f32_16x16x32_bf16 v[72:75], v[160:163], v[192:195], v[72:75]
	v_mfma_f32_16x16x32_bf16 v[124:127], v[148:151], v[172:175], v[124:127]
	v_mfma_f32_16x16x32_bf16 v[120:123], v[164:167], v[172:175], v[120:123]
	v_mfma_f32_16x16x32_bf16 v[108:111], v[148:151], v[180:183], v[108:111]
	v_mfma_f32_16x16x32_bf16 v[104:107], v[164:167], v[180:183], v[104:107]
	v_mfma_f32_16x16x32_bf16 v[92:95], v[148:151], v[188:191], v[92:95]
	v_mfma_f32_16x16x32_bf16 v[88:91], v[164:167], v[188:191], v[88:91]
	v_mfma_f32_16x16x32_bf16 v[76:79], v[148:151], v[196:199], v[76:79]
	v_mfma_f32_16x16x32_bf16 v[72:75], v[164:167], v[196:199], v[72:75]
	s_barrier
	s_add_i32 s59, s50, s23
	s_add_u32 s98, s42, s2
	s_addc_u32 s99, s43, s3
	s_mov_b32 m0, s59
	ds_read_b128 v[200:203], v157
	ds_read_b128 v[204:207], v157 offset:1024
	ds_read_b128 v[208:211], v157 offset:2048
	ds_read_b128 v[212:215], v157 offset:3072
	global_load_lds_dwordx4 v132, s[42:43]
	s_add_i32 m0, s59, 0x2000
	s_nop 0
	global_load_lds_dwordx4 v128, s[42:43]
	s_waitcnt lgkmcnt(0)
	s_barrier
	v_mfma_f32_16x16x32_bf16 v[116:119], v[200:203], v[168:171], v[116:119]
	v_mfma_f32_16x16x32_bf16 v[112:115], v[208:211], v[168:171], v[112:115]
	v_mfma_f32_16x16x32_bf16 v[100:103], v[200:203], v[176:179], v[100:103]
	v_mfma_f32_16x16x32_bf16 v[96:99], v[208:211], v[176:179], v[96:99]
	v_mfma_f32_16x16x32_bf16 v[84:87], v[200:203], v[184:187], v[84:87]
	v_mfma_f32_16x16x32_bf16 v[80:83], v[208:211], v[184:187], v[80:83]
	v_mfma_f32_16x16x32_bf16 v[68:71], v[200:203], v[192:195], v[68:71]
	v_mfma_f32_16x16x32_bf16 v[64:67], v[208:211], v[192:195], v[64:67]
	v_mfma_f32_16x16x32_bf16 v[116:119], v[204:207], v[172:175], v[116:119]
	v_mfma_f32_16x16x32_bf16 v[112:115], v[212:215], v[172:175], v[112:115]
	v_mfma_f32_16x16x32_bf16 v[100:103], v[204:207], v[180:183], v[100:103]
	v_mfma_f32_16x16x32_bf16 v[96:99], v[212:215], v[180:183], v[96:99]
	v_mfma_f32_16x16x32_bf16 v[84:87], v[204:207], v[188:191], v[84:87]
	v_mfma_f32_16x16x32_bf16 v[80:83], v[212:215], v[188:191], v[80:83]
	v_mfma_f32_16x16x32_bf16 v[68:71], v[204:207], v[196:199], v[68:71]
	v_mfma_f32_16x16x32_bf16 v[64:67], v[212:215], v[196:199], v[64:67]
	s_mov_b32 m0, s27
	s_add_u32 s100, s44, s2
	s_addc_u32 s101, s45, s3
	s_barrier
	ds_read_b128 v[168:171], v156 offset:16384
	ds_read_b128 v[172:175], v156 offset:17408
	ds_read_b128 v[176:179], v156 offset:18432
	ds_read_b128 v[180:183], v156 offset:19456
	ds_read_b128 v[184:187], v156 offset:20480
	ds_read_b128 v[188:191], v156 offset:21504
	ds_read_b128 v[192:195], v156 offset:22528
	ds_read_b128 v[196:199], v156 offset:23552
	global_load_lds_dwordx4 v134, s[44:45]
	s_mov_b32 m0, s28
	s_nop 0
	global_load_lds_dwordx4 v130, s[44:45]
	s_waitcnt lgkmcnt(0)
	s_barrier
	v_mfma_f32_16x16x32_bf16 v[60:63], v[144:147], v[168:171], v[60:63]
	v_mfma_f32_16x16x32_bf16 v[56:59], v[160:163], v[168:171], v[56:59]
	v_mfma_f32_16x16x32_bf16 v[44:47], v[144:147], v[176:179], v[44:47]
	v_mfma_f32_16x16x32_bf16 v[40:43], v[160:163], v[176:179], v[40:43]
	v_mfma_f32_16x16x32_bf16 v[28:31], v[144:147], v[184:187], v[28:31]
	v_mfma_f32_16x16x32_bf16 v[24:27], v[160:163], v[184:187], v[24:27]
	v_mfma_f32_16x16x32_bf16 v[12:15], v[144:147], v[192:195], v[12:15]
	v_mfma_f32_16x16x32_bf16 v[8:11], v[160:163], v[192:195], v[8:11]
	v_mfma_f32_16x16x32_bf16 v[60:63], v[148:151], v[172:175], v[60:63]
	v_mfma_f32_16x16x32_bf16 v[56:59], v[164:167], v[172:175], v[56:59]
	v_mfma_f32_16x16x32_bf16 v[44:47], v[148:151], v[180:183], v[44:47]
	v_mfma_f32_16x16x32_bf16 v[40:43], v[164:167], v[180:183], v[40:43]
	v_mfma_f32_16x16x32_bf16 v[28:31], v[148:151], v[188:191], v[28:31]
	v_mfma_f32_16x16x32_bf16 v[24:27], v[164:167], v[188:191], v[24:27]
	v_mfma_f32_16x16x32_bf16 v[12:15], v[148:151], v[196:199], v[12:15]
	v_mfma_f32_16x16x32_bf16 v[8:11], v[164:167], v[196:199], v[8:11]
	s_barrier
	s_add_u32 s60, s42, 0x80000
	s_addc_u32 s61, s43, 0
	s_add_i32 s59, s51, s23
	s_mov_b32 m0, s59
	s_nop 0
	global_load_lds_dwordx4 v132, s[60:61]
	s_add_i32 m0, s59, 0x2000
	s_nop 0
	global_load_lds_dwordx4 v128, s[60:61]
	s_waitcnt vmcnt(6)
	s_barrier
; #define PG8_STAGE(bufoff, gbase, voff) do { _Pragma("unroll") for (int _i = 0; _i < 2; ++_i) \
;         __builtin_amdgcn_global_load_lds((const unsigned*)((const char*)(gbase) + (voff)[_i]), (LAS unsigned*)(lds + (bufoff) + ldsw + _i * 8192), 16, 0, 0); } while (0)
; #define PG8_LDA(dst, b, h) do { _Pragma("unroll") for (int m = 0; m < 4; ++m) _Pragma("unroll") for (int k = 0; k < 2; ++k) dst[m][k] = *(const LAS bf16x8*)(lds + PG8_SA(b, h) + aoff + m * 2048 + k * 1024); } while (0)
; #define PG8_LDB(dst, b, h) do { _Pragma("unroll") for (int n = 0; n < 2; ++n) _Pragma("unroll") for (int k = 0; k < 2; ++k) dst[n][k] = *(const LAS bf16x8*)(lds + PG8_SB(b, h) + boff + n * 2048 + k * 1024); } while (0)
; #define PG8_MMA(ai, bj, At, Bt) do { __builtin_amdgcn_s_setprio(1); _Pragma("unroll") for (int m = 0; m < 4; ++m) _Pragma("unroll") for (int n = 0; n < 2; ++n) _Pragma("unroll") for (int k = 0; k < 2; ++k) \
;         acc[ai][bj][m][n] = __builtin_amdgcn_mfma_f32_16x16x32_bf16(Bt[n][k], At[m][k], acc[ai][bj][m][n], 0, 0, 0); __builtin_amdgcn_s_setprio(0); } while (0)
; #define PG8_WAIT_V(n) asm volatile("s_waitcnt vmcnt(" #n ")" ::: "memory")
; #define PG8_WAIT_L(n) asm volatile("s_waitcnt lgkmcnt(" #n ")" ::: "memory")
; #define PG8_BAR __builtin_amdgcn_s_barrier()
; #define PG8_SCHED __builtin_amdgcn_sched_barrier(0)
; template <class Epi>
; __device__ __forceinline__ void gemm_phase(LAS unsigned char* lds, const Gemm g, const StaticOrder& S, const Epi& E) {
;     ...
;             PG8_WAIT_V(6); PG8_BAR; PG8_MMA(1, 1, At, B1); PG8_BAR;
;             PG8_LDB(B0, 1, 0); PG8_SCHED; PG8_LDA(At, 1, 0); PG8_STAGE(PG8_SA(0, 1), a2 + hstep, voffA);
;             PG8_WAIT_L(8); PG8_BAR; PG8_WAIT_L(0); PG8_MMA(0, 0, At, B0); PG8_BAR; PG8_SCHED;
;             PG8_LDB(B1, 1, 1); PG8_STAGE(PG8_SB(1, 0), b3, voffB);
;             PG8_BAR; PG8_WAIT_L(0); PG8_MMA(0, 1, At, B1); PG8_BAR;
;             PG8_LDA(At, 1, 1); PG8_STAGE(PG8_SA(1, 0), a3, voffA);
;             PG8_BAR; PG8_WAIT_L(0); PG8_MMA(1, 0, At, B0); PG8_BAR; PG8_SCHED;
;             PG8_STAGE(PG8_SB(1, 1), b3 + hstep, voffB);
;             PG8_WAIT_V(6); PG8_BAR; PG8_MMA(1, 1, At, B1); PG8_BAR;
	v_mfma_f32_16x16x32_bf16 v[52:55], v[200:203], v[168:171], v[52:55]
	v_mfma_f32_16x16x32_bf16 v[48:51], v[208:211], v[168:171], v[48:51]
	v_mfma_f32_16x16x32_bf16 v[36:39], v[200:203], v[176:179], v[36:39]
	v_mfma_f32_16x16x32_bf16 v[32:35], v[208:211], v[176:179], v[32:35]
	v_mfma_f32_16x16x32_bf16 v[20:23], v[200:203], v[184:187], v[20:23]
	v_mfma_f32_16x16x32_bf16 v[16:19], v[208:211], v[184:187], v[16:19]
	v_mfma_f32_16x16x32_bf16 v[4:7], v[200:203], v[192:195], v[4:7]
	v_mfma_f32_16x16x32_bf16 v[0:3], v[208:211], v[192:195], v[0:3]
	v_mfma_f32_16x16x32_bf16 v[52:55], v[204:207], v[172:175], v[52:55]
	v_mfma_f32_16x16x32_bf16 v[48:51], v[212:215], v[172:175], v[48:51]
	v_mfma_f32_16x16x32_bf16 v[36:39], v[204:207], v[180:183], v[36:39]
	v_mfma_f32_16x16x32_bf16 v[32:35], v[212:215], v[180:183], v[32:35]
	v_mfma_f32_16x16x32_bf16 v[20:23], v[204:207], v[188:191], v[20:23]
	v_mfma_f32_16x16x32_bf16 v[16:19], v[212:215], v[188:191], v[16:19]
	v_mfma_f32_16x16x32_bf16 v[4:7], v[204:207], v[196:199], v[4:7]
	v_mfma_f32_16x16x32_bf16 v[0:3], v[212:215], v[196:199], v[0:3]
	s_add_i32 s59, 0, 0x18000
	v_add_u32_e32 v164, s59, v153
	s_barrier
	ds_read_b128 v[144:147], v164
	ds_read_b128 v[148:151], v164 offset:1024
	ds_read_b128 v[160:163], v164 offset:2048
	ds_read_b128 v[164:167], v164 offset:3072
	s_add_u32 s44, s44, 0x80000
	s_addc_u32 s45, s45, 0
	s_mov_b32 m0, s29
	ds_read_b128 v[168:171], v156 offset:32768
	ds_read_b128 v[172:175], v156 offset:33792
	ds_read_b128 v[176:179], v156 offset:34816
	ds_read_b128 v[180:183], v156 offset:35840
	ds_read_b128 v[184:187], v156 offset:36864
	ds_read_b128 v[188:191], v156 offset:37888
	ds_read_b128 v[192:195], v156 offset:38912
	ds_read_b128 v[196:199], v156 offset:39936
	global_load_lds_dwordx4 v134, s[44:45]
	s_mov_b32 m0, s33
	s_nop 0
	global_load_lds_dwordx4 v130, s[44:45]
	s_waitcnt lgkmcnt(8)
	s_barrier
	s_waitcnt lgkmcnt(0)
	v_mfma_f32_16x16x32_bf16 v[124:127], v[144:147], v[168:171], v[124:127]
	v_mfma_f32_16x16x32_bf16 v[120:123], v[160:163], v[168:171], v[120:123]
	v_mfma_f32_16x16x32_bf16 v[108:111], v[144:147], v[176:179], v[108:111]
	v_mfma_f32_16x16x32_bf16 v[104:107], v[160:163], v[176:179], v[104:107]
	v_mfma_f32_16x16x32_bf16 v[92:95], v[144:147], v[184:187], v[92:95]
	v_mfma_f32_16x16x32_bf16 v[88:91], v[160:163], v[184:187], v[88:91]
	v_mfma_f32_16x16x32_bf16 v[76:79], v[144:147], v[192:195], v[76:79]
	v_mfma_f32_16x16x32_bf16 v[72:75], v[160:163], v[192:195], v[72:75]
	v_mfma_f32_16x16x32_bf16 v[124:127], v[148:151], v[172:175], v[124:127]
	v_mfma_f32_16x16x32_bf16 v[120:123], v[164:167], v[172:175], v[120:123]
	v_mfma_f32_16x16x32_bf16 v[108:111], v[148:151], v[180:183], v[108:111]
	v_mfma_f32_16x16x32_bf16 v[104:107], v[164:167], v[180:183], v[104:107]
	v_mfma_f32_16x16x32_bf16 v[92:95], v[148:151], v[188:191], v[92:95]
	v_mfma_f32_16x16x32_bf16 v[88:91], v[164:167], v[188:191], v[88:91]
	v_mfma_f32_16x16x32_bf16 v[76:79], v[148:151], v[196:199], v[76:79]
	v_mfma_f32_16x16x32_bf16 v[72:75], v[164:167], v[196:199], v[72:75]
	s_barrier
	s_add_i32 s44, 0, 0x1c000
	s_add_i32 s45, s59, s23
	v_add_u32_e32 v212, s44, v153
	s_mov_b32 m0, s45
	ds_read_b128 v[200:203], v212
	ds_read_b128 v[204:207], v212 offset:1024
	ds_read_b128 v[208:211], v212 offset:2048
	ds_read_b128 v[212:215], v212 offset:3072
	global_load_lds_dwordx4 v132, s[98:99]
	s_add_i32 m0, s45, 0x2000
	s_nop 0
	global_load_lds_dwordx4 v128, s[98:99]
	s_waitcnt lgkmcnt(0)
	s_barrier
	v_mfma_f32_16x16x32_bf16 v[116:119], v[200:203], v[168:171], v[116:119]
	v_mfma_f32_16x16x32_bf16 v[112:115], v[208:211], v[168:171], v[112:115]
	v_mfma_f32_16x16x32_bf16 v[100:103], v[200:203], v[176:179], v[100:103]
	v_mfma_f32_16x16x32_bf16 v[96:99], v[208:211], v[176:179], v[96:99]
	v_mfma_f32_16x16x32_bf16 v[84:87], v[200:203], v[184:187], v[84:87]
	v_mfma_f32_16x16x32_bf16 v[80:83], v[208:211], v[184:187], v[80:83]
	v_mfma_f32_16x16x32_bf16 v[68:71], v[200:203], v[192:195], v[68:71]
	v_mfma_f32_16x16x32_bf16 v[64:67], v[208:211], v[192:195], v[64:67]
	v_mfma_f32_16x16x32_bf16 v[116:119], v[204:207], v[172:175], v[116:119]
	v_mfma_f32_16x16x32_bf16 v[112:115], v[212:215], v[172:175], v[112:115]
	v_mfma_f32_16x16x32_bf16 v[100:103], v[204:207], v[180:183], v[100:103]
	v_mfma_f32_16x16x32_bf16 v[96:99], v[212:215], v[180:183], v[96:99]
	v_mfma_f32_16x16x32_bf16 v[84:87], v[204:207], v[188:191], v[84:87]
	v_mfma_f32_16x16x32_bf16 v[80:83], v[212:215], v[188:191], v[80:83]
	v_mfma_f32_16x16x32_bf16 v[68:71], v[204:207], v[196:199], v[68:71]
	v_mfma_f32_16x16x32_bf16 v[64:67], v[212:215], v[196:199], v[64:67]
	s_mov_b32 m0, s46
	s_barrier
	ds_read_b128 v[168:171], v156 offset:49152
	ds_read_b128 v[172:175], v156 offset:50176
	ds_read_b128 v[176:179], v156 offset:51200
	ds_read_b128 v[180:183], v156 offset:52224
	ds_read_b128 v[184:187], v156 offset:53248
	ds_read_b128 v[188:191], v156 offset:54272
	ds_read_b128 v[192:195], v156 offset:55296
	ds_read_b128 v[196:199], v156 offset:56320
	global_load_lds_dwordx4 v134, s[100:101]
	s_mov_b32 m0, s47
	s_nop 0
	global_load_lds_dwordx4 v130, s[100:101]
	s_waitcnt lgkmcnt(0)
	s_barrier
; __device__ __forceinline__ float fast_rcp(float x) { return __builtin_amdgcn_rcpf(x); }
; __device__ __forceinline__ float fast_exp2(float x) { return __builtin_amdgcn_exp2f(x); }
; #define PG8_STAGE(bufoff, gbase, voff) do { _Pragma("unroll") for (int _i = 0; _i < 2; ++_i) \
;         __builtin_amdgcn_global_load_lds((const unsigned*)((const char*)(gbase) + (voff)[_i]), (LAS unsigned*)(lds + (bufoff) + ldsw + _i * 8192), 16, 0, 0); } while (0)
; #define PG8_MMA(ai, bj, At, Bt) do { __builtin_amdgcn_s_setprio(1); _Pragma("unroll") for (int m = 0; m < 4; ++m) _Pragma("unroll") for (int n = 0; n < 2; ++n) _Pragma("unroll") for (int k = 0; k < 2; ++k) \
;         acc[ai][bj][m][n] = __builtin_amdgcn_mfma_f32_16x16x32_bf16(Bt[n][k], At[m][k], acc[ai][bj][m][n], 0, 0, 0); __builtin_amdgcn_s_setprio(0); } while (0)
; #define PG8_WAIT_V(n) asm volatile("s_waitcnt vmcnt(" #n ")" ::: "memory")
; #define PG8_WAIT_L(n) asm volatile("s_waitcnt lgkmcnt(" #n ")" ::: "memory")
; #define PG8_BAR __builtin_amdgcn_s_barrier()
; #define PG8_SCHED __builtin_amdgcn_sched_barrier(0)
; template <class Epi>
; __device__ __forceinline__ void gemm_phase(LAS unsigned char* lds, const Gemm g, const StaticOrder& S, const Epi& E) {
;     ...
;             PG8_BAR; PG8_WAIT_L(0); PG8_MMA(1, 0, At, B0); PG8_BAR; PG8_SCHED;
;             PG8_STAGE(PG8_SB(1, 1), b3 + hstep, voffB);
;             PG8_WAIT_V(6); PG8_BAR; PG8_MMA(1, 1, At, B1); PG8_BAR;
;         }
;     __device__ __forceinline__ void operator()(const f32x4 (&acc)[2][2][4][2], const Unit& u, int wr, int wc, int fr, int fq) const {
;         const int row0 = u.pm * BM + wr * 64 + fr, col0 = u.pn * HALF + wc * 32 + 8 * fq;
; #pragma unroll
;         for (int ai = 0; ai < 2; ++ai)
; #pragma unroll
;             for (int m = 0; m < 4; ++m) { bf16_t* rowp = O + (size_t)(row0 + ai * HALF + m * 16) * DFF + col0;
;                 const float r = rs[row0 + ai * HALF + m * 16], r2 = r * r;
;                 f32x4 h0, h1;
; #pragma unroll
;                 for (int j = 0; j < 4; ++j) {
;                     const float g0 = acc[ai][0][m][0][j], g1 = acc[ai][0][m][1][j];
;                     h0[j] = g0 * r2 * fast_rcp(1.0f + fast_exp2(g0 * (-LOG2E * r))) * acc[ai][1][m][0][j];
;                     h1[j] = g1 * r2 * fast_rcp(1.0f + fast_exp2(g1 * (-LOG2E * r))) * acc[ai][1][m][1][j]; }
;                 *(u32x4*)rowp = pack8(h0, h1); }
	v_mfma_f32_16x16x32_bf16 v[60:63], v[144:147], v[168:171], v[60:63]
	v_mfma_f32_16x16x32_bf16 v[56:59], v[160:163], v[168:171], v[56:59]
	v_mfma_f32_16x16x32_bf16 v[44:47], v[144:147], v[176:179], v[44:47]
	v_mfma_f32_16x16x32_bf16 v[40:43], v[160:163], v[176:179], v[40:43]
	v_mfma_f32_16x16x32_bf16 v[28:31], v[144:147], v[184:187], v[28:31]
	v_mfma_f32_16x16x32_bf16 v[24:27], v[160:163], v[184:187], v[24:27]
	v_mfma_f32_16x16x32_bf16 v[12:15], v[144:147], v[192:195], v[12:15]
	v_mfma_f32_16x16x32_bf16 v[8:11], v[160:163], v[192:195], v[8:11]
	v_mfma_f32_16x16x32_bf16 v[60:63], v[148:151], v[172:175], v[60:63]
	v_mfma_f32_16x16x32_bf16 v[56:59], v[164:167], v[172:175], v[56:59]
	v_mfma_f32_16x16x32_bf16 v[44:47], v[148:151], v[180:183], v[44:47]
	v_mfma_f32_16x16x32_bf16 v[40:43], v[164:167], v[180:183], v[40:43]
	v_mfma_f32_16x16x32_bf16 v[28:31], v[148:151], v[188:191], v[28:31]
	v_mfma_f32_16x16x32_bf16 v[24:27], v[164:167], v[188:191], v[24:27]
	v_mfma_f32_16x16x32_bf16 v[12:15], v[148:151], v[196:199], v[12:15]
	v_mfma_f32_16x16x32_bf16 v[8:11], v[164:167], v[196:199], v[8:11]
	s_barrier
	s_add_u32 s42, s42, 0x80080
	s_addc_u32 s43, s43, 0
	s_add_i32 s44, s44, s23
	s_mov_b32 m0, s44
	s_nop 0
	global_load_lds_dwordx4 v132, s[42:43]
	s_add_i32 m0, s44, 0x2000
	s_nop 0
	global_load_lds_dwordx4 v128, s[42:43]
	s_waitcnt vmcnt(6)
	s_barrier
	v_mfma_f32_16x16x32_bf16 v[52:55], v[200:203], v[168:171], v[52:55]
	v_mfma_f32_16x16x32_bf16 v[48:51], v[208:211], v[168:171], v[48:51]
	v_mfma_f32_16x16x32_bf16 v[36:39], v[200:203], v[176:179], v[36:39]
	v_mfma_f32_16x16x32_bf16 v[32:35], v[208:211], v[176:179], v[32:35]
	v_mfma_f32_16x16x32_bf16 v[20:23], v[200:203], v[184:187], v[20:23]
	v_mfma_f32_16x16x32_bf16 v[16:19], v[208:211], v[184:187], v[16:19]
	v_mfma_f32_16x16x32_bf16 v[4:7], v[200:203], v[192:195], v[4:7]
	v_mfma_f32_16x16x32_bf16 v[0:3], v[208:211], v[192:195], v[0:3]
	v_mfma_f32_16x16x32_bf16 v[52:55], v[204:207], v[172:175], v[52:55]
	v_mfma_f32_16x16x32_bf16 v[48:51], v[212:215], v[172:175], v[48:51]
	v_mfma_f32_16x16x32_bf16 v[36:39], v[204:207], v[180:183], v[36:39]
	v_mfma_f32_16x16x32_bf16 v[32:35], v[212:215], v[180:183], v[32:35]
	v_mfma_f32_16x16x32_bf16 v[20:23], v[204:207], v[188:191], v[20:23]
	v_mfma_f32_16x16x32_bf16 v[16:19], v[212:215], v[188:191], v[16:19]
	v_mfma_f32_16x16x32_bf16 v[4:7], v[204:207], v[196:199], v[4:7]
	v_mfma_f32_16x16x32_bf16 v[0:3], v[212:215], v[196:199], v[0:3]
	s_add_i32 s58, s58, 2
	s_add_u32 s40, s40, 0x100
	s_addc_u32 s41, s41, 0
	s_add_u32 s56, s56, 0x100
	s_addc_u32 s57, s57, 0
	s_cmp_gt_u32 s58, 29
	s_barrier
	s_cbranch_scc0 .LBB0_796
	v_lshl_add_u32 v144, s38, 8, v152
	v_ashrrev_i32_e32 v145, 31, v144
	v_lshl_add_u64 v[150:151], v[144:145], 2, s[14:15]
	v_mov_b32_e32 v145, v224
	v_mov_b32_e32 v204, v225
	v_mov_b32_e32 v205, v226
	v_mov_b32_e32 v206, v227
	v_mov_b32_e32 v207, v228
	v_mov_b32_e32 v208, v229
	v_mov_b32_e32 v209, v230
	v_mov_b32_e32 v210, v231
	v_lshl_or_b32 v148, s53, 7, v154
	v_mov_b64_e32 v[146:147], s[20:21]
	v_ashrrev_i32_e32 v149, 31, v148
	v_mad_i64_i32 v[160:161], s[40:41], v144, s52, v[146:147]
	v_lshlrev_b64 v[148:149], 1, v[148:149]
	v_lshl_add_u64 v[160:161], v[160:161], 0, v[148:149]
	s_and_b64 vcc, exec, s[6:7]
	s_mov_b32 s53, s8
	s_mov_b32 s38, s30
	s_mov_b64 s[42:43], s[36:37]
	v_mul_f32_e32 v162, v145, v145
	v_mul_f32_e32 v145, 0xbfb8aa3b, v145
	v_mul_f32_e32 v163, v124, v162
	v_mul_f32_e32 v164, v120, v162
	v_mul_f32_e32 v120, v120, v145
	v_mul_f32_e32 v165, v125, v162
	v_mul_f32_e32 v125, v125, v145
	v_mul_f32_e32 v166, v121, v162
	v_mul_f32_e32 v121, v121, v145
	v_mul_f32_e32 v167, v126, v162
	v_mul_f32_e32 v126, v126, v145
	v_mul_f32_e32 v168, v122, v162
	v_mul_f32_e32 v122, v122, v145
	v_mul_f32_e32 v169, v127, v162
	v_mul_f32_e32 v127, v127, v145
	v_mul_f32_e32 v162, v123, v162
	v_mul_f32_e32 v123, v123, v145
	v_mul_f32_e32 v124, v124, v145
	v_exp_f32_e32 v120, v120
	v_exp_f32_e32 v125, v125
	v_exp_f32_e32 v121, v121
	v_exp_f32_e32 v126, v126
	v_exp_f32_e32 v122, v122
	v_exp_f32_e32 v127, v127
	v_exp_f32_e32 v123, v123
	v_exp_f32_e32 v124, v124
	v_add_f32_e32 v120, 1.0, v120
	v_add_f32_e32 v125, 1.0, v125
	v_add_f32_e32 v121, 1.0, v121
	v_add_f32_e32 v126, 1.0, v126
	v_add_f32_e32 v122, 1.0, v122
	v_add_f32_e32 v127, 1.0, v127
	v_add_f32_e32 v123, 1.0, v123
	v_add_f32_e32 v124, 1.0, v124
	v_rcp_f32_e32 v120, v120
	v_rcp_f32_e32 v125, v125
	v_rcp_f32_e32 v121, v121
	v_rcp_f32_e32 v126, v126
	v_rcp_f32_e32 v122, v122
	v_rcp_f32_e32 v127, v127
	v_rcp_f32_e32 v123, v123
	v_rcp_f32_e32 v124, v124
	v_mul_f32_e32 v120, v164, v120
	v_mul_f32_e32 v125, v165, v125
	v_mul_f32_e32 v121, v166, v121
	v_mul_f32_e32 v126, v167, v126
	v_mul_f32_e32 v122, v168, v122
	v_mul_f32_e32 v127, v169, v127
	v_mul_f32_e32 v123, v162, v123
	v_mul_f32_e32 v124, v163, v124
	v_mul_f32_e32 v120, v112, v120
	v_mul_f32_e32 v112, v117, v125
	v_mul_f32_e32 v117, v113, v121
	v_mul_f32_e32 v113, v118, v126
	v_mul_f32_e32 v118, v114, v122
	v_mul_f32_e32 v114, v119, v127
	v_mul_f32_e32 v115, v115, v123
	v_mul_f32_e32 v116, v116, v124
	v_cvt_pk_bf16_f32 v112, v116, v112
	v_cvt_pk_bf16_f32 v113, v113, v114
	v_cvt_pk_bf16_f32 v114, v120, v117
	v_cvt_pk_bf16_f32 v115, v118, v115
	global_store_dwordx4 v[160:161], v[112:115], off
	s_nop 1
	v_mov_b32_e32 v114, v204
	s_nop 0
	v_or_b32_e32 v112, 16, v144
	v_mad_i64_i32 v[112:113], s[40:41], v112, s52, v[146:147]
	v_lshl_add_u64 v[112:113], v[112:113], 0, v[148:149]
	v_mul_f32_e32 v115, v114, v114
	v_mul_f32_e32 v114, 0xbfb8aa3b, v114
	v_mul_f32_e32 v116, v108, v115
	v_mul_f32_e32 v117, v104, v115
	v_mul_f32_e32 v104, v104, v114
; __device__ __forceinline__ float fast_rcp(float x) { return __builtin_amdgcn_rcpf(x); }
; __device__ __forceinline__ float fast_exp2(float x) { return __builtin_amdgcn_exp2f(x); }
; __device__ __forceinline__ u32x4 pack8(f32x4 v0, f32x4 v1) { u32x4 w; w.x = cvt_pk_bf16(v0[0], v0[1]); w.y = cvt_pk_bf16(v0[2], v0[3]); w.z = cvt_pk_bf16(v1[0], v1[1]); w.w = cvt_pk_bf16(v1[2], v1[3]); return w; }
;     __device__ __forceinline__ void operator()(const f32x4 (&acc)[2][2][4][2], const Unit& u, int wr, int wc, int fr, int fq) const {
;         const int row0 = u.pm * BM + wr * 64 + fr, col0 = u.pn * HALF + wc * 32 + 8 * fq;
; #pragma unroll
;         for (int ai = 0; ai < 2; ++ai)
; #pragma unroll
;             for (int m = 0; m < 4; ++m) { bf16_t* rowp = O + (size_t)(row0 + ai * HALF + m * 16) * DFF + col0;
;                 const float r = rs[row0 + ai * HALF + m * 16], r2 = r * r;
;                 f32x4 h0, h1;
; #pragma unroll
;                 for (int j = 0; j < 4; ++j) {
;                     const float g0 = acc[ai][0][m][0][j], g1 = acc[ai][0][m][1][j];
;                     h0[j] = g0 * r2 * fast_rcp(1.0f + fast_exp2(g0 * (-LOG2E * r))) * acc[ai][1][m][0][j];
;                     h1[j] = g1 * r2 * fast_rcp(1.0f + fast_exp2(g1 * (-LOG2E * r))) * acc[ai][1][m][1][j]; }
;                 *(u32x4*)rowp = pack8(h0, h1); }
	v_mul_f32_e32 v118, v109, v115
	v_mul_f32_e32 v109, v109, v114
	v_mul_f32_e32 v119, v105, v115
	v_mul_f32_e32 v105, v105, v114
	v_mul_f32_e32 v120, v110, v115
	v_mul_f32_e32 v110, v110, v114
	v_mul_f32_e32 v121, v106, v115
	v_mul_f32_e32 v106, v106, v114
	v_mul_f32_e32 v122, v111, v115
	v_mul_f32_e32 v111, v111, v114
	v_mul_f32_e32 v115, v107, v115
	v_mul_f32_e32 v107, v107, v114
	v_mul_f32_e32 v108, v108, v114
	v_exp_f32_e32 v104, v104
	v_exp_f32_e32 v109, v109
	v_exp_f32_e32 v105, v105
	v_exp_f32_e32 v110, v110
	v_exp_f32_e32 v106, v106
	v_exp_f32_e32 v111, v111
	v_exp_f32_e32 v107, v107
	v_exp_f32_e32 v108, v108
	v_add_f32_e32 v104, 1.0, v104
	v_add_f32_e32 v109, 1.0, v109
	v_add_f32_e32 v105, 1.0, v105
	v_add_f32_e32 v110, 1.0, v110
	v_add_f32_e32 v106, 1.0, v106
	v_add_f32_e32 v111, 1.0, v111
	v_add_f32_e32 v107, 1.0, v107
	v_add_f32_e32 v108, 1.0, v108
	v_rcp_f32_e32 v104, v104
	v_rcp_f32_e32 v109, v109
	v_rcp_f32_e32 v105, v105
	v_rcp_f32_e32 v110, v110
	v_rcp_f32_e32 v106, v106
	v_rcp_f32_e32 v111, v111
	v_rcp_f32_e32 v107, v107
	v_rcp_f32_e32 v108, v108
	v_mul_f32_e32 v104, v117, v104
	v_mul_f32_e32 v109, v118, v109
	v_mul_f32_e32 v105, v119, v105
	v_mul_f32_e32 v110, v120, v110
	v_mul_f32_e32 v106, v121, v106
	v_mul_f32_e32 v111, v122, v111
	v_mul_f32_e32 v107, v115, v107
	v_mul_f32_e32 v108, v116, v108
	v_mul_f32_e32 v104, v96, v104
	v_mul_f32_e32 v96, v101, v109
	v_mul_f32_e32 v101, v97, v105
	v_mul_f32_e32 v97, v102, v110
	v_mul_f32_e32 v102, v98, v106
	v_mul_f32_e32 v98, v103, v111
	v_mul_f32_e32 v99, v99, v107
	v_mul_f32_e32 v100, v100, v108
	v_cvt_pk_bf16_f32 v96, v100, v96
	v_cvt_pk_bf16_f32 v97, v97, v98
	v_cvt_pk_bf16_f32 v98, v104, v101
	v_cvt_pk_bf16_f32 v99, v102, v99
	global_store_dwordx4 v[112:113], v[96:99], off
	s_nop 1
	v_mov_b32_e32 v98, v205
	s_nop 0
	v_or_b32_e32 v96, 32, v144
	v_mad_i64_i32 v[96:97], s[40:41], v96, s52, v[146:147]
	v_lshl_add_u64 v[96:97], v[96:97], 0, v[148:149]
	v_mul_f32_e32 v99, v98, v98
	v_mul_f32_e32 v98, 0xbfb8aa3b, v98
	v_mul_f32_e32 v100, v92, v99
	v_mul_f32_e32 v101, v88, v99
	v_mul_f32_e32 v88, v88, v98
	v_mul_f32_e32 v102, v93, v99
	v_mul_f32_e32 v93, v93, v98
	v_mul_f32_e32 v103, v89, v99
	v_mul_f32_e32 v89, v89, v98
	v_mul_f32_e32 v104, v94, v99
	v_mul_f32_e32 v94, v94, v98
	v_mul_f32_e32 v105, v90, v99
	v_mul_f32_e32 v90, v90, v98
	v_mul_f32_e32 v106, v95, v99
	v_mul_f32_e32 v95, v95, v98
	v_mul_f32_e32 v99, v91, v99
	v_mul_f32_e32 v91, v91, v98
	v_mul_f32_e32 v92, v92, v98
	v_exp_f32_e32 v88, v88
	v_exp_f32_e32 v93, v93
	v_exp_f32_e32 v89, v89
	v_exp_f32_e32 v94, v94
	v_exp_f32_e32 v90, v90
	v_exp_f32_e32 v95, v95
	v_exp_f32_e32 v91, v91
	v_exp_f32_e32 v92, v92
	v_add_f32_e32 v88, 1.0, v88
	v_add_f32_e32 v93, 1.0, v93
	v_add_f32_e32 v89, 1.0, v89
	v_add_f32_e32 v94, 1.0, v94
	v_add_f32_e32 v90, 1.0, v90
	v_add_f32_e32 v95, 1.0, v95
	v_add_f32_e32 v91, 1.0, v91
	v_add_f32_e32 v92, 1.0, v92
	v_rcp_f32_e32 v88, v88
	v_rcp_f32_e32 v93, v93
	v_rcp_f32_e32 v89, v89
	v_rcp_f32_e32 v94, v94
	v_rcp_f32_e32 v90, v90
	v_rcp_f32_e32 v95, v95
	v_rcp_f32_e32 v91, v91
	v_rcp_f32_e32 v92, v92
	v_mul_f32_e32 v88, v101, v88
	v_mul_f32_e32 v93, v102, v93
	v_mul_f32_e32 v89, v103, v89
	v_mul_f32_e32 v94, v104, v94
	v_mul_f32_e32 v90, v105, v90
	v_mul_f32_e32 v95, v106, v95
	v_mul_f32_e32 v91, v99, v91
	v_mul_f32_e32 v92, v100, v92
	v_mul_f32_e32 v88, v80, v88
	v_mul_f32_e32 v80, v85, v93
	v_mul_f32_e32 v85, v81, v89
	v_mul_f32_e32 v81, v86, v94
	v_mul_f32_e32 v86, v82, v90
	v_mul_f32_e32 v82, v87, v95
	v_mul_f32_e32 v83, v83, v91
	v_mul_f32_e32 v84, v84, v92
	v_cvt_pk_bf16_f32 v80, v84, v80
	v_cvt_pk_bf16_f32 v81, v81, v82
	v_cvt_pk_bf16_f32 v82, v88, v85
	v_cvt_pk_bf16_f32 v83, v86, v83
	global_store_dwordx4 v[96:97], v[80:83], off
	s_nop 1
	v_mov_b32_e32 v82, v206
	s_nop 0
	v_or_b32_e32 v80, 48, v144
	v_mad_i64_i32 v[80:81], s[40:41], v80, s52, v[146:147]
	v_lshl_add_u64 v[80:81], v[80:81], 0, v[148:149]
	v_mul_f32_e32 v83, v82, v82
	v_mul_f32_e32 v82, 0xbfb8aa3b, v82
	v_mul_f32_e32 v84, v76, v83
	v_mul_f32_e32 v85, v72, v83
	v_mul_f32_e32 v72, v72, v82
	v_mul_f32_e32 v86, v77, v83
	v_mul_f32_e32 v77, v77, v82
	v_mul_f32_e32 v87, v73, v83
	v_mul_f32_e32 v73, v73, v82
	v_mul_f32_e32 v88, v78, v83
	v_mul_f32_e32 v78, v78, v82
	v_mul_f32_e32 v89, v74, v83
	v_mul_f32_e32 v74, v74, v82
	v_mul_f32_e32 v90, v79, v83
	v_mul_f32_e32 v79, v79, v82
	v_mul_f32_e32 v83, v75, v83
	v_mul_f32_e32 v75, v75, v82
	v_mul_f32_e32 v76, v76, v82
	v_exp_f32_e32 v72, v72
	v_exp_f32_e32 v77, v77
	v_exp_f32_e32 v73, v73
	v_exp_f32_e32 v78, v78
	v_exp_f32_e32 v74, v74
	v_exp_f32_e32 v79, v79
	v_exp_f32_e32 v75, v75
	v_exp_f32_e32 v76, v76
	v_add_f32_e32 v72, 1.0, v72
	v_add_f32_e32 v77, 1.0, v77
	v_add_f32_e32 v73, 1.0, v73
	v_add_f32_e32 v78, 1.0, v78
	v_add_f32_e32 v74, 1.0, v74
	v_add_f32_e32 v79, 1.0, v79
	v_add_f32_e32 v75, 1.0, v75
	v_add_f32_e32 v76, 1.0, v76
	v_rcp_f32_e32 v72, v72
	v_rcp_f32_e32 v77, v77
	v_rcp_f32_e32 v73, v73
	v_rcp_f32_e32 v78, v78
	v_rcp_f32_e32 v74, v74
	v_rcp_f32_e32 v79, v79
	v_rcp_f32_e32 v75, v75
	v_rcp_f32_e32 v76, v76
	v_mul_f32_e32 v72, v85, v72
	v_mul_f32_e32 v77, v86, v77
	v_mul_f32_e32 v73, v87, v73
	v_mul_f32_e32 v78, v88, v78
	v_mul_f32_e32 v74, v89, v74
	v_mul_f32_e32 v79, v90, v79
	v_mul_f32_e32 v75, v83, v75
	v_mul_f32_e32 v76, v84, v76
	v_mul_f32_e32 v72, v64, v72
	v_mul_f32_e32 v64, v69, v77
	v_mul_f32_e32 v69, v65, v73
	v_mul_f32_e32 v65, v70, v78
	v_mul_f32_e32 v70, v66, v74
	v_mul_f32_e32 v66, v71, v79
	v_mul_f32_e32 v67, v67, v75
	v_mul_f32_e32 v68, v68, v76
	v_cvt_pk_bf16_f32 v64, v68, v64
	v_cvt_pk_bf16_f32 v65, v65, v66
	v_cvt_pk_bf16_f32 v66, v72, v69
; __device__ __forceinline__ float fast_rcp(float x) { return __builtin_amdgcn_rcpf(x); }
; __device__ __forceinline__ float fast_exp2(float x) { return __builtin_amdgcn_exp2f(x); }
; __device__ __forceinline__ u32x4 pack8(f32x4 v0, f32x4 v1) { u32x4 w; w.x = cvt_pk_bf16(v0[0], v0[1]); w.y = cvt_pk_bf16(v0[2], v0[3]); w.z = cvt_pk_bf16(v1[0], v1[1]); w.w = cvt_pk_bf16(v1[2], v1[3]); return w; }
;     __device__ __forceinline__ void operator()(const f32x4 (&acc)[2][2][4][2], const Unit& u, int wr, int wc, int fr, int fq) const {
;         const int row0 = u.pm * BM + wr * 64 + fr, col0 = u.pn * HALF + wc * 32 + 8 * fq;
; #pragma unroll
;         for (int ai = 0; ai < 2; ++ai)
; #pragma unroll
;             for (int m = 0; m < 4; ++m) { bf16_t* rowp = O + (size_t)(row0 + ai * HALF + m * 16) * DFF + col0;
;                 const float r = rs[row0 + ai * HALF + m * 16], r2 = r * r;
;                 f32x4 h0, h1;
; #pragma unroll
;                 for (int j = 0; j < 4; ++j) {
;                     const float g0 = acc[ai][0][m][0][j], g1 = acc[ai][0][m][1][j];
;                     h0[j] = g0 * r2 * fast_rcp(1.0f + fast_exp2(g0 * (-LOG2E * r))) * acc[ai][1][m][0][j];
;                     h1[j] = g1 * r2 * fast_rcp(1.0f + fast_exp2(g1 * (-LOG2E * r))) * acc[ai][1][m][1][j]; }
;                 *(u32x4*)rowp = pack8(h0, h1); }
	v_cvt_pk_bf16_f32 v67, v70, v67
	global_store_dwordx4 v[80:81], v[64:67], off
	s_nop 1
	v_mov_b32_e32 v66, v207
	s_nop 0
	v_add_u32_e32 v64, 0x80, v144
	v_mad_i64_i32 v[64:65], s[40:41], v64, s52, v[146:147]
	v_lshl_add_u64 v[64:65], v[64:65], 0, v[148:149]
	v_mul_f32_e32 v67, v66, v66
	v_mul_f32_e32 v66, 0xbfb8aa3b, v66
	v_mul_f32_e32 v68, v60, v67
	v_mul_f32_e32 v69, v56, v67
	v_mul_f32_e32 v56, v56, v66
	v_mul_f32_e32 v70, v61, v67
	v_mul_f32_e32 v61, v61, v66
	v_mul_f32_e32 v71, v57, v67
	v_mul_f32_e32 v57, v57, v66
	v_mul_f32_e32 v72, v62, v67
	v_mul_f32_e32 v62, v62, v66
	v_mul_f32_e32 v73, v58, v67
	v_mul_f32_e32 v58, v58, v66
	v_mul_f32_e32 v74, v63, v67
	v_mul_f32_e32 v63, v63, v66
	v_mul_f32_e32 v67, v59, v67
	v_mul_f32_e32 v59, v59, v66
	v_mul_f32_e32 v60, v60, v66
	v_exp_f32_e32 v56, v56
	v_exp_f32_e32 v61, v61
	v_exp_f32_e32 v57, v57
	v_exp_f32_e32 v62, v62
	v_exp_f32_e32 v58, v58
	v_exp_f32_e32 v63, v63
	v_exp_f32_e32 v59, v59
	v_exp_f32_e32 v60, v60
	v_add_f32_e32 v56, 1.0, v56
	v_add_f32_e32 v61, 1.0, v61
	v_add_f32_e32 v57, 1.0, v57
	v_add_f32_e32 v62, 1.0, v62
	v_add_f32_e32 v58, 1.0, v58
	v_add_f32_e32 v63, 1.0, v63
	v_add_f32_e32 v59, 1.0, v59
	v_add_f32_e32 v60, 1.0, v60
	v_rcp_f32_e32 v56, v56
	v_rcp_f32_e32 v61, v61
	v_rcp_f32_e32 v57, v57
	v_rcp_f32_e32 v62, v62
	v_rcp_f32_e32 v58, v58
	v_rcp_f32_e32 v63, v63
	v_rcp_f32_e32 v59, v59
	v_rcp_f32_e32 v60, v60
	v_mul_f32_e32 v56, v69, v56
	v_mul_f32_e32 v61, v70, v61
	v_mul_f32_e32 v57, v71, v57
	v_mul_f32_e32 v62, v72, v62
	v_mul_f32_e32 v58, v73, v58
	v_mul_f32_e32 v63, v74, v63
	v_mul_f32_e32 v59, v67, v59
	v_mul_f32_e32 v60, v68, v60
	v_mul_f32_e32 v56, v48, v56
	v_mul_f32_e32 v48, v53, v61
	v_mul_f32_e32 v53, v49, v57
	v_mul_f32_e32 v49, v54, v62
	v_mul_f32_e32 v54, v50, v58
	v_mul_f32_e32 v50, v55, v63
	v_mul_f32_e32 v51, v51, v59
	v_mul_f32_e32 v52, v52, v60
	v_cvt_pk_bf16_f32 v48, v52, v48
	v_cvt_pk_bf16_f32 v49, v49, v50
	v_cvt_pk_bf16_f32 v50, v56, v53
	v_cvt_pk_bf16_f32 v51, v54, v51
	global_store_dwordx4 v[64:65], v[48:51], off
	s_nop 1
	v_mov_b32_e32 v50, v208
	s_nop 0
	v_add_u32_e32 v48, 0x90, v144
	v_mad_i64_i32 v[48:49], s[40:41], v48, s52, v[146:147]
	v_lshl_add_u64 v[48:49], v[48:49], 0, v[148:149]
	v_mul_f32_e32 v51, v50, v50
	v_mul_f32_e32 v50, 0xbfb8aa3b, v50
	v_mul_f32_e32 v52, v44, v51
	v_mul_f32_e32 v53, v40, v51
	v_mul_f32_e32 v40, v40, v50
	v_mul_f32_e32 v54, v45, v51
	v_mul_f32_e32 v45, v45, v50
	v_mul_f32_e32 v55, v41, v51
	v_mul_f32_e32 v41, v41, v50
	v_mul_f32_e32 v56, v46, v51
	v_mul_f32_e32 v46, v46, v50
	v_mul_f32_e32 v57, v42, v51
	v_mul_f32_e32 v42, v42, v50
	v_mul_f32_e32 v58, v47, v51
	v_mul_f32_e32 v47, v47, v50
	v_mul_f32_e32 v51, v43, v51
	v_mul_f32_e32 v43, v43, v50
	v_mul_f32_e32 v44, v44, v50
	v_exp_f32_e32 v40, v40
	v_exp_f32_e32 v45, v45
	v_exp_f32_e32 v41, v41
	v_exp_f32_e32 v46, v46
	v_exp_f32_e32 v42, v42
	v_exp_f32_e32 v47, v47
	v_exp_f32_e32 v43, v43
	v_exp_f32_e32 v44, v44
	v_add_f32_e32 v40, 1.0, v40
	v_add_f32_e32 v45, 1.0, v45
	v_add_f32_e32 v41, 1.0, v41
	v_add_f32_e32 v46, 1.0, v46
	v_add_f32_e32 v42, 1.0, v42
	v_add_f32_e32 v47, 1.0, v47
	v_add_f32_e32 v43, 1.0, v43
	v_add_f32_e32 v44, 1.0, v44
	v_rcp_f32_e32 v40, v40
	v_rcp_f32_e32 v45, v45
	v_rcp_f32_e32 v41, v41
	v_rcp_f32_e32 v46, v46
	v_rcp_f32_e32 v42, v42
	v_rcp_f32_e32 v47, v47
	v_rcp_f32_e32 v43, v43
	v_rcp_f32_e32 v44, v44
	v_mul_f32_e32 v40, v53, v40
	v_mul_f32_e32 v45, v54, v45
	v_mul_f32_e32 v41, v55, v41
	v_mul_f32_e32 v46, v56, v46
	v_mul_f32_e32 v42, v57, v42
	v_mul_f32_e32 v47, v58, v47
	v_mul_f32_e32 v43, v51, v43
	v_mul_f32_e32 v44, v52, v44
	v_mul_f32_e32 v40, v32, v40
	v_mul_f32_e32 v32, v37, v45
	v_mul_f32_e32 v37, v33, v41
	v_mul_f32_e32 v33, v38, v46
	v_mul_f32_e32 v38, v34, v42
	v_mul_f32_e32 v34, v39, v47
	v_mul_f32_e32 v35, v35, v43
	v_mul_f32_e32 v36, v36, v44
	v_cvt_pk_bf16_f32 v32, v36, v32
	v_cvt_pk_bf16_f32 v33, v33, v34
	v_cvt_pk_bf16_f32 v34, v40, v37
	v_cvt_pk_bf16_f32 v35, v38, v35
	global_store_dwordx4 v[48:49], v[32:35], off
; __device__ __forceinline__ float fast_rcp(float x) { return __builtin_amdgcn_rcpf(x); }
; __device__ __forceinline__ float fast_exp2(float x) { return __builtin_amdgcn_exp2f(x); }
; __device__ __forceinline__ u32x4 pack8(f32x4 v0, f32x4 v1) { u32x4 w; w.x = cvt_pk_bf16(v0[0], v0[1]); w.y = cvt_pk_bf16(v0[2], v0[3]); w.z = cvt_pk_bf16(v1[0], v1[1]); w.w = cvt_pk_bf16(v1[2], v1[3]); return w; }
;     __device__ __forceinline__ void operator()(const f32x4 (&acc)[2][2][4][2], const Unit& u, int wr, int wc, int fr, int fq) const {
;         const int row0 = u.pm * BM + wr * 64 + fr, col0 = u.pn * HALF + wc * 32 + 8 * fq;
; #pragma unroll
;         for (int ai = 0; ai < 2; ++ai)
; #pragma unroll
;             for (int m = 0; m < 4; ++m) { bf16_t* rowp = O + (size_t)(row0 + ai * HALF + m * 16) * DFF + col0;
;                 const float r = rs[row0 + ai * HALF + m * 16], r2 = r * r;
;                 f32x4 h0, h1;
; #pragma unroll
;                 for (int j = 0; j < 4; ++j) {
;                     const float g0 = acc[ai][0][m][0][j], g1 = acc[ai][0][m][1][j];
;                     h0[j] = g0 * r2 * fast_rcp(1.0f + fast_exp2(g0 * (-LOG2E * r))) * acc[ai][1][m][0][j];
;                     h1[j] = g1 * r2 * fast_rcp(1.0f + fast_exp2(g1 * (-LOG2E * r))) * acc[ai][1][m][1][j]; }
;                 *(u32x4*)rowp = pack8(h0, h1); }
	s_nop 1
	v_mov_b32_e32 v34, v209
	s_nop 0
	v_add_u32_e32 v32, 0xa0, v144
	v_mad_i64_i32 v[32:33], s[40:41], v32, s52, v[146:147]
	v_lshl_add_u64 v[32:33], v[32:33], 0, v[148:149]
	s_mov_b64 s[40:41], s[34:35]
	v_mul_f32_e32 v35, v34, v34
	v_mul_f32_e32 v34, 0xbfb8aa3b, v34
	v_mul_f32_e32 v36, v28, v35
	v_mul_f32_e32 v37, v24, v35
	v_mul_f32_e32 v24, v24, v34
	v_mul_f32_e32 v38, v29, v35
	v_mul_f32_e32 v29, v29, v34
	v_mul_f32_e32 v39, v25, v35
	v_mul_f32_e32 v25, v25, v34
	v_mul_f32_e32 v40, v30, v35
	v_mul_f32_e32 v30, v30, v34
	v_mul_f32_e32 v41, v26, v35
	v_mul_f32_e32 v26, v26, v34
	v_mul_f32_e32 v42, v31, v35
	v_mul_f32_e32 v31, v31, v34
	v_mul_f32_e32 v35, v27, v35
	v_mul_f32_e32 v27, v27, v34
	v_mul_f32_e32 v28, v28, v34
	v_exp_f32_e32 v24, v24
	v_exp_f32_e32 v29, v29
	v_exp_f32_e32 v25, v25
	v_exp_f32_e32 v30, v30
	v_exp_f32_e32 v26, v26
	v_exp_f32_e32 v31, v31
	v_exp_f32_e32 v27, v27
	v_exp_f32_e32 v28, v28
	v_add_f32_e32 v24, 1.0, v24
	v_add_f32_e32 v29, 1.0, v29
	v_add_f32_e32 v25, 1.0, v25
	v_add_f32_e32 v30, 1.0, v30
	v_add_f32_e32 v26, 1.0, v26
	v_add_f32_e32 v31, 1.0, v31
	v_add_f32_e32 v27, 1.0, v27
	v_add_f32_e32 v28, 1.0, v28
	v_rcp_f32_e32 v24, v24
	v_rcp_f32_e32 v29, v29
	v_rcp_f32_e32 v25, v25
	v_rcp_f32_e32 v30, v30
	v_rcp_f32_e32 v26, v26
	v_rcp_f32_e32 v31, v31
	v_rcp_f32_e32 v27, v27
	v_rcp_f32_e32 v28, v28
	v_mul_f32_e32 v24, v37, v24
	v_mul_f32_e32 v29, v38, v29
	v_mul_f32_e32 v25, v39, v25
	v_mul_f32_e32 v30, v40, v30
	v_mul_f32_e32 v26, v41, v26
	v_mul_f32_e32 v31, v42, v31
	v_mul_f32_e32 v27, v35, v27
	v_mul_f32_e32 v28, v36, v28
	v_mul_f32_e32 v24, v16, v24
	v_mul_f32_e32 v16, v21, v29
	v_mul_f32_e32 v21, v17, v25
	v_mul_f32_e32 v17, v22, v30
	v_mul_f32_e32 v22, v18, v26
	v_mul_f32_e32 v18, v23, v31
	v_mul_f32_e32 v19, v19, v27
	v_mul_f32_e32 v20, v20, v28
	v_cvt_pk_bf16_f32 v16, v20, v16
	v_cvt_pk_bf16_f32 v17, v17, v18
	v_cvt_pk_bf16_f32 v18, v24, v21
	v_cvt_pk_bf16_f32 v19, v22, v19
	global_store_dwordx4 v[32:33], v[16:19], off
	s_nop 1
	v_mov_b32_e32 v18, v210
	s_nop 0
	v_add_u32_e32 v16, 0xb0, v144
	v_mad_i64_i32 v[16:17], s[6:7], v16, s52, v[146:147]
	v_lshl_add_u64 v[16:17], v[16:17], 0, v[148:149]
	v_mul_f32_e32 v19, v18, v18
	v_mul_f32_e32 v18, 0xbfb8aa3b, v18
	v_mul_f32_e32 v20, v12, v19
	v_mul_f32_e32 v21, v8, v19
	v_mul_f32_e32 v8, v8, v18
	v_mul_f32_e32 v22, v13, v19
	v_mul_f32_e32 v13, v13, v18
	v_mul_f32_e32 v23, v9, v19
	v_mul_f32_e32 v9, v9, v18
	v_mul_f32_e32 v24, v14, v19
	v_mul_f32_e32 v14, v14, v18
	v_mul_f32_e32 v25, v10, v19
	v_mul_f32_e32 v10, v10, v18
	v_mul_f32_e32 v26, v15, v19
	v_mul_f32_e32 v15, v15, v18
	v_mul_f32_e32 v19, v11, v19
	v_mul_f32_e32 v11, v11, v18
	v_mul_f32_e32 v12, v12, v18
	v_exp_f32_e32 v8, v8
	v_exp_f32_e32 v13, v13
	v_exp_f32_e32 v9, v9
	v_exp_f32_e32 v14, v14
	v_exp_f32_e32 v10, v10
	v_exp_f32_e32 v15, v15
	v_exp_f32_e32 v11, v11
	v_exp_f32_e32 v12, v12
	v_add_f32_e32 v8, 1.0, v8
	v_add_f32_e32 v13, 1.0, v13
	v_add_f32_e32 v9, 1.0, v9
	v_add_f32_e32 v14, 1.0, v14
	v_add_f32_e32 v10, 1.0, v10
	v_add_f32_e32 v15, 1.0, v15
	v_add_f32_e32 v11, 1.0, v11
	v_add_f32_e32 v12, 1.0, v12
	v_rcp_f32_e32 v8, v8
	v_rcp_f32_e32 v13, v13
	v_rcp_f32_e32 v9, v9
	v_rcp_f32_e32 v14, v14
	v_rcp_f32_e32 v10, v10
	v_rcp_f32_e32 v15, v15
	v_rcp_f32_e32 v11, v11
	v_rcp_f32_e32 v12, v12
	v_mul_f32_e32 v8, v21, v8
	v_mul_f32_e32 v13, v22, v13
	v_mul_f32_e32 v9, v23, v9
	v_mul_f32_e32 v14, v24, v14
	v_mul_f32_e32 v10, v25, v10
	v_mul_f32_e32 v15, v26, v15
	v_mul_f32_e32 v11, v19, v11
	v_mul_f32_e32 v12, v20, v12
	v_mul_f32_e32 v8, v0, v8
	v_mul_f32_e32 v0, v5, v13
	v_mul_f32_e32 v5, v1, v9
	v_mul_f32_e32 v1, v6, v14
	v_mul_f32_e32 v6, v2, v10
	v_mul_f32_e32 v2, v7, v15
	v_mul_f32_e32 v3, v3, v11
	v_mul_f32_e32 v4, v4, v12
	v_cvt_pk_bf16_f32 v0, v4, v0
	v_cvt_pk_bf16_f32 v1, v1, v2
	v_cvt_pk_bf16_f32 v2, v8, v5
	v_cvt_pk_bf16_f32 v3, v6, v3
	global_store_dwordx4 v[16:17], v[0:3], off
	s_cbranch_vccz .LBB0_793
	s_waitcnt vmcnt(0)
	s_cmpk_gt_u32 s10, 0xff
	s_cbranch_scc1 .LBB0_800
	s_barrier

; #define PG8_STAGE(bufoff, gbase, voff) do { _Pragma("unroll") for (int _i = 0; _i < 2; ++_i) \
;         __builtin_amdgcn_global_load_lds((const unsigned*)((const char*)(gbase) + (voff)[_i]), (LAS unsigned*)(lds + (bufoff) + ldsw + _i * 8192), 16, 0, 0); } while (0)
; #define PG8_LDA(dst, b, h) do { _Pragma("unroll") for (int m = 0; m < 4; ++m) _Pragma("unroll") for (int k = 0; k < 2; ++k) dst[m][k] = *(const LAS bf16x8*)(lds + PG8_SA(b, h) + aoff + m * 2048 + k * 1024); } while (0)
; #define PG8_LDB(dst, b, h) do { _Pragma("unroll") for (int n = 0; n < 2; ++n) _Pragma("unroll") for (int k = 0; k < 2; ++k) dst[n][k] = *(const LAS bf16x8*)(lds + PG8_SB(b, h) + boff + n * 2048 + k * 1024); } while (0)
; #define PG8_WAIT_V(n) asm volatile("s_waitcnt vmcnt(" #n ")" ::: "memory")
; #define PG8_WAIT_L(n) asm volatile("s_waitcnt lgkmcnt(" #n ")" ::: "memory")
; #define PG8_BAR __builtin_amdgcn_s_barrier()
; #define PG8_SCHED __builtin_amdgcn_sched_barrier(0)
; template <class Epi>
; __device__ __forceinline__ void gemm_phase(LAS unsigned char* lds, const Gemm g, const StaticOrder& S, const Epi& E) {
;     ...
;         for (int t = 0; t < nt; t += 2) {
;             const bool last = (t == nt - 2);
;             const char* a1 = cA + (size_t)(t + 1) * kstep;
;             const char* a2 = last ? nA : cA + (size_t)(t + 2) * kstep; const char* b2 = last ? nB : cB + (size_t)(t + 2) * kstep;
;             const char* a3 = a2 + kstep; const char* b3 = b2 + kstep;
;             PG8_LDB(B0, 0, 0); PG8_SCHED; PG8_LDA(At, 0, 0); PG8_STAGE(PG8_SA(1, 1), a1 + hstep, voffA);
;             PG8_WAIT_L(8); PG8_BAR; PG8_WAIT_L(0); PG8_MMA(0, 0, At, B0); PG8_BAR; PG8_SCHED;
;             PG8_LDB(B1, 0, 1); PG8_STAGE(PG8_SB(0, 0), b2, voffB);
;             PG8_BAR; PG8_WAIT_L(0); PG8_MMA(0, 1, At, B1); PG8_BAR;
;             PG8_LDA(At, 0, 1); PG8_STAGE(PG8_SA(0, 0), a2, voffA);
;             PG8_BAR; PG8_WAIT_L(0); PG8_MMA(1, 0, At, B0); PG8_BAR; PG8_SCHED;
;             PG8_STAGE(PG8_SB(0, 1), b2 + hstep, voffB);
;             PG8_WAIT_V(6); PG8_BAR; PG8_MMA(1, 1, At, B1); PG8_BAR;
;             PG8_LDB(B0, 1, 0); PG8_SCHED; PG8_LDA(At, 1, 0); PG8_STAGE(PG8_SA(0, 1), a2 + hstep, voffA);
;             PG8_WAIT_L(8); PG8_BAR; PG8_WAIT_L(0); PG8_MMA(0, 0, At, B0); PG8_BAR; PG8_SCHED;
.LBB0_864:
	ds_read_b128 v[148:151], v145
	ds_read_b128 v[152:155], v145 offset:1024
	ds_read_b128 v[160:163], v145 offset:2048
	ds_read_b128 v[164:167], v145 offset:3072
	s_add_u32 s44, s42, 0x100
	s_addc_u32 s45, s43, 0
	s_cmpk_eq_i32 s67, 0x54
	s_cselect_b32 s49, s41, s45
	s_cselect_b32 s48, s40, s44
	s_cselect_b32 s47, s7, s66
	s_cselect_b32 s46, s6, s65
	s_add_i32 m0, s28, 0xc000
	ds_read_b128 v[168:171], v146
	ds_read_b128 v[172:175], v146 offset:1024
	ds_read_b128 v[176:179], v146 offset:2048
	ds_read_b128 v[180:183], v146 offset:3072
	ds_read_b128 v[184:187], v146 offset:4096
	ds_read_b128 v[188:191], v146 offset:5120
	ds_read_b128 v[192:195], v146 offset:6144
	ds_read_b128 v[196:199], v146 offset:7168
	global_load_lds_dwordx4 v136, s[42:43]
	s_add_i32 m0, s28, 0xe000
	s_nop 0
	global_load_lds_dwordx4 v138, s[42:43]
	s_waitcnt lgkmcnt(8)
	s_barrier
	s_waitcnt lgkmcnt(0)
	v_mfma_f32_16x16x32_bf16 v[124:127], v[148:151], v[168:171], v[124:127]
	v_mfma_f32_16x16x32_bf16 v[120:123], v[160:163], v[168:171], v[120:123]
	v_mfma_f32_16x16x32_bf16 v[112:115], v[148:151], v[176:179], v[112:115]
	v_mfma_f32_16x16x32_bf16 v[104:107], v[160:163], v[176:179], v[104:107]
	v_mfma_f32_16x16x32_bf16 v[96:99], v[148:151], v[184:187], v[96:99]
	v_mfma_f32_16x16x32_bf16 v[88:91], v[160:163], v[184:187], v[88:91]
	v_mfma_f32_16x16x32_bf16 v[80:83], v[148:151], v[192:195], v[80:83]
	v_mfma_f32_16x16x32_bf16 v[72:75], v[160:163], v[192:195], v[72:75]
	v_mfma_f32_16x16x32_bf16 v[124:127], v[152:155], v[172:175], v[124:127]
	v_mfma_f32_16x16x32_bf16 v[120:123], v[164:167], v[172:175], v[120:123]
	v_mfma_f32_16x16x32_bf16 v[112:115], v[152:155], v[180:183], v[112:115]
	v_mfma_f32_16x16x32_bf16 v[104:107], v[164:167], v[180:183], v[104:107]
	v_mfma_f32_16x16x32_bf16 v[96:99], v[152:155], v[188:191], v[96:99]
	v_mfma_f32_16x16x32_bf16 v[88:91], v[164:167], v[188:191], v[88:91]
	v_mfma_f32_16x16x32_bf16 v[80:83], v[152:155], v[196:199], v[80:83]
	v_mfma_f32_16x16x32_bf16 v[72:75], v[164:167], v[196:199], v[72:75]
	s_barrier
	s_add_i32 s42, s55, s23
	s_add_u32 s98, s46, s2
	s_addc_u32 s99, s47, s3
	s_mov_b32 m0, s42
	ds_read_b128 v[200:203], v147
	ds_read_b128 v[204:207], v147 offset:1024
	ds_read_b128 v[208:211], v147 offset:2048
	ds_read_b128 v[212:215], v147 offset:3072
	global_load_lds_dwordx4 v132, s[46:47]
	s_add_i32 m0, s42, 0x2000
	s_nop 0
	global_load_lds_dwordx4 v128, s[46:47]
	s_waitcnt lgkmcnt(0)
	s_barrier
	v_mfma_f32_16x16x32_bf16 v[116:119], v[200:203], v[168:171], v[116:119]
	v_mfma_f32_16x16x32_bf16 v[108:111], v[208:211], v[168:171], v[108:111]
	v_mfma_f32_16x16x32_bf16 v[100:103], v[200:203], v[176:179], v[100:103]
	v_mfma_f32_16x16x32_bf16 v[92:95], v[208:211], v[176:179], v[92:95]
	v_mfma_f32_16x16x32_bf16 v[84:87], v[200:203], v[184:187], v[84:87]
	v_mfma_f32_16x16x32_bf16 v[76:79], v[208:211], v[184:187], v[76:79]
	v_mfma_f32_16x16x32_bf16 v[68:71], v[200:203], v[192:195], v[68:71]
	v_mfma_f32_16x16x32_bf16 v[64:67], v[208:211], v[192:195], v[64:67]
	v_mfma_f32_16x16x32_bf16 v[116:119], v[204:207], v[172:175], v[116:119]
	v_mfma_f32_16x16x32_bf16 v[108:111], v[212:215], v[172:175], v[108:111]
	v_mfma_f32_16x16x32_bf16 v[100:103], v[204:207], v[180:183], v[100:103]
	v_mfma_f32_16x16x32_bf16 v[92:95], v[212:215], v[180:183], v[92:95]
	v_mfma_f32_16x16x32_bf16 v[84:87], v[204:207], v[188:191], v[84:87]
	v_mfma_f32_16x16x32_bf16 v[76:79], v[212:215], v[188:191], v[76:79]
	v_mfma_f32_16x16x32_bf16 v[68:71], v[204:207], v[196:199], v[68:71]
	v_mfma_f32_16x16x32_bf16 v[64:67], v[212:215], v[196:199], v[64:67]
	s_mov_b32 m0, s28
	s_add_u32 s100, s48, s2
	s_addc_u32 s101, s49, s3
	s_barrier
	ds_read_b128 v[168:171], v146 offset:16384
	ds_read_b128 v[172:175], v146 offset:17408
	ds_read_b128 v[176:179], v146 offset:18432
	ds_read_b128 v[180:183], v146 offset:19456
	ds_read_b128 v[184:187], v146 offset:20480
	ds_read_b128 v[188:191], v146 offset:21504
	ds_read_b128 v[192:195], v146 offset:22528
	ds_read_b128 v[196:199], v146 offset:23552
	global_load_lds_dwordx4 v134, s[48:49]
	s_mov_b32 m0, s29
	s_nop 0
	global_load_lds_dwordx4 v130, s[48:49]
	s_waitcnt lgkmcnt(0)
	s_barrier
	v_mfma_f32_16x16x32_bf16 v[60:63], v[148:151], v[168:171], v[60:63]
	v_mfma_f32_16x16x32_bf16 v[56:59], v[160:163], v[168:171], v[56:59]
	v_mfma_f32_16x16x32_bf16 v[52:55], v[148:151], v[176:179], v[52:55]
	v_mfma_f32_16x16x32_bf16 v[44:47], v[160:163], v[176:179], v[44:47]
	v_mfma_f32_16x16x32_bf16 v[36:39], v[148:151], v[184:187], v[36:39]
	v_mfma_f32_16x16x32_bf16 v[28:31], v[160:163], v[184:187], v[28:31]
	v_mfma_f32_16x16x32_bf16 v[20:23], v[148:151], v[192:195], v[20:23]
	v_mfma_f32_16x16x32_bf16 v[12:15], v[160:163], v[192:195], v[12:15]
	v_mfma_f32_16x16x32_bf16 v[60:63], v[152:155], v[172:175], v[60:63]
	v_mfma_f32_16x16x32_bf16 v[56:59], v[164:167], v[172:175], v[56:59]
	v_mfma_f32_16x16x32_bf16 v[52:55], v[152:155], v[180:183], v[52:55]
	v_mfma_f32_16x16x32_bf16 v[44:47], v[164:167], v[180:183], v[44:47]
	v_mfma_f32_16x16x32_bf16 v[36:39], v[152:155], v[188:191], v[36:39]
	v_mfma_f32_16x16x32_bf16 v[28:31], v[164:167], v[188:191], v[28:31]
	v_mfma_f32_16x16x32_bf16 v[20:23], v[152:155], v[196:199], v[20:23]
	v_mfma_f32_16x16x32_bf16 v[12:15], v[164:167], v[196:199], v[12:15]
	s_barrier
	s_add_u32 s42, s46, 0x160000
	s_addc_u32 s43, s47, 0
	s_add_i32 s68, s56, s23
	s_mov_b32 m0, s68
	s_nop 0
	global_load_lds_dwordx4 v132, s[42:43]
	s_add_i32 m0, s68, 0x2000
	s_nop 0
	global_load_lds_dwordx4 v128, s[42:43]
	s_waitcnt vmcnt(6)
	s_barrier
; #define PG8_STAGE(bufoff, gbase, voff) do { _Pragma("unroll") for (int _i = 0; _i < 2; ++_i) \
;         __builtin_amdgcn_global_load_lds((const unsigned*)((const char*)(gbase) + (voff)[_i]), (LAS unsigned*)(lds + (bufoff) + ldsw + _i * 8192), 16, 0, 0); } while (0)
; #define PG8_LDA(dst, b, h) do { _Pragma("unroll") for (int m = 0; m < 4; ++m) _Pragma("unroll") for (int k = 0; k < 2; ++k) dst[m][k] = *(const LAS bf16x8*)(lds + PG8_SA(b, h) + aoff + m * 2048 + k * 1024); } while (0)
; #define PG8_LDB(dst, b, h) do { _Pragma("unroll") for (int n = 0; n < 2; ++n) _Pragma("unroll") for (int k = 0; k < 2; ++k) dst[n][k] = *(const LAS bf16x8*)(lds + PG8_SB(b, h) + boff + n * 2048 + k * 1024); } while (0)
; #define PG8_MMA(ai, bj, At, Bt) do { __builtin_amdgcn_s_setprio(1); _Pragma("unroll") for (int m = 0; m < 4; ++m) _Pragma("unroll") for (int n = 0; n < 2; ++n) _Pragma("unroll") for (int k = 0; k < 2; ++k) \
;         acc[ai][bj][m][n] = __builtin_amdgcn_mfma_f32_16x16x32_bf16(Bt[n][k], At[m][k], acc[ai][bj][m][n], 0, 0, 0); __builtin_amdgcn_s_setprio(0); } while (0)
; #define PG8_WAIT_V(n) asm volatile("s_waitcnt vmcnt(" #n ")" ::: "memory")
; #define PG8_WAIT_L(n) asm volatile("s_waitcnt lgkmcnt(" #n ")" ::: "memory")
; #define PG8_BAR __builtin_amdgcn_s_barrier()
; #define PG8_SCHED __builtin_amdgcn_sched_barrier(0)
; template <class Epi>
; __device__ __forceinline__ void gemm_phase(LAS unsigned char* lds, const Gemm g, const StaticOrder& S, const Epi& E) {
;     ...
;             PG8_WAIT_V(6); PG8_BAR; PG8_MMA(1, 1, At, B1); PG8_BAR;
;             PG8_LDB(B0, 1, 0); PG8_SCHED; PG8_LDA(At, 1, 0); PG8_STAGE(PG8_SA(0, 1), a2 + hstep, voffA);
;             PG8_WAIT_L(8); PG8_BAR; PG8_WAIT_L(0); PG8_MMA(0, 0, At, B0); PG8_BAR; PG8_SCHED;
;             PG8_LDB(B1, 1, 1); PG8_STAGE(PG8_SB(1, 0), b3, voffB);
;             PG8_BAR; PG8_WAIT_L(0); PG8_MMA(0, 1, At, B1); PG8_BAR;
;             PG8_LDA(At, 1, 1); PG8_STAGE(PG8_SA(1, 0), a3, voffA);
;             PG8_BAR; PG8_WAIT_L(0); PG8_MMA(1, 0, At, B0); PG8_BAR; PG8_SCHED;
;             PG8_STAGE(PG8_SB(1, 1), b3 + hstep, voffB);
;             PG8_WAIT_V(6); PG8_BAR; PG8_MMA(1, 1, At, B1); PG8_BAR;
	v_mfma_f32_16x16x32_bf16 v[48:51], v[200:203], v[168:171], v[48:51]
	v_mfma_f32_16x16x32_bf16 v[40:43], v[208:211], v[168:171], v[40:43]
	v_mfma_f32_16x16x32_bf16 v[32:35], v[200:203], v[176:179], v[32:35]
	v_mfma_f32_16x16x32_bf16 v[24:27], v[208:211], v[176:179], v[24:27]
	v_mfma_f32_16x16x32_bf16 v[16:19], v[200:203], v[184:187], v[16:19]
	v_mfma_f32_16x16x32_bf16 v[8:11], v[208:211], v[184:187], v[8:11]
	v_mfma_f32_16x16x32_bf16 v[4:7], v[200:203], v[192:195], v[4:7]
	v_mfma_f32_16x16x32_bf16 v[0:3], v[208:211], v[192:195], v[0:3]
	v_mfma_f32_16x16x32_bf16 v[48:51], v[204:207], v[172:175], v[48:51]
	v_mfma_f32_16x16x32_bf16 v[40:43], v[212:215], v[172:175], v[40:43]
	v_mfma_f32_16x16x32_bf16 v[32:35], v[204:207], v[180:183], v[32:35]
	v_mfma_f32_16x16x32_bf16 v[24:27], v[212:215], v[180:183], v[24:27]
	v_mfma_f32_16x16x32_bf16 v[16:19], v[204:207], v[188:191], v[16:19]
	v_mfma_f32_16x16x32_bf16 v[8:11], v[212:215], v[188:191], v[8:11]
	v_mfma_f32_16x16x32_bf16 v[4:7], v[204:207], v[196:199], v[4:7]
	v_mfma_f32_16x16x32_bf16 v[0:3], v[212:215], v[196:199], v[0:3]
	s_add_i32 s68, 0, 0x18000
	v_add_u32_e32 v164, s68, v143
	s_barrier
	ds_read_b128 v[148:151], v164
	ds_read_b128 v[152:155], v164 offset:1024
	ds_read_b128 v[160:163], v164 offset:2048
	ds_read_b128 v[164:167], v164 offset:3072
	s_add_u32 s42, s48, 0x160000
	s_addc_u32 s43, s49, 0
	s_mov_b32 m0, s33
	ds_read_b128 v[168:171], v146 offset:32768
	ds_read_b128 v[172:175], v146 offset:33792
	ds_read_b128 v[176:179], v146 offset:34816
	ds_read_b128 v[180:183], v146 offset:35840
	ds_read_b128 v[184:187], v146 offset:36864
	ds_read_b128 v[188:191], v146 offset:37888
	ds_read_b128 v[192:195], v146 offset:38912
	ds_read_b128 v[196:199], v146 offset:39936
	global_load_lds_dwordx4 v134, s[42:43]
	s_mov_b32 m0, s50
	s_nop 0
	global_load_lds_dwordx4 v130, s[42:43]
	s_waitcnt lgkmcnt(8)
	s_barrier
	s_waitcnt lgkmcnt(0)
	v_mfma_f32_16x16x32_bf16 v[124:127], v[148:151], v[168:171], v[124:127]
	v_mfma_f32_16x16x32_bf16 v[120:123], v[160:163], v[168:171], v[120:123]
	v_mfma_f32_16x16x32_bf16 v[112:115], v[148:151], v[176:179], v[112:115]
	v_mfma_f32_16x16x32_bf16 v[104:107], v[160:163], v[176:179], v[104:107]
	v_mfma_f32_16x16x32_bf16 v[96:99], v[148:151], v[184:187], v[96:99]
	v_mfma_f32_16x16x32_bf16 v[88:91], v[160:163], v[184:187], v[88:91]
	v_mfma_f32_16x16x32_bf16 v[80:83], v[148:151], v[192:195], v[80:83]
	v_mfma_f32_16x16x32_bf16 v[72:75], v[160:163], v[192:195], v[72:75]
	v_mfma_f32_16x16x32_bf16 v[124:127], v[152:155], v[172:175], v[124:127]
	v_mfma_f32_16x16x32_bf16 v[120:123], v[164:167], v[172:175], v[120:123]
	v_mfma_f32_16x16x32_bf16 v[112:115], v[152:155], v[180:183], v[112:115]
	v_mfma_f32_16x16x32_bf16 v[104:107], v[164:167], v[180:183], v[104:107]
	v_mfma_f32_16x16x32_bf16 v[96:99], v[152:155], v[188:191], v[96:99]
	v_mfma_f32_16x16x32_bf16 v[88:91], v[164:167], v[188:191], v[88:91]
	v_mfma_f32_16x16x32_bf16 v[80:83], v[152:155], v[196:199], v[80:83]
	v_mfma_f32_16x16x32_bf16 v[72:75], v[164:167], v[196:199], v[72:75]
	s_barrier
	s_add_i32 s48, 0, 0x1c000
	s_add_i32 s42, s68, s23
	v_add_u32_e32 v212, s48, v143
	s_mov_b32 m0, s42
	ds_read_b128 v[200:203], v212
	ds_read_b128 v[204:207], v212 offset:1024
	ds_read_b128 v[208:211], v212 offset:2048
	ds_read_b128 v[212:215], v212 offset:3072
	global_load_lds_dwordx4 v132, s[98:99]
	s_add_i32 m0, s42, 0x2000
	s_nop 0
	global_load_lds_dwordx4 v128, s[98:99]
	s_waitcnt lgkmcnt(0)
	s_barrier
	v_mfma_f32_16x16x32_bf16 v[116:119], v[200:203], v[168:171], v[116:119]
	v_mfma_f32_16x16x32_bf16 v[108:111], v[208:211], v[168:171], v[108:111]
	v_mfma_f32_16x16x32_bf16 v[100:103], v[200:203], v[176:179], v[100:103]
	v_mfma_f32_16x16x32_bf16 v[92:95], v[208:211], v[176:179], v[92:95]
	v_mfma_f32_16x16x32_bf16 v[84:87], v[200:203], v[184:187], v[84:87]
	v_mfma_f32_16x16x32_bf16 v[76:79], v[208:211], v[184:187], v[76:79]
	v_mfma_f32_16x16x32_bf16 v[68:71], v[200:203], v[192:195], v[68:71]
	v_mfma_f32_16x16x32_bf16 v[64:67], v[208:211], v[192:195], v[64:67]
	v_mfma_f32_16x16x32_bf16 v[116:119], v[204:207], v[172:175], v[116:119]
	v_mfma_f32_16x16x32_bf16 v[108:111], v[212:215], v[172:175], v[108:111]
	v_mfma_f32_16x16x32_bf16 v[100:103], v[204:207], v[180:183], v[100:103]
	v_mfma_f32_16x16x32_bf16 v[92:95], v[212:215], v[180:183], v[92:95]
	v_mfma_f32_16x16x32_bf16 v[84:87], v[204:207], v[188:191], v[84:87]
	v_mfma_f32_16x16x32_bf16 v[76:79], v[212:215], v[188:191], v[76:79]
	v_mfma_f32_16x16x32_bf16 v[68:71], v[204:207], v[196:199], v[68:71]
	v_mfma_f32_16x16x32_bf16 v[64:67], v[212:215], v[196:199], v[64:67]
	s_mov_b32 m0, s52
	s_barrier
	ds_read_b128 v[168:171], v146 offset:49152
	ds_read_b128 v[172:175], v146 offset:50176
	ds_read_b128 v[176:179], v146 offset:51200
	ds_read_b128 v[180:183], v146 offset:52224
	ds_read_b128 v[184:187], v146 offset:53248
	ds_read_b128 v[188:191], v146 offset:54272
	ds_read_b128 v[192:195], v146 offset:55296
	ds_read_b128 v[196:199], v146 offset:56320
	global_load_lds_dwordx4 v134, s[100:101]
	s_mov_b32 m0, s53
	s_nop 0
	global_load_lds_dwordx4 v130, s[100:101]
	s_waitcnt lgkmcnt(0)
	s_barrier
; #define PG8_STAGE(bufoff, gbase, voff) do { _Pragma("unroll") for (int _i = 0; _i < 2; ++_i) \
;         __builtin_amdgcn_global_load_lds((const unsigned*)((const char*)(gbase) + (voff)[_i]), (LAS unsigned*)(lds + (bufoff) + ldsw + _i * 8192), 16, 0, 0); } while (0)
; #define PG8_MMA(ai, bj, At, Bt) do { __builtin_amdgcn_s_setprio(1); _Pragma("unroll") for (int m = 0; m < 4; ++m) _Pragma("unroll") for (int n = 0; n < 2; ++n) _Pragma("unroll") for (int k = 0; k < 2; ++k) \
;         acc[ai][bj][m][n] = __builtin_amdgcn_mfma_f32_16x16x32_bf16(Bt[n][k], At[m][k], acc[ai][bj][m][n], 0, 0, 0); __builtin_amdgcn_s_setprio(0); } while (0)
; #define PG8_WAIT_V(n) asm volatile("s_waitcnt vmcnt(" #n ")" ::: "memory")
; #define PG8_WAIT_L(n) asm volatile("s_waitcnt lgkmcnt(" #n ")" ::: "memory")
; #define PG8_BAR __builtin_amdgcn_s_barrier()
; #define PG8_SCHED __builtin_amdgcn_sched_barrier(0)
; template <class Epi>
; __device__ __forceinline__ void gemm_phase(LAS unsigned char* lds, const Gemm g, const StaticOrder& S, const Epi& E) {
;     ...
;             PG8_BAR; PG8_WAIT_L(0); PG8_MMA(1, 0, At, B0); PG8_BAR; PG8_SCHED;
;             PG8_STAGE(PG8_SB(1, 1), b3 + hstep, voffB);
;             PG8_WAIT_V(6); PG8_BAR; PG8_MMA(1, 1, At, B1); PG8_BAR;
;         }
	v_mfma_f32_16x16x32_bf16 v[60:63], v[148:151], v[168:171], v[60:63]
	v_mfma_f32_16x16x32_bf16 v[56:59], v[160:163], v[168:171], v[56:59]
	v_mfma_f32_16x16x32_bf16 v[52:55], v[148:151], v[176:179], v[52:55]
	v_mfma_f32_16x16x32_bf16 v[44:47], v[160:163], v[176:179], v[44:47]
	v_mfma_f32_16x16x32_bf16 v[36:39], v[148:151], v[184:187], v[36:39]
	v_mfma_f32_16x16x32_bf16 v[28:31], v[160:163], v[184:187], v[28:31]
	v_mfma_f32_16x16x32_bf16 v[20:23], v[148:151], v[192:195], v[20:23]
	v_mfma_f32_16x16x32_bf16 v[12:15], v[160:163], v[192:195], v[12:15]
	v_mfma_f32_16x16x32_bf16 v[60:63], v[152:155], v[172:175], v[60:63]
	v_mfma_f32_16x16x32_bf16 v[56:59], v[164:167], v[172:175], v[56:59]
	v_mfma_f32_16x16x32_bf16 v[52:55], v[152:155], v[180:183], v[52:55]
	v_mfma_f32_16x16x32_bf16 v[44:47], v[164:167], v[180:183], v[44:47]
	v_mfma_f32_16x16x32_bf16 v[36:39], v[152:155], v[188:191], v[36:39]
	v_mfma_f32_16x16x32_bf16 v[28:31], v[164:167], v[188:191], v[28:31]
	v_mfma_f32_16x16x32_bf16 v[20:23], v[152:155], v[196:199], v[20:23]
	v_mfma_f32_16x16x32_bf16 v[12:15], v[164:167], v[196:199], v[12:15]
	s_barrier
	s_add_u32 s42, s46, 0x160080
	s_addc_u32 s43, s47, 0
	s_add_i32 s46, s48, s23
	s_mov_b32 m0, s46
	s_nop 0
	global_load_lds_dwordx4 v132, s[42:43]
	s_add_i32 m0, s46, 0x2000
	s_nop 0
	global_load_lds_dwordx4 v128, s[42:43]
	s_waitcnt vmcnt(6)
	s_barrier
	v_mfma_f32_16x16x32_bf16 v[48:51], v[200:203], v[168:171], v[48:51]
	v_mfma_f32_16x16x32_bf16 v[40:43], v[208:211], v[168:171], v[40:43]
	v_mfma_f32_16x16x32_bf16 v[32:35], v[200:203], v[176:179], v[32:35]
	v_mfma_f32_16x16x32_bf16 v[24:27], v[208:211], v[176:179], v[24:27]
	v_mfma_f32_16x16x32_bf16 v[16:19], v[200:203], v[184:187], v[16:19]
	v_mfma_f32_16x16x32_bf16 v[8:11], v[208:211], v[184:187], v[8:11]
	v_mfma_f32_16x16x32_bf16 v[4:7], v[200:203], v[192:195], v[4:7]
	v_mfma_f32_16x16x32_bf16 v[0:3], v[208:211], v[192:195], v[0:3]
	v_mfma_f32_16x16x32_bf16 v[48:51], v[204:207], v[172:175], v[48:51]
	v_mfma_f32_16x16x32_bf16 v[40:43], v[212:215], v[172:175], v[40:43]
	v_mfma_f32_16x16x32_bf16 v[32:35], v[204:207], v[180:183], v[32:35]
	v_mfma_f32_16x16x32_bf16 v[24:27], v[212:215], v[180:183], v[24:27]
	v_mfma_f32_16x16x32_bf16 v[16:19], v[204:207], v[188:191], v[16:19]
	v_mfma_f32_16x16x32_bf16 v[8:11], v[212:215], v[188:191], v[8:11]
	v_mfma_f32_16x16x32_bf16 v[4:7], v[204:207], v[196:199], v[4:7]
	v_mfma_f32_16x16x32_bf16 v[0:3], v[212:215], v[196:199], v[0:3]
	s_add_i32 s67, s67, 2
	s_add_u32 s65, s65, 0x100
	s_addc_u32 s66, s66, 0
	s_cmpk_gt_u32 s67, 0x55
	s_mov_b64 s[42:43], s[44:45]
	s_barrier
	s_cbranch_scc0 .LBB0_864
; #define PG8_WAIT_V(n) asm volatile("s_waitcnt vmcnt(" #n ")" ::: "memory")
; #define PG8_BAR __builtin_amdgcn_s_barrier()
; __device__ __forceinline__ u32x4 pack8(f32x4 v0, f32x4 v1) { u32x4 w; w.x = cvt_pk_bf16(v0[0], v0[1]); w.y = cvt_pk_bf16(v0[2], v0[3]); w.z = cvt_pk_bf16(v1[0], v1[1]); w.w = cvt_pk_bf16(v1[2], v1[3]); return w; }
; template <class Epi>
; __device__ __forceinline__ void gemm_phase(LAS unsigned char* lds, const Gemm g, const StaticOrder& S, const Epi& E) {
;     ...
;         cur = nxt; cA = nA; cB = nB; ++ui;
;     }
;     PG8_WAIT_V(0);
;     if (wr == 0) PG8_BAR;
;     PG8_BAR;
;     __device__ __forceinline__ void operator()(const f32x4 (&acc)[2][2][4][2], const Unit& u, int wr, int wc, int fr, int fq) const {
;         const int row0 = u.pm * BM + wr * 64 + fr, col0 = u.pn * BM + wc * 32 + 8 * fq;
; #pragma unroll
;         for (int ai = 0; ai < 2; ++ai)
; #pragma unroll
;             for (int m = 0; m < 4; ++m) { bf16_t* rowp = O + (size_t)(row0 + ai * HALF + m * 16) * ldc + col0;
; #pragma unroll
;                 for (int bj = 0; bj < 2; ++bj) *(u32x4*)(rowp + bj * HALF) = pack8(acc[ai][bj][m][0], acc[ai][bj][m][1]); }
	v_lshl_add_u32 v148, s63, 8, v142
	v_lshl_or_b32 v140, s64, 8, v144
	v_ashrrev_i32_e32 v149, 31, v148
	v_ashrrev_i32_e32 v141, 31, v140
	v_lshlrev_b64 v[150:151], 12, v[148:149]
	v_lshl_add_u64 v[150:151], s[24:25], 0, v[150:151]
	v_lshlrev_b64 v[152:153], 1, v[140:141]
	v_lshl_add_u64 v[140:141], v[150:151], 0, v[152:153]
	v_cvt_pk_bf16_f32 v124, v124, v125
	v_cvt_pk_bf16_f32 v125, v126, v127
	v_cvt_pk_bf16_f32 v126, v120, v121
	v_cvt_pk_bf16_f32 v127, v122, v123
	global_store_dwordx4 v[140:141], v[124:127], off
	v_cvt_pk_bf16_f32 v116, v116, v117
	v_cvt_pk_bf16_f32 v117, v118, v119
	v_cvt_pk_bf16_f32 v118, v108, v109
	v_or_b32_e32 v108, 16, v148
	v_ashrrev_i32_e32 v109, 31, v108
	v_lshlrev_b64 v[108:109], 12, v[108:109]
	v_lshl_add_u64 v[108:109], s[24:25], 0, v[108:109]
	v_cvt_pk_bf16_f32 v119, v110, v111
	global_store_dwordx4 v[140:141], v[116:119], off offset:256
	s_mov_b32 s64, s61
	s_mov_b32 s63, s62
	v_lshl_add_u64 v[116:117], v[108:109], 0, v[152:153]
	v_cvt_pk_bf16_f32 v108, v112, v113
	v_cvt_pk_bf16_f32 v109, v114, v115
	v_cvt_pk_bf16_f32 v110, v104, v105
	v_cvt_pk_bf16_f32 v111, v106, v107
	global_store_dwordx4 v[116:117], v[108:111], off
	v_cvt_pk_bf16_f32 v100, v100, v101
	v_cvt_pk_bf16_f32 v101, v102, v103
	v_cvt_pk_bf16_f32 v102, v92, v93
	v_or_b32_e32 v92, 32, v148
	v_ashrrev_i32_e32 v93, 31, v92
	v_lshlrev_b64 v[92:93], 12, v[92:93]
	v_lshl_add_u64 v[92:93], s[24:25], 0, v[92:93]
	v_cvt_pk_bf16_f32 v103, v94, v95
	global_store_dwordx4 v[116:117], v[100:103], off offset:256
	s_mov_b64 s[44:45], s[6:7]
	s_mov_b64 s[42:43], s[40:41]
	v_lshl_add_u64 v[100:101], v[92:93], 0, v[152:153]
	v_cvt_pk_bf16_f32 v92, v96, v97
	v_cvt_pk_bf16_f32 v93, v98, v99
	v_cvt_pk_bf16_f32 v94, v88, v89
	v_cvt_pk_bf16_f32 v95, v90, v91
	global_store_dwordx4 v[100:101], v[92:95], off
	v_cvt_pk_bf16_f32 v84, v84, v85
	v_cvt_pk_bf16_f32 v85, v86, v87
	v_cvt_pk_bf16_f32 v86, v76, v77
	v_or_b32_e32 v76, 48, v148
	v_ashrrev_i32_e32 v77, 31, v76
	v_lshlrev_b64 v[76:77], 12, v[76:77]
	v_lshl_add_u64 v[76:77], s[24:25], 0, v[76:77]
	v_cvt_pk_bf16_f32 v87, v78, v79
	global_store_dwordx4 v[100:101], v[84:87], off offset:256
	s_nop 1
	v_lshl_add_u64 v[84:85], v[76:77], 0, v[152:153]
	v_cvt_pk_bf16_f32 v76, v80, v81
	v_cvt_pk_bf16_f32 v77, v82, v83
	v_cvt_pk_bf16_f32 v78, v72, v73
	v_cvt_pk_bf16_f32 v79, v74, v75
	global_store_dwordx4 v[84:85], v[76:79], off
	v_cvt_pk_bf16_f32 v68, v68, v69
	v_cvt_pk_bf16_f32 v69, v70, v71
	v_cvt_pk_bf16_f32 v70, v64, v65
	v_cvt_pk_bf16_f32 v71, v66, v67
	global_store_dwordx4 v[84:85], v[68:71], off offset:256
	v_cvt_pk_bf16_f32 v60, v60, v61
	v_cvt_pk_bf16_f32 v61, v62, v63
	v_cvt_pk_bf16_f32 v62, v56, v57
	v_add_co_u32_e32 v56, vcc, s57, v140
	v_lshl_add_u64 v[64:65], v[140:141], 0, s[8:9]
	s_nop 0
	v_addc_co_u32_e32 v57, vcc, 0, v141, vcc
	v_cvt_pk_bf16_f32 v63, v58, v59
	global_store_dwordx4 v[56:57], v[60:63], off
	v_cvt_pk_bf16_f32 v48, v48, v49
	v_cvt_pk_bf16_f32 v49, v50, v51
	v_cvt_pk_bf16_f32 v50, v40, v41
	v_cvt_pk_bf16_f32 v51, v42, v43
	global_store_dwordx4 v[64:65], v[48:51], off offset:256
	v_cvt_pk_bf16_f32 v40, v52, v53
	v_cvt_pk_bf16_f32 v41, v54, v55
	v_cvt_pk_bf16_f32 v42, v44, v45
	v_add_co_u32_e32 v44, vcc, s58, v140
	s_nop 0
	v_lshl_add_u64 v[48:49], v[140:141], 0, s[30:31]
	v_addc_co_u32_e32 v45, vcc, 0, v141, vcc
	v_cvt_pk_bf16_f32 v43, v46, v47
	global_store_dwordx4 v[44:45], v[40:43], off
	v_cvt_pk_bf16_f32 v32, v32, v33
	v_cvt_pk_bf16_f32 v33, v34, v35
	v_cvt_pk_bf16_f32 v34, v24, v25
	v_cvt_pk_bf16_f32 v35, v26, v27
	global_store_dwordx4 v[48:49], v[32:35], off offset:256
	v_cvt_pk_bf16_f32 v24, v36, v37
	v_cvt_pk_bf16_f32 v25, v38, v39
	v_cvt_pk_bf16_f32 v26, v28, v29
	v_add_co_u32_e32 v28, vcc, s59, v140
	s_nop 0
	v_lshl_add_u64 v[32:33], v[140:141], 0, s[34:35]
	v_addc_co_u32_e32 v29, vcc, 0, v141, vcc
	v_cvt_pk_bf16_f32 v27, v30, v31
	global_store_dwordx4 v[28:29], v[24:27], off
	v_cvt_pk_bf16_f32 v16, v16, v17
	v_cvt_pk_bf16_f32 v17, v18, v19
	v_cvt_pk_bf16_f32 v18, v8, v9
	v_cvt_pk_bf16_f32 v19, v10, v11
	global_store_dwordx4 v[32:33], v[16:19], off offset:256
	v_cvt_pk_bf16_f32 v8, v20, v21
	v_cvt_pk_bf16_f32 v9, v22, v23
	v_cvt_pk_bf16_f32 v10, v12, v13
	v_add_co_u32_e32 v12, vcc, s60, v140
	s_nop 0
	v_lshl_add_u64 v[16:17], v[140:141], 0, s[36:37]
	v_addc_co_u32_e32 v13, vcc, 0, v141, vcc
	s_and_b64 vcc, exec, s[38:39]
	v_cvt_pk_bf16_f32 v11, v14, v15
	global_store_dwordx4 v[12:13], v[8:11], off
	v_cvt_pk_bf16_f32 v4, v4, v5
	v_cvt_pk_bf16_f32 v5, v6, v7
	v_cvt_pk_bf16_f32 v6, v0, v1
	v_cvt_pk_bf16_f32 v7, v2, v3
	global_store_dwordx4 v[16:17], v[4:7], off offset:256
	s_cbranch_vccz .LBB0_857
	s_waitcnt vmcnt(0)
	s_cmpk_gt_u32 s10, 0xff
	v_readlane_b32 s62, v232, 20
	v_readlane_b32 s61, v232, 21
	s_cbranch_scc1 .LBB0_868
	s_barrier

; #define PG8_STAGE(bufoff, gbase, voff) do { _Pragma("unroll") for (int _i = 0; _i < 2; ++_i) \
;         __builtin_amdgcn_global_load_lds((const unsigned*)((const char*)(gbase) + (voff)[_i]), (LAS unsigned*)(lds + (bufoff) + ldsw + _i * 8192), 16, 0, 0); } while (0)
; #define PG8_LDA(dst, b, h) do { _Pragma("unroll") for (int m = 0; m < 4; ++m) _Pragma("unroll") for (int k = 0; k < 2; ++k) dst[m][k] = *(const LAS bf16x8*)(lds + PG8_SA(b, h) + aoff + m * 2048 + k * 1024); } while (0)
; #define PG8_LDB(dst, b, h) do { _Pragma("unroll") for (int n = 0; n < 2; ++n) _Pragma("unroll") for (int k = 0; k < 2; ++k) dst[n][k] = *(const LAS bf16x8*)(lds + PG8_SB(b, h) + boff + n * 2048 + k * 1024); } while (0)
; #define PG8_WAIT_V(n) asm volatile("s_waitcnt vmcnt(" #n ")" ::: "memory")
; #define PG8_WAIT_L(n) asm volatile("s_waitcnt lgkmcnt(" #n ")" ::: "memory")
; #define PG8_BAR __builtin_amdgcn_s_barrier()
; #define PG8_SCHED __builtin_amdgcn_sched_barrier(0)
; template <class Epi>
; __device__ __forceinline__ void gemm_phase(LAS unsigned char* lds, const Gemm g, const StaticOrder& S, const Epi& E) {
;     ...
;         for (int t = 0; t < nt; t += 2) {
;             const bool last = (t == nt - 2);
;             const char* a1 = cA + (size_t)(t + 1) * kstep;
;             const char* a2 = last ? nA : cA + (size_t)(t + 2) * kstep; const char* b2 = last ? nB : cB + (size_t)(t + 2) * kstep;
;             const char* a3 = a2 + kstep; const char* b3 = b2 + kstep;
;             PG8_LDB(B0, 0, 0); PG8_SCHED; PG8_LDA(At, 0, 0); PG8_STAGE(PG8_SA(1, 1), a1 + hstep, voffA);
;             PG8_WAIT_L(8); PG8_BAR; PG8_WAIT_L(0); PG8_MMA(0, 0, At, B0); PG8_BAR; PG8_SCHED;
;             PG8_LDB(B1, 0, 1); PG8_STAGE(PG8_SB(0, 0), b2, voffB);
;             PG8_BAR; PG8_WAIT_L(0); PG8_MMA(0, 1, At, B1); PG8_BAR;
;             PG8_LDA(At, 0, 1); PG8_STAGE(PG8_SA(0, 0), a2, voffA);
;             PG8_BAR; PG8_WAIT_L(0); PG8_MMA(1, 0, At, B0); PG8_BAR; PG8_SCHED;
;             PG8_STAGE(PG8_SB(0, 1), b2 + hstep, voffB);
;             PG8_WAIT_V(6); PG8_BAR; PG8_MMA(1, 1, At, B1); PG8_BAR;
;             PG8_LDB(B0, 1, 0); PG8_SCHED; PG8_LDA(At, 1, 0); PG8_STAGE(PG8_SA(0, 1), a2 + hstep, voffA);
;             PG8_WAIT_L(8); PG8_BAR; PG8_WAIT_L(0); PG8_MMA(0, 0, At, B0); PG8_BAR; PG8_SCHED;
.LBB0_999:
	ds_read_b128 v[140:143], v151
	ds_read_b128 v[144:147], v151 offset:1024
	ds_read_b128 v[154:157], v151 offset:2048
	ds_read_b128 v[160:163], v151 offset:3072
	s_add_u32 s48, s46, 0xfff80080
	s_addc_u32 s49, s47, -1
	s_cmp_eq_u32 s63, 28
	s_cselect_b32 s51, s37, s49
	s_cselect_b32 s50, s59, s48
	s_cselect_b32 s49, s35, s62
	s_cselect_b32 s48, s60, s61
	s_add_i32 m0, s28, 0xc000
	ds_read_b128 v[164:167], v152
	ds_read_b128 v[168:171], v152 offset:1024
	ds_read_b128 v[172:175], v152 offset:2048
	ds_read_b128 v[176:179], v152 offset:3072
	ds_read_b128 v[180:183], v152 offset:4096
	ds_read_b128 v[184:187], v152 offset:5120
	ds_read_b128 v[188:191], v152 offset:6144
	ds_read_b128 v[192:195], v152 offset:7168
	global_load_lds_dwordx4 v136, s[46:47]
	s_add_i32 m0, s28, 0xe000
	s_nop 0
	global_load_lds_dwordx4 v138, s[46:47]
	s_waitcnt lgkmcnt(8)
	s_barrier
	s_waitcnt lgkmcnt(0)
	v_mfma_f32_16x16x32_bf16 v[124:127], v[140:143], v[164:167], v[124:127]
	v_mfma_f32_16x16x32_bf16 v[120:123], v[154:157], v[164:167], v[120:123]
	v_mfma_f32_16x16x32_bf16 v[108:111], v[140:143], v[172:175], v[108:111]
	v_mfma_f32_16x16x32_bf16 v[104:107], v[154:157], v[172:175], v[104:107]
	v_mfma_f32_16x16x32_bf16 v[92:95], v[140:143], v[180:183], v[92:95]
	v_mfma_f32_16x16x32_bf16 v[88:91], v[154:157], v[180:183], v[88:91]
	v_mfma_f32_16x16x32_bf16 v[76:79], v[140:143], v[188:191], v[76:79]
	v_mfma_f32_16x16x32_bf16 v[72:75], v[154:157], v[188:191], v[72:75]
	v_mfma_f32_16x16x32_bf16 v[124:127], v[144:147], v[168:171], v[124:127]
	v_mfma_f32_16x16x32_bf16 v[120:123], v[160:163], v[168:171], v[120:123]
	v_mfma_f32_16x16x32_bf16 v[108:111], v[144:147], v[176:179], v[108:111]
	v_mfma_f32_16x16x32_bf16 v[104:107], v[160:163], v[176:179], v[104:107]
	v_mfma_f32_16x16x32_bf16 v[92:95], v[144:147], v[184:187], v[92:95]
	v_mfma_f32_16x16x32_bf16 v[88:91], v[160:163], v[184:187], v[88:91]
	v_mfma_f32_16x16x32_bf16 v[76:79], v[144:147], v[192:195], v[76:79]
	v_mfma_f32_16x16x32_bf16 v[72:75], v[160:163], v[192:195], v[72:75]
	s_barrier
	s_add_i32 s64, s56, s23
	s_add_u32 s98, s48, s4
	s_addc_u32 s99, s49, s5
	s_mov_b32 m0, s64
	ds_read_b128 v[196:199], v153
	ds_read_b128 v[200:203], v153 offset:1024
	ds_read_b128 v[204:207], v153 offset:2048
	ds_read_b128 v[208:211], v153 offset:3072
	global_load_lds_dwordx4 v132, s[48:49]
	s_add_i32 m0, s64, 0x2000
	s_nop 0
	global_load_lds_dwordx4 v128, s[48:49]
	s_waitcnt lgkmcnt(0)
	s_barrier
	v_mfma_f32_16x16x32_bf16 v[116:119], v[196:199], v[164:167], v[116:119]
	v_mfma_f32_16x16x32_bf16 v[112:115], v[204:207], v[164:167], v[112:115]
	v_mfma_f32_16x16x32_bf16 v[100:103], v[196:199], v[172:175], v[100:103]
	v_mfma_f32_16x16x32_bf16 v[96:99], v[204:207], v[172:175], v[96:99]
	v_mfma_f32_16x16x32_bf16 v[84:87], v[196:199], v[180:183], v[84:87]
	v_mfma_f32_16x16x32_bf16 v[80:83], v[204:207], v[180:183], v[80:83]
	v_mfma_f32_16x16x32_bf16 v[68:71], v[196:199], v[188:191], v[68:71]
	v_mfma_f32_16x16x32_bf16 v[64:67], v[204:207], v[188:191], v[64:67]
	v_mfma_f32_16x16x32_bf16 v[116:119], v[200:203], v[168:171], v[116:119]
	v_mfma_f32_16x16x32_bf16 v[112:115], v[208:211], v[168:171], v[112:115]
	v_mfma_f32_16x16x32_bf16 v[100:103], v[200:203], v[176:179], v[100:103]
	v_mfma_f32_16x16x32_bf16 v[96:99], v[208:211], v[176:179], v[96:99]
	v_mfma_f32_16x16x32_bf16 v[84:87], v[200:203], v[184:187], v[84:87]
	v_mfma_f32_16x16x32_bf16 v[80:83], v[208:211], v[184:187], v[80:83]
	v_mfma_f32_16x16x32_bf16 v[68:71], v[200:203], v[192:195], v[68:71]
	v_mfma_f32_16x16x32_bf16 v[64:67], v[208:211], v[192:195], v[64:67]
	s_mov_b32 m0, s28
	s_add_u32 s100, s50, s4
	s_addc_u32 s101, s51, s5
	s_barrier
	ds_read_b128 v[164:167], v152 offset:16384
	ds_read_b128 v[168:171], v152 offset:17408
	ds_read_b128 v[172:175], v152 offset:18432
	ds_read_b128 v[176:179], v152 offset:19456
	ds_read_b128 v[180:183], v152 offset:20480
	ds_read_b128 v[184:187], v152 offset:21504
	ds_read_b128 v[188:191], v152 offset:22528
	ds_read_b128 v[192:195], v152 offset:23552
	global_load_lds_dwordx4 v134, s[50:51]
	s_mov_b32 m0, s29
	s_nop 0
	global_load_lds_dwordx4 v130, s[50:51]
	s_waitcnt lgkmcnt(0)
	s_barrier
	v_mfma_f32_16x16x32_bf16 v[60:63], v[140:143], v[164:167], v[60:63]
	v_mfma_f32_16x16x32_bf16 v[56:59], v[154:157], v[164:167], v[56:59]
	v_mfma_f32_16x16x32_bf16 v[44:47], v[140:143], v[172:175], v[44:47]
	v_mfma_f32_16x16x32_bf16 v[40:43], v[154:157], v[172:175], v[40:43]
	v_mfma_f32_16x16x32_bf16 v[28:31], v[140:143], v[180:183], v[28:31]
	v_mfma_f32_16x16x32_bf16 v[24:27], v[154:157], v[180:183], v[24:27]
	v_mfma_f32_16x16x32_bf16 v[12:15], v[140:143], v[188:191], v[12:15]
	v_mfma_f32_16x16x32_bf16 v[8:11], v[154:157], v[188:191], v[8:11]
	v_mfma_f32_16x16x32_bf16 v[60:63], v[144:147], v[168:171], v[60:63]
	v_mfma_f32_16x16x32_bf16 v[56:59], v[160:163], v[168:171], v[56:59]
	v_mfma_f32_16x16x32_bf16 v[44:47], v[144:147], v[176:179], v[44:47]
	v_mfma_f32_16x16x32_bf16 v[40:43], v[160:163], v[176:179], v[40:43]
	v_mfma_f32_16x16x32_bf16 v[28:31], v[144:147], v[184:187], v[28:31]
	v_mfma_f32_16x16x32_bf16 v[24:27], v[160:163], v[184:187], v[24:27]
	v_mfma_f32_16x16x32_bf16 v[12:15], v[144:147], v[192:195], v[12:15]
	v_mfma_f32_16x16x32_bf16 v[8:11], v[160:163], v[192:195], v[8:11]
	s_barrier
	s_add_u32 s64, s48, 0x80000
	s_addc_u32 s65, s49, 0
	s_add_i32 s66, s57, s23
	s_mov_b32 m0, s66
	s_nop 0
	global_load_lds_dwordx4 v132, s[64:65]
	s_add_i32 m0, s66, 0x2000
	s_nop 0
	global_load_lds_dwordx4 v128, s[64:65]
	s_waitcnt vmcnt(6)
	s_barrier
; #define PG8_STAGE(bufoff, gbase, voff) do { _Pragma("unroll") for (int _i = 0; _i < 2; ++_i) \
;         __builtin_amdgcn_global_load_lds((const unsigned*)((const char*)(gbase) + (voff)[_i]), (LAS unsigned*)(lds + (bufoff) + ldsw + _i * 8192), 16, 0, 0); } while (0)
; #define PG8_LDA(dst, b, h) do { _Pragma("unroll") for (int m = 0; m < 4; ++m) _Pragma("unroll") for (int k = 0; k < 2; ++k) dst[m][k] = *(const LAS bf16x8*)(lds + PG8_SA(b, h) + aoff + m * 2048 + k * 1024); } while (0)
; #define PG8_LDB(dst, b, h) do { _Pragma("unroll") for (int n = 0; n < 2; ++n) _Pragma("unroll") for (int k = 0; k < 2; ++k) dst[n][k] = *(const LAS bf16x8*)(lds + PG8_SB(b, h) + boff + n * 2048 + k * 1024); } while (0)
; #define PG8_MMA(ai, bj, At, Bt) do { __builtin_amdgcn_s_setprio(1); _Pragma("unroll") for (int m = 0; m < 4; ++m) _Pragma("unroll") for (int n = 0; n < 2; ++n) _Pragma("unroll") for (int k = 0; k < 2; ++k) \
;         acc[ai][bj][m][n] = __builtin_amdgcn_mfma_f32_16x16x32_bf16(Bt[n][k], At[m][k], acc[ai][bj][m][n], 0, 0, 0); __builtin_amdgcn_s_setprio(0); } while (0)
; #define PG8_WAIT_V(n) asm volatile("s_waitcnt vmcnt(" #n ")" ::: "memory")
; #define PG8_WAIT_L(n) asm volatile("s_waitcnt lgkmcnt(" #n ")" ::: "memory")
; #define PG8_BAR __builtin_amdgcn_s_barrier()
; #define PG8_SCHED __builtin_amdgcn_sched_barrier(0)
; template <class Epi>
; __device__ __forceinline__ void gemm_phase(LAS unsigned char* lds, const Gemm g, const StaticOrder& S, const Epi& E) {
;     ...
;             PG8_WAIT_V(6); PG8_BAR; PG8_MMA(1, 1, At, B1); PG8_BAR;
;             PG8_LDB(B0, 1, 0); PG8_SCHED; PG8_LDA(At, 1, 0); PG8_STAGE(PG8_SA(0, 1), a2 + hstep, voffA);
;             PG8_WAIT_L(8); PG8_BAR; PG8_WAIT_L(0); PG8_MMA(0, 0, At, B0); PG8_BAR; PG8_SCHED;
;             PG8_LDB(B1, 1, 1); PG8_STAGE(PG8_SB(1, 0), b3, voffB);
;             PG8_BAR; PG8_WAIT_L(0); PG8_MMA(0, 1, At, B1); PG8_BAR;
;             PG8_LDA(At, 1, 1); PG8_STAGE(PG8_SA(1, 0), a3, voffA);
;             PG8_BAR; PG8_WAIT_L(0); PG8_MMA(1, 0, At, B0); PG8_BAR; PG8_SCHED;
;             PG8_STAGE(PG8_SB(1, 1), b3 + hstep, voffB);
;             PG8_WAIT_V(6); PG8_BAR; PG8_MMA(1, 1, At, B1); PG8_BAR;
	v_mfma_f32_16x16x32_bf16 v[52:55], v[196:199], v[164:167], v[52:55]
	v_mfma_f32_16x16x32_bf16 v[48:51], v[204:207], v[164:167], v[48:51]
	v_mfma_f32_16x16x32_bf16 v[36:39], v[196:199], v[172:175], v[36:39]
	v_mfma_f32_16x16x32_bf16 v[32:35], v[204:207], v[172:175], v[32:35]
	v_mfma_f32_16x16x32_bf16 v[20:23], v[196:199], v[180:183], v[20:23]
	v_mfma_f32_16x16x32_bf16 v[16:19], v[204:207], v[180:183], v[16:19]
	v_mfma_f32_16x16x32_bf16 v[4:7], v[196:199], v[188:191], v[4:7]
	v_mfma_f32_16x16x32_bf16 v[0:3], v[204:207], v[188:191], v[0:3]
	v_mfma_f32_16x16x32_bf16 v[52:55], v[200:203], v[168:171], v[52:55]
	v_mfma_f32_16x16x32_bf16 v[48:51], v[208:211], v[168:171], v[48:51]
	v_mfma_f32_16x16x32_bf16 v[36:39], v[200:203], v[176:179], v[36:39]
	v_mfma_f32_16x16x32_bf16 v[32:35], v[208:211], v[176:179], v[32:35]
	v_mfma_f32_16x16x32_bf16 v[20:23], v[200:203], v[184:187], v[20:23]
	v_mfma_f32_16x16x32_bf16 v[16:19], v[208:211], v[184:187], v[16:19]
	v_mfma_f32_16x16x32_bf16 v[4:7], v[200:203], v[192:195], v[4:7]
	v_mfma_f32_16x16x32_bf16 v[0:3], v[208:211], v[192:195], v[0:3]
	s_add_i32 s64, 0, 0x18000
	v_add_u32_e32 v160, s64, v149
	s_barrier
	ds_read_b128 v[140:143], v160
	ds_read_b128 v[144:147], v160 offset:1024
	ds_read_b128 v[154:157], v160 offset:2048
	ds_read_b128 v[160:163], v160 offset:3072
	s_add_u32 s50, s50, 0x80000
	s_addc_u32 s51, s51, 0
	s_mov_b32 m0, s33
	ds_read_b128 v[164:167], v152 offset:32768
	ds_read_b128 v[168:171], v152 offset:33792
	ds_read_b128 v[172:175], v152 offset:34816
	ds_read_b128 v[176:179], v152 offset:35840
	ds_read_b128 v[180:183], v152 offset:36864
	ds_read_b128 v[184:187], v152 offset:37888
	ds_read_b128 v[188:191], v152 offset:38912
	ds_read_b128 v[192:195], v152 offset:39936
	global_load_lds_dwordx4 v134, s[50:51]
	s_mov_b32 m0, s45
	s_nop 0
	global_load_lds_dwordx4 v130, s[50:51]
	s_waitcnt lgkmcnt(8)
	s_barrier
	s_waitcnt lgkmcnt(0)
	v_mfma_f32_16x16x32_bf16 v[124:127], v[140:143], v[164:167], v[124:127]
	v_mfma_f32_16x16x32_bf16 v[120:123], v[154:157], v[164:167], v[120:123]
	v_mfma_f32_16x16x32_bf16 v[108:111], v[140:143], v[172:175], v[108:111]
	v_mfma_f32_16x16x32_bf16 v[104:107], v[154:157], v[172:175], v[104:107]
	v_mfma_f32_16x16x32_bf16 v[92:95], v[140:143], v[180:183], v[92:95]
	v_mfma_f32_16x16x32_bf16 v[88:91], v[154:157], v[180:183], v[88:91]
	v_mfma_f32_16x16x32_bf16 v[76:79], v[140:143], v[188:191], v[76:79]
	v_mfma_f32_16x16x32_bf16 v[72:75], v[154:157], v[188:191], v[72:75]
	v_mfma_f32_16x16x32_bf16 v[124:127], v[144:147], v[168:171], v[124:127]
	v_mfma_f32_16x16x32_bf16 v[120:123], v[160:163], v[168:171], v[120:123]
	v_mfma_f32_16x16x32_bf16 v[108:111], v[144:147], v[176:179], v[108:111]
	v_mfma_f32_16x16x32_bf16 v[104:107], v[160:163], v[176:179], v[104:107]
	v_mfma_f32_16x16x32_bf16 v[92:95], v[144:147], v[184:187], v[92:95]
	v_mfma_f32_16x16x32_bf16 v[88:91], v[160:163], v[184:187], v[88:91]
	v_mfma_f32_16x16x32_bf16 v[76:79], v[144:147], v[192:195], v[76:79]
	v_mfma_f32_16x16x32_bf16 v[72:75], v[160:163], v[192:195], v[72:75]
	s_barrier
	s_add_i32 s50, 0, 0x1c000
	s_add_i32 s51, s64, s23
	v_add_u32_e32 v208, s50, v149
	s_mov_b32 m0, s51
	ds_read_b128 v[196:199], v208
	ds_read_b128 v[200:203], v208 offset:1024
	ds_read_b128 v[204:207], v208 offset:2048
	ds_read_b128 v[208:211], v208 offset:3072
	global_load_lds_dwordx4 v132, s[98:99]
	s_add_i32 m0, s51, 0x2000
	s_nop 0
	global_load_lds_dwordx4 v128, s[98:99]
	s_waitcnt lgkmcnt(0)
	s_barrier
	v_mfma_f32_16x16x32_bf16 v[116:119], v[196:199], v[164:167], v[116:119]
	v_mfma_f32_16x16x32_bf16 v[112:115], v[204:207], v[164:167], v[112:115]
	v_mfma_f32_16x16x32_bf16 v[100:103], v[196:199], v[172:175], v[100:103]
	v_mfma_f32_16x16x32_bf16 v[96:99], v[204:207], v[172:175], v[96:99]
	v_mfma_f32_16x16x32_bf16 v[84:87], v[196:199], v[180:183], v[84:87]
	v_mfma_f32_16x16x32_bf16 v[80:83], v[204:207], v[180:183], v[80:83]
	v_mfma_f32_16x16x32_bf16 v[68:71], v[196:199], v[188:191], v[68:71]
	v_mfma_f32_16x16x32_bf16 v[64:67], v[204:207], v[188:191], v[64:67]
	v_mfma_f32_16x16x32_bf16 v[116:119], v[200:203], v[168:171], v[116:119]
	v_mfma_f32_16x16x32_bf16 v[112:115], v[208:211], v[168:171], v[112:115]
	v_mfma_f32_16x16x32_bf16 v[100:103], v[200:203], v[176:179], v[100:103]
	v_mfma_f32_16x16x32_bf16 v[96:99], v[208:211], v[176:179], v[96:99]
	v_mfma_f32_16x16x32_bf16 v[84:87], v[200:203], v[184:187], v[84:87]
	v_mfma_f32_16x16x32_bf16 v[80:83], v[208:211], v[184:187], v[80:83]
	v_mfma_f32_16x16x32_bf16 v[68:71], v[200:203], v[192:195], v[68:71]
	v_mfma_f32_16x16x32_bf16 v[64:67], v[208:211], v[192:195], v[64:67]
	s_mov_b32 m0, s53
	s_barrier
	ds_read_b128 v[164:167], v152 offset:49152
	ds_read_b128 v[168:171], v152 offset:50176
	ds_read_b128 v[172:175], v152 offset:51200
	ds_read_b128 v[176:179], v152 offset:52224
	ds_read_b128 v[180:183], v152 offset:53248
	ds_read_b128 v[184:187], v152 offset:54272
	ds_read_b128 v[188:191], v152 offset:55296
	ds_read_b128 v[192:195], v152 offset:56320
	global_load_lds_dwordx4 v134, s[100:101]
	s_mov_b32 m0, s54
	s_nop 0
	global_load_lds_dwordx4 v130, s[100:101]
	s_waitcnt lgkmcnt(0)
	s_barrier
; __device__ __forceinline__ float bf_lo(unsigned w) { return __uint_as_float(w << 16); }
; __device__ __forceinline__ float bf_hi(unsigned w) { return __uint_as_float(w & 0xffff0000u); }
; __device__ __forceinline__ float fast_rcp(float x) { return __builtin_amdgcn_rcpf(x); }
; __device__ __forceinline__ float fast_exp2(float x) { return __builtin_amdgcn_exp2f(x); }
; #define PG8_STAGE(bufoff, gbase, voff) do { _Pragma("unroll") for (int _i = 0; _i < 2; ++_i) \
;         __builtin_amdgcn_global_load_lds((const unsigned*)((const char*)(gbase) + (voff)[_i]), (LAS unsigned*)(lds + (bufoff) + ldsw + _i * 8192), 16, 0, 0); } while (0)
; #define PG8_WAIT_V(n) asm volatile("s_waitcnt vmcnt(" #n ")" ::: "memory")
; #define PG8_WAIT_L(n) asm volatile("s_waitcnt lgkmcnt(" #n ")" ::: "memory")
; #define PG8_BAR __builtin_amdgcn_s_barrier()
; template <class Epi>
; __device__ __forceinline__ void gemm_phase(LAS unsigned char* lds, const Gemm g, const StaticOrder& S, const Epi& E) {
;     ...
;             PG8_BAR; PG8_WAIT_L(0); PG8_MMA(1, 0, At, B0); PG8_BAR; PG8_SCHED;
;             PG8_STAGE(PG8_SB(1, 1), b3 + hstep, voffB);
;             PG8_WAIT_V(6); PG8_BAR; PG8_MMA(1, 1, At, B1); PG8_BAR;
;         }
;     __device__ __forceinline__ void operator()(const f32x4 (&acc)[2][2][4][2], const Unit& u, int wr, int wc, int fr, int fq) const {
;         const int row0 = u.pm * BM + wr * 64 + fr, col0 = u.pn * BM + wc * 32 + 8 * fq;
; #pragma unroll
;         for (int ai = 0; ai < 2; ++ai)
; #pragma unroll
;             for (int m = 0; m < 4; ++m) { const size_t ro = (size_t)(row0 + ai * HALF + m * 16) * DM + col0; const float nr = -LOG2E * rs[row0 + ai * HALF + m * 16];
; #pragma unroll
;                 for (int bj = 0; bj < 2; ++bj) {
;                     const u32x4 pw = *(const u32x4*)(PP + ro + bj * HALF);
;                     const float pv[8] = {bf_lo(pw.x), bf_hi(pw.x), bf_lo(pw.y), bf_hi(pw.y), bf_lo(pw.z), bf_hi(pw.z), bf_lo(pw.w), bf_hi(pw.w)};
;                     f32x4 t0, t1;
; #pragma unroll
;                     for (int j = 0; j < 4; ++j) {
;                         t0[j] = fast_rcp(1.0f + fast_exp2(acc[ai][bj][m][0][j] * nr)) * pv[j];
;                         t1[j] = fast_rcp(1.0f + fast_exp2(acc[ai][bj][m][1][j] * nr)) * pv[4 + j]; }
;                     *(u32x4*)(O + ro + bj * HALF) = pack8(t0, t1); } }
	v_mfma_f32_16x16x32_bf16 v[60:63], v[140:143], v[164:167], v[60:63]
	v_mfma_f32_16x16x32_bf16 v[56:59], v[154:157], v[164:167], v[56:59]
	v_mfma_f32_16x16x32_bf16 v[44:47], v[140:143], v[172:175], v[44:47]
	v_mfma_f32_16x16x32_bf16 v[40:43], v[154:157], v[172:175], v[40:43]
	v_mfma_f32_16x16x32_bf16 v[28:31], v[140:143], v[180:183], v[28:31]
	v_mfma_f32_16x16x32_bf16 v[24:27], v[154:157], v[180:183], v[24:27]
	v_mfma_f32_16x16x32_bf16 v[12:15], v[140:143], v[188:191], v[12:15]
	v_mfma_f32_16x16x32_bf16 v[8:11], v[154:157], v[188:191], v[8:11]
	v_mfma_f32_16x16x32_bf16 v[60:63], v[144:147], v[168:171], v[60:63]
	v_mfma_f32_16x16x32_bf16 v[56:59], v[160:163], v[168:171], v[56:59]
	v_mfma_f32_16x16x32_bf16 v[44:47], v[144:147], v[176:179], v[44:47]
	v_mfma_f32_16x16x32_bf16 v[40:43], v[160:163], v[176:179], v[40:43]
	v_mfma_f32_16x16x32_bf16 v[28:31], v[144:147], v[184:187], v[28:31]
	v_mfma_f32_16x16x32_bf16 v[24:27], v[160:163], v[184:187], v[24:27]
	v_mfma_f32_16x16x32_bf16 v[12:15], v[144:147], v[192:195], v[12:15]
	v_mfma_f32_16x16x32_bf16 v[8:11], v[160:163], v[192:195], v[8:11]
	s_barrier
	s_add_u32 s48, s48, 0x80080
	s_addc_u32 s49, s49, 0
	s_add_i32 s50, s50, s23
	s_mov_b32 m0, s50
	s_nop 0
	global_load_lds_dwordx4 v132, s[48:49]
	s_add_i32 m0, s50, 0x2000
	s_nop 0
	global_load_lds_dwordx4 v128, s[48:49]
	s_waitcnt vmcnt(6)
	s_barrier
	v_mfma_f32_16x16x32_bf16 v[52:55], v[196:199], v[164:167], v[52:55]
	v_mfma_f32_16x16x32_bf16 v[48:51], v[204:207], v[164:167], v[48:51]
	v_mfma_f32_16x16x32_bf16 v[36:39], v[196:199], v[172:175], v[36:39]
	v_mfma_f32_16x16x32_bf16 v[32:35], v[204:207], v[172:175], v[32:35]
	v_mfma_f32_16x16x32_bf16 v[20:23], v[196:199], v[180:183], v[20:23]
	v_mfma_f32_16x16x32_bf16 v[16:19], v[204:207], v[180:183], v[16:19]
	v_mfma_f32_16x16x32_bf16 v[4:7], v[196:199], v[188:191], v[4:7]
	v_mfma_f32_16x16x32_bf16 v[0:3], v[204:207], v[188:191], v[0:3]
	v_mfma_f32_16x16x32_bf16 v[52:55], v[200:203], v[168:171], v[52:55]
	v_mfma_f32_16x16x32_bf16 v[48:51], v[208:211], v[168:171], v[48:51]
	v_mfma_f32_16x16x32_bf16 v[36:39], v[200:203], v[176:179], v[36:39]
	v_mfma_f32_16x16x32_bf16 v[32:35], v[208:211], v[176:179], v[32:35]
	v_mfma_f32_16x16x32_bf16 v[20:23], v[200:203], v[184:187], v[20:23]
	v_mfma_f32_16x16x32_bf16 v[16:19], v[208:211], v[184:187], v[16:19]
	v_mfma_f32_16x16x32_bf16 v[4:7], v[200:203], v[192:195], v[4:7]
	v_mfma_f32_16x16x32_bf16 v[0:3], v[208:211], v[192:195], v[0:3]
	s_add_i32 s63, s63, 2
	s_add_u32 s46, s46, 0x100
	s_addc_u32 s47, s47, 0
	s_add_u32 s61, s61, 0x100
	s_addc_u32 s62, s62, 0
	s_cmp_gt_u32 s63, 29
	s_barrier
	s_cbranch_scc0 .LBB0_999
	v_lshl_add_u32 v144, s44, 8, v148
	v_ashrrev_i32_e32 v145, 31, v144
	v_lshl_add_u64 v[140:141], v[144:145], 2, s[14:15]
	global_load_dword v164, v[140:141], off
	v_lshl_or_b32 v146, s58, 8, v150
	v_ashrrev_i32_e32 v147, 31, v146
	v_lshlrev_b64 v[142:143], 11, v[144:145]
	v_lshl_add_u64 v[142:143], v[142:143], 0, v[146:147]
	v_lshlrev_b64 v[142:143], 1, v[142:143]
	v_lshl_add_u64 v[160:161], s[20:21], 0, v[142:143]
	global_load_dwordx4 v[154:157], v[160:161], off
	global_load_dwordx4 v[220:223], v[160:161], off offset:256
	v_lshl_add_u64 v[162:163], s[24:25], 0, v[142:143]
	s_and_b64 vcc, exec, s[38:39]
	s_mov_b32 s58, s34
	s_mov_b32 s44, s36
	s_mov_b64 s[48:49], s[42:43]
	s_mov_b64 s[46:47], s[40:41]
	s_waitcnt vmcnt(0)
	v_mul_f32_e32 v145, 0xbfb8aa3b, v164
	v_mul_f32_e32 v124, v124, v145
	v_mul_f32_e32 v120, v120, v145
	v_mul_f32_e32 v125, v125, v145
	v_mul_f32_e32 v121, v121, v145
	v_mul_f32_e32 v126, v126, v145
	v_mul_f32_e32 v122, v122, v145
	v_mul_f32_e32 v127, v127, v145
	v_mul_f32_e32 v123, v123, v145
	v_exp_f32_e32 v124, v124
	v_exp_f32_e32 v120, v120
	v_exp_f32_e32 v125, v125
	v_exp_f32_e32 v121, v121
	v_exp_f32_e32 v126, v126
	v_exp_f32_e32 v122, v122
	v_exp_f32_e32 v127, v127
	v_exp_f32_e32 v123, v123
	v_add_f32_e32 v124, 1.0, v124
	v_add_f32_e32 v120, 1.0, v120
	v_add_f32_e32 v125, 1.0, v125
	v_add_f32_e32 v121, 1.0, v121
	v_add_f32_e32 v126, 1.0, v126
	v_add_f32_e32 v122, 1.0, v122
	v_add_f32_e32 v127, 1.0, v127
	v_add_f32_e32 v123, 1.0, v123
	v_rcp_f32_e32 v124, v124
	v_rcp_f32_e32 v120, v120
	v_rcp_f32_e32 v125, v125
	v_rcp_f32_e32 v121, v121
	v_rcp_f32_e32 v126, v126
	v_rcp_f32_e32 v122, v122
	v_rcp_f32_e32 v127, v127
	v_rcp_f32_e32 v123, v123
	v_lshlrev_b32_e32 v164, 16, v154
	v_and_b32_e32 v154, 0xffff0000, v154
	v_lshlrev_b32_e32 v165, 16, v155
	v_and_b32_e32 v155, 0xffff0000, v155
	v_lshlrev_b32_e32 v166, 16, v156
	v_and_b32_e32 v156, 0xffff0000, v156
	v_lshlrev_b32_e32 v167, 16, v157
	v_and_b32_e32 v157, 0xffff0000, v157
	v_mul_f32_e32 v124, v124, v164
	v_mul_f32_e32 v164, v120, v166
	v_mul_f32_e32 v120, v125, v154
	v_mul_f32_e32 v125, v121, v156
	v_mul_f32_e32 v121, v126, v165
	v_mul_f32_e32 v126, v122, v167
	v_mul_f32_e32 v122, v127, v155
	v_mul_f32_e32 v123, v123, v157
	v_cvt_pk_bf16_f32 v120, v124, v120
	v_cvt_pk_bf16_f32 v121, v121, v122
	v_cvt_pk_bf16_f32 v122, v164, v125
	v_cvt_pk_bf16_f32 v123, v126, v123
	global_store_dwordx4 v[162:163], v[120:123], off
	v_mul_f32_e32 v116, v116, v145
	v_mul_f32_e32 v112, v112, v145
	v_mul_f32_e32 v117, v117, v145
	v_mul_f32_e32 v113, v113, v145
	v_mul_f32_e32 v118, v118, v145
	v_mul_f32_e32 v114, v114, v145
	v_mul_f32_e32 v119, v119, v145
	v_mul_f32_e32 v115, v115, v145
	v_exp_f32_e32 v116, v116
	v_exp_f32_e32 v112, v112
	v_exp_f32_e32 v117, v117
	v_exp_f32_e32 v113, v113
	v_exp_f32_e32 v118, v118
	v_exp_f32_e32 v114, v114
	v_exp_f32_e32 v119, v119
	v_exp_f32_e32 v115, v115
	v_add_f32_e32 v116, 1.0, v116
	v_add_f32_e32 v112, 1.0, v112
	v_add_f32_e32 v117, 1.0, v117
	v_add_f32_e32 v113, 1.0, v113
; __device__ __forceinline__ float bf_lo(unsigned w) { return __uint_as_float(w << 16); }
; __device__ __forceinline__ float bf_hi(unsigned w) { return __uint_as_float(w & 0xffff0000u); }
; __device__ __forceinline__ float fast_rcp(float x) { return __builtin_amdgcn_rcpf(x); }
; __device__ __forceinline__ float fast_exp2(float x) { return __builtin_amdgcn_exp2f(x); }
; __device__ __forceinline__ u32x4 pack8(f32x4 v0, f32x4 v1) { u32x4 w; w.x = cvt_pk_bf16(v0[0], v0[1]); w.y = cvt_pk_bf16(v0[2], v0[3]); w.z = cvt_pk_bf16(v1[0], v1[1]); w.w = cvt_pk_bf16(v1[2], v1[3]); return w; }
;     __device__ __forceinline__ void operator()(const f32x4 (&acc)[2][2][4][2], const Unit& u, int wr, int wc, int fr, int fq) const {
;         const int row0 = u.pm * BM + wr * 64 + fr, col0 = u.pn * BM + wc * 32 + 8 * fq;
; #pragma unroll
;         for (int ai = 0; ai < 2; ++ai)
; #pragma unroll
;             for (int m = 0; m < 4; ++m) { const size_t ro = (size_t)(row0 + ai * HALF + m * 16) * DM + col0; const float nr = -LOG2E * rs[row0 + ai * HALF + m * 16];
; #pragma unroll
;                 for (int bj = 0; bj < 2; ++bj) {
;                     const u32x4 pw = *(const u32x4*)(PP + ro + bj * HALF);
;                     const float pv[8] = {bf_lo(pw.x), bf_hi(pw.x), bf_lo(pw.y), bf_hi(pw.y), bf_lo(pw.z), bf_hi(pw.z), bf_lo(pw.w), bf_hi(pw.w)};
;                     f32x4 t0, t1;
; #pragma unroll
;                     for (int j = 0; j < 4; ++j) {
;                         t0[j] = fast_rcp(1.0f + fast_exp2(acc[ai][bj][m][0][j] * nr)) * pv[j];
;                         t1[j] = fast_rcp(1.0f + fast_exp2(acc[ai][bj][m][1][j] * nr)) * pv[4 + j]; }
;                     *(u32x4*)(O + ro + bj * HALF) = pack8(t0, t1); } }
	v_add_f32_e32 v118, 1.0, v118
	v_add_f32_e32 v114, 1.0, v114
	v_add_f32_e32 v119, 1.0, v119
	v_add_f32_e32 v115, 1.0, v115
	v_rcp_f32_e32 v116, v116
	v_rcp_f32_e32 v112, v112
	v_rcp_f32_e32 v117, v117
	v_rcp_f32_e32 v113, v113
	v_rcp_f32_e32 v118, v118
	v_rcp_f32_e32 v114, v114
	v_rcp_f32_e32 v119, v119
	v_rcp_f32_e32 v115, v115
	v_or_b32_e32 v124, 16, v144
	v_ashrrev_i32_e32 v125, 31, v124
	v_lshlrev_b64 v[124:125], 11, v[124:125]
	v_lshl_add_u64 v[124:125], v[124:125], 0, v[146:147]
	v_lshlrev_b64 v[124:125], 1, v[124:125]
	v_lshl_add_u64 v[126:127], s[20:21], 0, v[124:125]
	v_lshlrev_b32_e32 v145, 16, v220
	v_and_b32_e32 v120, 0xffff0000, v220
	v_lshlrev_b32_e32 v154, 16, v221
	v_and_b32_e32 v121, 0xffff0000, v221
	v_lshlrev_b32_e32 v155, 16, v222
	v_and_b32_e32 v122, 0xffff0000, v222
	v_lshlrev_b32_e32 v156, 16, v223
	v_and_b32_e32 v123, 0xffff0000, v223
	v_mul_f32_e32 v116, v116, v145
	v_mul_f32_e32 v145, v112, v155
	v_mul_f32_e32 v112, v117, v120
	v_mul_f32_e32 v117, v113, v122
	v_mul_f32_e32 v113, v118, v154
	v_mul_f32_e32 v118, v114, v156
	v_mul_f32_e32 v114, v119, v121
	v_mul_f32_e32 v115, v115, v123
	v_cvt_pk_bf16_f32 v112, v116, v112
	v_cvt_pk_bf16_f32 v113, v113, v114
	v_cvt_pk_bf16_f32 v114, v145, v117
	v_cvt_pk_bf16_f32 v115, v118, v115
	global_store_dwordx4 v[162:163], v[112:115], off offset:256
	global_load_dword v118, v[140:141], off offset:64
	s_nop 0
	global_load_dwordx4 v[112:115], v[126:127], off
	global_load_dwordx4 v[224:227], v[126:127], off offset:256
	v_lshl_add_u64 v[116:117], s[24:25], 0, v[124:125]
	s_waitcnt vmcnt(0)
	v_mul_f32_e32 v118, 0xbfb8aa3b, v118
	v_mul_f32_e32 v108, v108, v118
	v_mul_f32_e32 v104, v104, v118
	v_mul_f32_e32 v109, v109, v118
	v_mul_f32_e32 v105, v105, v118
	v_mul_f32_e32 v110, v110, v118
	v_mul_f32_e32 v106, v106, v118
	v_mul_f32_e32 v111, v111, v118
	v_mul_f32_e32 v107, v107, v118
	v_exp_f32_e32 v108, v108
	v_exp_f32_e32 v104, v104
	v_exp_f32_e32 v109, v109
	v_exp_f32_e32 v105, v105
	v_exp_f32_e32 v110, v110
	v_exp_f32_e32 v106, v106
	v_exp_f32_e32 v111, v111
	v_exp_f32_e32 v107, v107
	v_add_f32_e32 v108, 1.0, v108
	v_add_f32_e32 v104, 1.0, v104
	v_add_f32_e32 v109, 1.0, v109
	v_add_f32_e32 v105, 1.0, v105
	v_add_f32_e32 v110, 1.0, v110
	v_add_f32_e32 v106, 1.0, v106
	v_add_f32_e32 v111, 1.0, v111
	v_add_f32_e32 v107, 1.0, v107
	v_rcp_f32_e32 v108, v108
	v_rcp_f32_e32 v104, v104
	v_rcp_f32_e32 v109, v109
	v_rcp_f32_e32 v105, v105
	v_rcp_f32_e32 v110, v110
	v_rcp_f32_e32 v106, v106
	v_rcp_f32_e32 v111, v111
	v_rcp_f32_e32 v107, v107
	v_lshlrev_b32_e32 v119, 16, v112
	v_and_b32_e32 v112, 0xffff0000, v112
	v_lshlrev_b32_e32 v120, 16, v113
	v_and_b32_e32 v113, 0xffff0000, v113
	v_lshlrev_b32_e32 v121, 16, v114
	v_and_b32_e32 v114, 0xffff0000, v114
	v_lshlrev_b32_e32 v122, 16, v115
	v_and_b32_e32 v115, 0xffff0000, v115
	v_mul_f32_e32 v108, v108, v119
	v_mul_f32_e32 v119, v104, v121
	v_mul_f32_e32 v104, v109, v112
	v_mul_f32_e32 v109, v105, v114
	v_mul_f32_e32 v105, v110, v120
	v_mul_f32_e32 v110, v106, v122
	v_mul_f32_e32 v106, v111, v113
	v_mul_f32_e32 v107, v107, v115
	v_cvt_pk_bf16_f32 v104, v108, v104
	v_cvt_pk_bf16_f32 v105, v105, v106
	v_cvt_pk_bf16_f32 v106, v119, v109
	v_cvt_pk_bf16_f32 v107, v110, v107
	global_store_dwordx4 v[116:117], v[104:107], off
	v_mul_f32_e32 v100, v100, v118
	v_mul_f32_e32 v96, v96, v118
	v_mul_f32_e32 v101, v101, v118
	v_mul_f32_e32 v97, v97, v118
	v_mul_f32_e32 v102, v102, v118
	v_mul_f32_e32 v98, v98, v118
	v_mul_f32_e32 v103, v103, v118
	v_mul_f32_e32 v99, v99, v118
	v_exp_f32_e32 v100, v100
	v_exp_f32_e32 v96, v96
	v_exp_f32_e32 v101, v101
	v_exp_f32_e32 v97, v97
	v_exp_f32_e32 v102, v102
	v_exp_f32_e32 v98, v98
	v_exp_f32_e32 v103, v103
	v_exp_f32_e32 v99, v99
	v_add_f32_e32 v100, 1.0, v100
	v_add_f32_e32 v96, 1.0, v96
	v_add_f32_e32 v101, 1.0, v101
	v_add_f32_e32 v97, 1.0, v97
	v_add_f32_e32 v102, 1.0, v102
	v_add_f32_e32 v98, 1.0, v98
	v_add_f32_e32 v103, 1.0, v103
	v_add_f32_e32 v99, 1.0, v99
	v_rcp_f32_e32 v100, v100
	v_rcp_f32_e32 v96, v96
	v_rcp_f32_e32 v101, v101
	v_rcp_f32_e32 v97, v97
	v_rcp_f32_e32 v102, v102
	v_rcp_f32_e32 v98, v98
	v_rcp_f32_e32 v103, v103
	v_rcp_f32_e32 v99, v99
	v_or_b32_e32 v108, 32, v144
	v_ashrrev_i32_e32 v109, 31, v108
	v_lshlrev_b64 v[108:109], 11, v[108:109]
	v_lshl_add_u64 v[108:109], v[108:109], 0, v[146:147]
	v_lshlrev_b64 v[108:109], 1, v[108:109]
	v_lshl_add_u64 v[110:111], s[20:21], 0, v[108:109]
	v_lshlrev_b32_e32 v112, 16, v224
	v_and_b32_e32 v104, 0xffff0000, v224
	v_lshlrev_b32_e32 v113, 16, v225
	v_and_b32_e32 v105, 0xffff0000, v225
	v_lshlrev_b32_e32 v114, 16, v226
	v_and_b32_e32 v106, 0xffff0000, v226
	v_lshlrev_b32_e32 v115, 16, v227
	v_and_b32_e32 v107, 0xffff0000, v227
	v_mul_f32_e32 v100, v100, v112
	v_mul_f32_e32 v112, v96, v114
	v_mul_f32_e32 v96, v101, v104
	v_mul_f32_e32 v101, v97, v106
	v_mul_f32_e32 v97, v102, v113
	v_mul_f32_e32 v102, v98, v115
	v_mul_f32_e32 v98, v103, v105
	v_mul_f32_e32 v99, v99, v107
	v_cvt_pk_bf16_f32 v96, v100, v96
	v_cvt_pk_bf16_f32 v97, v97, v98
	v_cvt_pk_bf16_f32 v98, v112, v101
	v_cvt_pk_bf16_f32 v99, v102, v99
	global_store_dwordx4 v[116:117], v[96:99], off offset:256
	global_load_dword v102, v[140:141], off offset:128
	s_nop 0
	global_load_dwordx4 v[96:99], v[110:111], off
	global_load_dwordx4 v[220:223], v[110:111], off offset:256
	v_lshl_add_u64 v[100:101], s[24:25], 0, v[108:109]
	s_waitcnt vmcnt(0)
; __device__ __forceinline__ float bf_lo(unsigned w) { return __uint_as_float(w << 16); }
; __device__ __forceinline__ float bf_hi(unsigned w) { return __uint_as_float(w & 0xffff0000u); }
; __device__ __forceinline__ float fast_rcp(float x) { return __builtin_amdgcn_rcpf(x); }
; __device__ __forceinline__ float fast_exp2(float x) { return __builtin_amdgcn_exp2f(x); }
; __device__ __forceinline__ u32x4 pack8(f32x4 v0, f32x4 v1) { u32x4 w; w.x = cvt_pk_bf16(v0[0], v0[1]); w.y = cvt_pk_bf16(v0[2], v0[3]); w.z = cvt_pk_bf16(v1[0], v1[1]); w.w = cvt_pk_bf16(v1[2], v1[3]); return w; }
;     __device__ __forceinline__ void operator()(const f32x4 (&acc)[2][2][4][2], const Unit& u, int wr, int wc, int fr, int fq) const {
;         const int row0 = u.pm * BM + wr * 64 + fr, col0 = u.pn * BM + wc * 32 + 8 * fq;
; #pragma unroll
;         for (int ai = 0; ai < 2; ++ai)
; #pragma unroll
;             for (int m = 0; m < 4; ++m) { const size_t ro = (size_t)(row0 + ai * HALF + m * 16) * DM + col0; const float nr = -LOG2E * rs[row0 + ai * HALF + m * 16];
; #pragma unroll
;                 for (int bj = 0; bj < 2; ++bj) {
;                     const u32x4 pw = *(const u32x4*)(PP + ro + bj * HALF);
;                     const float pv[8] = {bf_lo(pw.x), bf_hi(pw.x), bf_lo(pw.y), bf_hi(pw.y), bf_lo(pw.z), bf_hi(pw.z), bf_lo(pw.w), bf_hi(pw.w)};
;                     f32x4 t0, t1;
; #pragma unroll
;                     for (int j = 0; j < 4; ++j) {
;                         t0[j] = fast_rcp(1.0f + fast_exp2(acc[ai][bj][m][0][j] * nr)) * pv[j];
;                         t1[j] = fast_rcp(1.0f + fast_exp2(acc[ai][bj][m][1][j] * nr)) * pv[4 + j]; }
;                     *(u32x4*)(O + ro + bj * HALF) = pack8(t0, t1); } }
	v_mul_f32_e32 v102, 0xbfb8aa3b, v102
	v_mul_f32_e32 v92, v92, v102
	v_mul_f32_e32 v88, v88, v102
	v_mul_f32_e32 v93, v93, v102
	v_mul_f32_e32 v89, v89, v102
	v_mul_f32_e32 v94, v94, v102
	v_mul_f32_e32 v90, v90, v102
	v_mul_f32_e32 v95, v95, v102
	v_mul_f32_e32 v91, v91, v102
	v_exp_f32_e32 v92, v92
	v_exp_f32_e32 v88, v88
	v_exp_f32_e32 v93, v93
	v_exp_f32_e32 v89, v89
	v_exp_f32_e32 v94, v94
	v_exp_f32_e32 v90, v90
	v_exp_f32_e32 v95, v95
	v_exp_f32_e32 v91, v91
	v_add_f32_e32 v92, 1.0, v92
	v_add_f32_e32 v88, 1.0, v88
	v_add_f32_e32 v93, 1.0, v93
	v_add_f32_e32 v89, 1.0, v89
	v_add_f32_e32 v94, 1.0, v94
	v_add_f32_e32 v90, 1.0, v90
	v_add_f32_e32 v95, 1.0, v95
	v_add_f32_e32 v91, 1.0, v91
	v_rcp_f32_e32 v92, v92
	v_rcp_f32_e32 v88, v88
	v_rcp_f32_e32 v93, v93
	v_rcp_f32_e32 v89, v89
	v_rcp_f32_e32 v94, v94
	v_rcp_f32_e32 v90, v90
	v_rcp_f32_e32 v95, v95
	v_rcp_f32_e32 v91, v91
	v_lshlrev_b32_e32 v103, 16, v96
	v_and_b32_e32 v96, 0xffff0000, v96
	v_lshlrev_b32_e32 v104, 16, v97
	v_and_b32_e32 v97, 0xffff0000, v97
	v_lshlrev_b32_e32 v105, 16, v98
	v_and_b32_e32 v98, 0xffff0000, v98
	v_lshlrev_b32_e32 v106, 16, v99
	v_and_b32_e32 v99, 0xffff0000, v99
	v_mul_f32_e32 v92, v92, v103
	v_mul_f32_e32 v103, v88, v105
	v_mul_f32_e32 v88, v93, v96
	v_mul_f32_e32 v93, v89, v98
	v_mul_f32_e32 v89, v94, v104
	v_mul_f32_e32 v94, v90, v106
	v_mul_f32_e32 v90, v95, v97
	v_mul_f32_e32 v91, v91, v99
	v_cvt_pk_bf16_f32 v88, v92, v88
	v_cvt_pk_bf16_f32 v89, v89, v90
	v_cvt_pk_bf16_f32 v90, v103, v93
	v_cvt_pk_bf16_f32 v91, v94, v91
	global_store_dwordx4 v[100:101], v[88:91], off
	v_mul_f32_e32 v84, v84, v102
	v_mul_f32_e32 v80, v80, v102
	v_mul_f32_e32 v85, v85, v102
	v_mul_f32_e32 v81, v81, v102
	v_mul_f32_e32 v86, v86, v102
	v_mul_f32_e32 v82, v82, v102
	v_mul_f32_e32 v87, v87, v102
	v_mul_f32_e32 v83, v83, v102
	v_exp_f32_e32 v84, v84
	v_exp_f32_e32 v80, v80
	v_exp_f32_e32 v85, v85
	v_exp_f32_e32 v81, v81
	v_exp_f32_e32 v86, v86
	v_exp_f32_e32 v82, v82
	v_exp_f32_e32 v87, v87
	v_exp_f32_e32 v83, v83
	v_add_f32_e32 v84, 1.0, v84
	v_add_f32_e32 v80, 1.0, v80
	v_add_f32_e32 v85, 1.0, v85
	v_add_f32_e32 v81, 1.0, v81
	v_add_f32_e32 v86, 1.0, v86
	v_add_f32_e32 v82, 1.0, v82
	v_add_f32_e32 v87, 1.0, v87
	v_add_f32_e32 v83, 1.0, v83
	v_rcp_f32_e32 v84, v84
	v_rcp_f32_e32 v80, v80
	v_rcp_f32_e32 v85, v85
	v_rcp_f32_e32 v81, v81
	v_rcp_f32_e32 v86, v86
	v_rcp_f32_e32 v82, v82
	v_rcp_f32_e32 v87, v87
	v_rcp_f32_e32 v83, v83
	v_or_b32_e32 v92, 48, v144
	v_ashrrev_i32_e32 v93, 31, v92
	v_lshlrev_b64 v[92:93], 11, v[92:93]
	v_lshl_add_u64 v[92:93], v[92:93], 0, v[146:147]
	v_lshlrev_b64 v[92:93], 1, v[92:93]
	v_lshl_add_u64 v[94:95], s[20:21], 0, v[92:93]
	v_lshlrev_b32_e32 v96, 16, v220
	v_and_b32_e32 v88, 0xffff0000, v220
	v_lshlrev_b32_e32 v97, 16, v221
	v_and_b32_e32 v89, 0xffff0000, v221
	v_lshlrev_b32_e32 v98, 16, v222
	v_and_b32_e32 v90, 0xffff0000, v222
	v_lshlrev_b32_e32 v99, 16, v223
	v_and_b32_e32 v91, 0xffff0000, v223
	v_mul_f32_e32 v84, v84, v96
	v_mul_f32_e32 v96, v80, v98
	v_mul_f32_e32 v80, v85, v88
	v_mul_f32_e32 v85, v81, v90
	v_mul_f32_e32 v81, v86, v97
	v_mul_f32_e32 v86, v82, v99
	v_mul_f32_e32 v82, v87, v89
	v_mul_f32_e32 v83, v83, v91
	v_cvt_pk_bf16_f32 v80, v84, v80
	v_cvt_pk_bf16_f32 v81, v81, v82
	v_cvt_pk_bf16_f32 v82, v96, v85
	v_cvt_pk_bf16_f32 v83, v86, v83
	global_store_dwordx4 v[100:101], v[80:83], off offset:256
	global_load_dword v86, v[140:141], off offset:192
	s_nop 0
	global_load_dwordx4 v[80:83], v[94:95], off
	global_load_dwordx4 v[224:227], v[94:95], off offset:256
	v_lshl_add_u64 v[84:85], s[24:25], 0, v[92:93]
	s_waitcnt vmcnt(0)
	v_mul_f32_e32 v86, 0xbfb8aa3b, v86
	v_mul_f32_e32 v76, v76, v86
	v_mul_f32_e32 v72, v72, v86
	v_mul_f32_e32 v77, v77, v86
	v_mul_f32_e32 v73, v73, v86
	v_mul_f32_e32 v78, v78, v86
	v_mul_f32_e32 v74, v74, v86
	v_mul_f32_e32 v79, v79, v86
	v_mul_f32_e32 v75, v75, v86
	v_exp_f32_e32 v76, v76
	v_exp_f32_e32 v72, v72
	v_exp_f32_e32 v77, v77
	v_exp_f32_e32 v73, v73
	v_exp_f32_e32 v78, v78
	v_exp_f32_e32 v74, v74
	v_exp_f32_e32 v79, v79
	v_exp_f32_e32 v75, v75
	v_add_f32_e32 v76, 1.0, v76
	v_add_f32_e32 v72, 1.0, v72
	v_add_f32_e32 v77, 1.0, v77
	v_add_f32_e32 v73, 1.0, v73
	v_add_f32_e32 v78, 1.0, v78
	v_add_f32_e32 v74, 1.0, v74
	v_add_f32_e32 v79, 1.0, v79
	v_add_f32_e32 v75, 1.0, v75
	v_rcp_f32_e32 v76, v76
	v_rcp_f32_e32 v72, v72
	v_rcp_f32_e32 v77, v77
	v_rcp_f32_e32 v73, v73
	v_rcp_f32_e32 v78, v78
	v_rcp_f32_e32 v74, v74
	v_rcp_f32_e32 v79, v79
	v_rcp_f32_e32 v75, v75
	v_lshlrev_b32_e32 v87, 16, v80
	v_and_b32_e32 v80, 0xffff0000, v80
	v_lshlrev_b32_e32 v88, 16, v81
	v_and_b32_e32 v81, 0xffff0000, v81
	v_lshlrev_b32_e32 v89, 16, v82
	v_and_b32_e32 v82, 0xffff0000, v82
	v_lshlrev_b32_e32 v90, 16, v83
	v_and_b32_e32 v83, 0xffff0000, v83
	v_mul_f32_e32 v76, v76, v87
	v_mul_f32_e32 v87, v72, v89
	v_mul_f32_e32 v72, v77, v80
	v_mul_f32_e32 v77, v73, v82
	v_mul_f32_e32 v73, v78, v88
	v_mul_f32_e32 v78, v74, v90
	v_mul_f32_e32 v74, v79, v81
	v_mul_f32_e32 v75, v75, v83
	v_cvt_pk_bf16_f32 v72, v76, v72
	v_cvt_pk_bf16_f32 v73, v73, v74
	v_cvt_pk_bf16_f32 v74, v87, v77
	v_cvt_pk_bf16_f32 v75, v78, v75
	global_store_dwordx4 v[84:85], v[72:75], off
	v_mul_f32_e32 v68, v68, v86
	v_mul_f32_e32 v64, v64, v86
	v_mul_f32_e32 v69, v69, v86
	v_mul_f32_e32 v65, v65, v86
	v_mul_f32_e32 v70, v70, v86
	v_mul_f32_e32 v66, v66, v86
	v_mul_f32_e32 v71, v71, v86
	v_mul_f32_e32 v67, v67, v86
	v_exp_f32_e32 v68, v68
	v_exp_f32_e32 v64, v64
	v_exp_f32_e32 v69, v69
	v_exp_f32_e32 v65, v65
	v_exp_f32_e32 v70, v70
	v_exp_f32_e32 v66, v66
	v_exp_f32_e32 v71, v71
	v_exp_f32_e32 v67, v67
	v_add_f32_e32 v68, 1.0, v68
; __device__ __forceinline__ float bf_lo(unsigned w) { return __uint_as_float(w << 16); }
; __device__ __forceinline__ float bf_hi(unsigned w) { return __uint_as_float(w & 0xffff0000u); }
; __device__ __forceinline__ float fast_rcp(float x) { return __builtin_amdgcn_rcpf(x); }
; __device__ __forceinline__ float fast_exp2(float x) { return __builtin_amdgcn_exp2f(x); }
; __device__ __forceinline__ u32x4 pack8(f32x4 v0, f32x4 v1) { u32x4 w; w.x = cvt_pk_bf16(v0[0], v0[1]); w.y = cvt_pk_bf16(v0[2], v0[3]); w.z = cvt_pk_bf16(v1[0], v1[1]); w.w = cvt_pk_bf16(v1[2], v1[3]); return w; }
;     __device__ __forceinline__ void operator()(const f32x4 (&acc)[2][2][4][2], const Unit& u, int wr, int wc, int fr, int fq) const {
;         const int row0 = u.pm * BM + wr * 64 + fr, col0 = u.pn * BM + wc * 32 + 8 * fq;
; #pragma unroll
;         for (int ai = 0; ai < 2; ++ai)
; #pragma unroll
;             for (int m = 0; m < 4; ++m) { const size_t ro = (size_t)(row0 + ai * HALF + m * 16) * DM + col0; const float nr = -LOG2E * rs[row0 + ai * HALF + m * 16];
; #pragma unroll
;                 for (int bj = 0; bj < 2; ++bj) {
;                     const u32x4 pw = *(const u32x4*)(PP + ro + bj * HALF);
;                     const float pv[8] = {bf_lo(pw.x), bf_hi(pw.x), bf_lo(pw.y), bf_hi(pw.y), bf_lo(pw.z), bf_hi(pw.z), bf_lo(pw.w), bf_hi(pw.w)};
;                     f32x4 t0, t1;
; #pragma unroll
;                     for (int j = 0; j < 4; ++j) {
;                         t0[j] = fast_rcp(1.0f + fast_exp2(acc[ai][bj][m][0][j] * nr)) * pv[j];
;                         t1[j] = fast_rcp(1.0f + fast_exp2(acc[ai][bj][m][1][j] * nr)) * pv[4 + j]; }
;                     *(u32x4*)(O + ro + bj * HALF) = pack8(t0, t1); } }
	v_add_f32_e32 v64, 1.0, v64
	v_add_f32_e32 v69, 1.0, v69
	v_add_f32_e32 v65, 1.0, v65
	v_add_f32_e32 v70, 1.0, v70
	v_add_f32_e32 v66, 1.0, v66
	v_add_f32_e32 v71, 1.0, v71
	v_add_f32_e32 v67, 1.0, v67
	v_rcp_f32_e32 v68, v68
	v_rcp_f32_e32 v64, v64
	v_rcp_f32_e32 v69, v69
	v_rcp_f32_e32 v65, v65
	v_rcp_f32_e32 v70, v70
	v_rcp_f32_e32 v66, v66
	v_rcp_f32_e32 v71, v71
	v_rcp_f32_e32 v67, v67
	v_lshl_add_u64 v[76:77], v[142:143], 0, s[2:3]
	v_lshl_add_u64 v[78:79], s[20:21], 0, v[76:77]
	v_lshlrev_b32_e32 v80, 16, v224
	v_and_b32_e32 v72, 0xffff0000, v224
	v_lshlrev_b32_e32 v81, 16, v225
	v_and_b32_e32 v73, 0xffff0000, v225
	v_lshlrev_b32_e32 v82, 16, v226
	v_and_b32_e32 v74, 0xffff0000, v226
	v_lshlrev_b32_e32 v83, 16, v227
	v_and_b32_e32 v75, 0xffff0000, v227
	v_mul_f32_e32 v68, v68, v80
	v_mul_f32_e32 v80, v64, v82
	v_mul_f32_e32 v64, v69, v72
	v_mul_f32_e32 v69, v65, v74
	v_mul_f32_e32 v65, v70, v81
	v_mul_f32_e32 v70, v66, v83
	v_mul_f32_e32 v66, v71, v73
	v_mul_f32_e32 v67, v67, v75
	v_cvt_pk_bf16_f32 v64, v68, v64
	v_cvt_pk_bf16_f32 v65, v65, v66
	v_cvt_pk_bf16_f32 v66, v80, v69
	v_cvt_pk_bf16_f32 v67, v70, v67
	global_store_dwordx4 v[84:85], v[64:67], off offset:256
	global_load_dword v70, v[140:141], off offset:512
	s_nop 0
	global_load_dwordx4 v[64:67], v[78:79], off
	global_load_dwordx4 v[220:223], v[78:79], off offset:256
	v_lshl_add_u64 v[68:69], s[24:25], 0, v[76:77]
	s_waitcnt vmcnt(0)
	v_mul_f32_e32 v70, 0xbfb8aa3b, v70
	v_mul_f32_e32 v60, v60, v70
	v_mul_f32_e32 v56, v56, v70
	v_mul_f32_e32 v61, v61, v70
	v_mul_f32_e32 v57, v57, v70
	v_mul_f32_e32 v62, v62, v70
	v_mul_f32_e32 v58, v58, v70
	v_mul_f32_e32 v63, v63, v70
	v_mul_f32_e32 v59, v59, v70
	v_exp_f32_e32 v60, v60
	v_exp_f32_e32 v56, v56
	v_exp_f32_e32 v61, v61
	v_exp_f32_e32 v57, v57
	v_exp_f32_e32 v62, v62
	v_exp_f32_e32 v58, v58
	v_exp_f32_e32 v63, v63
	v_exp_f32_e32 v59, v59
	v_add_f32_e32 v60, 1.0, v60
	v_add_f32_e32 v56, 1.0, v56
	v_add_f32_e32 v61, 1.0, v61
	v_add_f32_e32 v57, 1.0, v57
	v_add_f32_e32 v62, 1.0, v62
	v_add_f32_e32 v58, 1.0, v58
	v_add_f32_e32 v63, 1.0, v63
	v_add_f32_e32 v59, 1.0, v59
	v_rcp_f32_e32 v60, v60
	v_rcp_f32_e32 v56, v56
	v_rcp_f32_e32 v61, v61
	v_rcp_f32_e32 v57, v57
	v_rcp_f32_e32 v62, v62
	v_rcp_f32_e32 v58, v58
	v_rcp_f32_e32 v63, v63
	v_rcp_f32_e32 v59, v59
	v_lshlrev_b32_e32 v71, 16, v64
	v_and_b32_e32 v64, 0xffff0000, v64
	v_lshlrev_b32_e32 v72, 16, v65
	v_and_b32_e32 v65, 0xffff0000, v65
	v_lshlrev_b32_e32 v73, 16, v66
	v_and_b32_e32 v66, 0xffff0000, v66
	v_lshlrev_b32_e32 v74, 16, v67
	v_and_b32_e32 v67, 0xffff0000, v67
	v_mul_f32_e32 v60, v60, v71
	v_mul_f32_e32 v71, v56, v73
	v_mul_f32_e32 v56, v61, v64
	v_mul_f32_e32 v61, v57, v66
	v_mul_f32_e32 v57, v62, v72
	v_mul_f32_e32 v62, v58, v74
	v_mul_f32_e32 v58, v63, v65
	v_mul_f32_e32 v59, v59, v67
	v_cvt_pk_bf16_f32 v56, v60, v56
	v_cvt_pk_bf16_f32 v57, v57, v58
	v_cvt_pk_bf16_f32 v58, v71, v61
	v_cvt_pk_bf16_f32 v59, v62, v59
	global_store_dwordx4 v[68:69], v[56:59], off
	v_mul_f32_e32 v52, v52, v70
	v_mul_f32_e32 v48, v48, v70
	v_mul_f32_e32 v53, v53, v70
	v_mul_f32_e32 v49, v49, v70
	v_mul_f32_e32 v54, v54, v70
	v_mul_f32_e32 v50, v50, v70
	v_mul_f32_e32 v55, v55, v70
	v_mul_f32_e32 v51, v51, v70
	v_exp_f32_e32 v52, v52
	v_exp_f32_e32 v48, v48
	v_exp_f32_e32 v53, v53
	v_exp_f32_e32 v49, v49
	v_exp_f32_e32 v54, v54
	v_exp_f32_e32 v50, v50
	v_exp_f32_e32 v55, v55
	v_exp_f32_e32 v51, v51
	v_add_f32_e32 v52, 1.0, v52
	v_add_f32_e32 v48, 1.0, v48
	v_add_f32_e32 v53, 1.0, v53
	v_add_f32_e32 v49, 1.0, v49
	v_add_f32_e32 v54, 1.0, v54
	v_add_f32_e32 v50, 1.0, v50
	v_add_f32_e32 v55, 1.0, v55
	v_add_f32_e32 v51, 1.0, v51
	v_rcp_f32_e32 v52, v52
	v_rcp_f32_e32 v48, v48
	v_rcp_f32_e32 v53, v53
	v_rcp_f32_e32 v49, v49
	v_rcp_f32_e32 v54, v54
	v_rcp_f32_e32 v50, v50
	v_rcp_f32_e32 v55, v55
	v_rcp_f32_e32 v51, v51
	v_lshl_add_u64 v[60:61], v[142:143], 0, s[6:7]
	v_lshl_add_u64 v[62:63], s[20:21], 0, v[60:61]
	v_lshlrev_b32_e32 v64, 16, v220
	v_and_b32_e32 v56, 0xffff0000, v220
	v_lshlrev_b32_e32 v65, 16, v221
	v_and_b32_e32 v57, 0xffff0000, v221
	v_lshlrev_b32_e32 v66, 16, v222
	v_and_b32_e32 v58, 0xffff0000, v222
	v_lshlrev_b32_e32 v67, 16, v223
	v_and_b32_e32 v59, 0xffff0000, v223
	v_mul_f32_e32 v52, v52, v64
	v_mul_f32_e32 v64, v48, v66
	v_mul_f32_e32 v48, v53, v56
	v_mul_f32_e32 v53, v49, v58
	v_mul_f32_e32 v49, v54, v65
	v_mul_f32_e32 v54, v50, v67
	v_mul_f32_e32 v50, v55, v57
	v_mul_f32_e32 v51, v51, v59
	v_cvt_pk_bf16_f32 v48, v52, v48
	v_cvt_pk_bf16_f32 v49, v49, v50
	v_cvt_pk_bf16_f32 v50, v64, v53
	v_cvt_pk_bf16_f32 v51, v54, v51
	global_store_dwordx4 v[68:69], v[48:51], off offset:256
	global_load_dword v54, v[140:141], off offset:576
	s_nop 0
	global_load_dwordx4 v[48:51], v[62:63], off
	global_load_dwordx4 v[224:227], v[62:63], off offset:256
	v_lshl_add_u64 v[52:53], s[24:25], 0, v[60:61]
	s_waitcnt vmcnt(0)
; __device__ __forceinline__ float bf_lo(unsigned w) { return __uint_as_float(w << 16); }
; __device__ __forceinline__ float bf_hi(unsigned w) { return __uint_as_float(w & 0xffff0000u); }
; __device__ __forceinline__ float fast_rcp(float x) { return __builtin_amdgcn_rcpf(x); }
; __device__ __forceinline__ float fast_exp2(float x) { return __builtin_amdgcn_exp2f(x); }
; __device__ __forceinline__ u32x4 pack8(f32x4 v0, f32x4 v1) { u32x4 w; w.x = cvt_pk_bf16(v0[0], v0[1]); w.y = cvt_pk_bf16(v0[2], v0[3]); w.z = cvt_pk_bf16(v1[0], v1[1]); w.w = cvt_pk_bf16(v1[2], v1[3]); return w; }
;     __device__ __forceinline__ void operator()(const f32x4 (&acc)[2][2][4][2], const Unit& u, int wr, int wc, int fr, int fq) const {
;         const int row0 = u.pm * BM + wr * 64 + fr, col0 = u.pn * BM + wc * 32 + 8 * fq;
; #pragma unroll
;         for (int ai = 0; ai < 2; ++ai)
; #pragma unroll
;             for (int m = 0; m < 4; ++m) { const size_t ro = (size_t)(row0 + ai * HALF + m * 16) * DM + col0; const float nr = -LOG2E * rs[row0 + ai * HALF + m * 16];
; #pragma unroll
;                 for (int bj = 0; bj < 2; ++bj) {
;                     const u32x4 pw = *(const u32x4*)(PP + ro + bj * HALF);
;                     const float pv[8] = {bf_lo(pw.x), bf_hi(pw.x), bf_lo(pw.y), bf_hi(pw.y), bf_lo(pw.z), bf_hi(pw.z), bf_lo(pw.w), bf_hi(pw.w)};
;                     f32x4 t0, t1;
; #pragma unroll
;                     for (int j = 0; j < 4; ++j) {
;                         t0[j] = fast_rcp(1.0f + fast_exp2(acc[ai][bj][m][0][j] * nr)) * pv[j];
;                         t1[j] = fast_rcp(1.0f + fast_exp2(acc[ai][bj][m][1][j] * nr)) * pv[4 + j]; }
;                     *(u32x4*)(O + ro + bj * HALF) = pack8(t0, t1); } }
	v_mul_f32_e32 v54, 0xbfb8aa3b, v54
	v_mul_f32_e32 v44, v44, v54
	v_mul_f32_e32 v40, v40, v54
	v_mul_f32_e32 v45, v45, v54
	v_mul_f32_e32 v41, v41, v54
	v_mul_f32_e32 v46, v46, v54
	v_mul_f32_e32 v42, v42, v54
	v_mul_f32_e32 v47, v47, v54
	v_mul_f32_e32 v43, v43, v54
	v_exp_f32_e32 v44, v44
	v_exp_f32_e32 v40, v40
	v_exp_f32_e32 v45, v45
	v_exp_f32_e32 v41, v41
	v_exp_f32_e32 v46, v46
	v_exp_f32_e32 v42, v42
	v_exp_f32_e32 v47, v47
	v_exp_f32_e32 v43, v43
	v_add_f32_e32 v44, 1.0, v44
	v_add_f32_e32 v40, 1.0, v40
	v_add_f32_e32 v45, 1.0, v45
	v_add_f32_e32 v41, 1.0, v41
	v_add_f32_e32 v46, 1.0, v46
	v_add_f32_e32 v42, 1.0, v42
	v_add_f32_e32 v47, 1.0, v47
	v_add_f32_e32 v43, 1.0, v43
	v_rcp_f32_e32 v44, v44
	v_rcp_f32_e32 v40, v40
	v_rcp_f32_e32 v45, v45
	v_rcp_f32_e32 v41, v41
	v_rcp_f32_e32 v46, v46
	v_rcp_f32_e32 v42, v42
	v_rcp_f32_e32 v47, v47
	v_rcp_f32_e32 v43, v43
	v_lshlrev_b32_e32 v55, 16, v48
	v_and_b32_e32 v48, 0xffff0000, v48
	v_lshlrev_b32_e32 v56, 16, v49
	v_and_b32_e32 v49, 0xffff0000, v49
	v_lshlrev_b32_e32 v57, 16, v50
	v_and_b32_e32 v50, 0xffff0000, v50
	v_lshlrev_b32_e32 v58, 16, v51
	v_and_b32_e32 v51, 0xffff0000, v51
	v_mul_f32_e32 v44, v44, v55
	v_mul_f32_e32 v55, v40, v57
	v_mul_f32_e32 v40, v45, v48
	v_mul_f32_e32 v45, v41, v50
	v_mul_f32_e32 v41, v46, v56
	v_mul_f32_e32 v46, v42, v58
	v_mul_f32_e32 v42, v47, v49
	v_mul_f32_e32 v43, v43, v51
	v_cvt_pk_bf16_f32 v40, v44, v40
	v_cvt_pk_bf16_f32 v41, v41, v42
	v_cvt_pk_bf16_f32 v42, v55, v45
	v_cvt_pk_bf16_f32 v43, v46, v43
	global_store_dwordx4 v[52:53], v[40:43], off
	v_mul_f32_e32 v36, v36, v54
	v_mul_f32_e32 v32, v32, v54
	v_mul_f32_e32 v37, v37, v54
	v_mul_f32_e32 v33, v33, v54
	v_mul_f32_e32 v38, v38, v54
	v_mul_f32_e32 v34, v34, v54
	v_mul_f32_e32 v39, v39, v54
	v_mul_f32_e32 v35, v35, v54
	v_exp_f32_e32 v36, v36
	v_exp_f32_e32 v32, v32
	v_exp_f32_e32 v37, v37
	v_exp_f32_e32 v33, v33
	v_exp_f32_e32 v38, v38
	v_exp_f32_e32 v34, v34
	v_exp_f32_e32 v39, v39
	v_exp_f32_e32 v35, v35
	v_add_f32_e32 v36, 1.0, v36
	v_add_f32_e32 v32, 1.0, v32
	v_add_f32_e32 v37, 1.0, v37
	v_add_f32_e32 v33, 1.0, v33
	v_add_f32_e32 v38, 1.0, v38
	v_add_f32_e32 v34, 1.0, v34
	v_add_f32_e32 v39, 1.0, v39
	v_add_f32_e32 v35, 1.0, v35
	v_rcp_f32_e32 v36, v36
	v_rcp_f32_e32 v32, v32
	v_rcp_f32_e32 v37, v37
	v_rcp_f32_e32 v33, v33
	v_rcp_f32_e32 v38, v38
	v_rcp_f32_e32 v34, v34
	v_rcp_f32_e32 v39, v39
	v_rcp_f32_e32 v35, v35
	v_lshl_add_u64 v[44:45], v[142:143], 0, s[8:9]
	v_lshl_add_u64 v[46:47], s[20:21], 0, v[44:45]
	v_lshlrev_b32_e32 v48, 16, v224
	v_and_b32_e32 v40, 0xffff0000, v224
	v_lshlrev_b32_e32 v49, 16, v225
	v_and_b32_e32 v41, 0xffff0000, v225
	v_lshlrev_b32_e32 v50, 16, v226
	v_and_b32_e32 v42, 0xffff0000, v226
	v_lshlrev_b32_e32 v51, 16, v227
	v_and_b32_e32 v43, 0xffff0000, v227
	v_mul_f32_e32 v36, v36, v48
	v_mul_f32_e32 v48, v32, v50
	v_mul_f32_e32 v32, v37, v40
	v_mul_f32_e32 v37, v33, v42
	v_mul_f32_e32 v33, v38, v49
	v_mul_f32_e32 v38, v34, v51
	v_mul_f32_e32 v34, v39, v41
	v_mul_f32_e32 v35, v35, v43
	v_cvt_pk_bf16_f32 v32, v36, v32
	v_cvt_pk_bf16_f32 v33, v33, v34
	v_cvt_pk_bf16_f32 v34, v48, v37
	v_cvt_pk_bf16_f32 v35, v38, v35
	global_store_dwordx4 v[52:53], v[32:35], off offset:256
	global_load_dword v38, v[140:141], off offset:640
	s_nop 0
	global_load_dwordx4 v[32:35], v[46:47], off
	global_load_dwordx4 v[220:223], v[46:47], off offset:256
	v_lshl_add_u64 v[36:37], s[24:25], 0, v[44:45]
	s_waitcnt vmcnt(0)
; __device__ __forceinline__ float bf_lo(unsigned w) { return __uint_as_float(w << 16); }
; __device__ __forceinline__ float bf_hi(unsigned w) { return __uint_as_float(w & 0xffff0000u); }
; __device__ __forceinline__ float fast_rcp(float x) { return __builtin_amdgcn_rcpf(x); }
; __device__ __forceinline__ float fast_exp2(float x) { return __builtin_amdgcn_exp2f(x); }
; #define PG8_WAIT_V(n) asm volatile("s_waitcnt vmcnt(" #n ")" ::: "memory")
; #define PG8_BAR __builtin_amdgcn_s_barrier()
; template <class Epi>
; __device__ __forceinline__ void gemm_phase(LAS unsigned char* lds, const Gemm g, const StaticOrder& S, const Epi& E) {
;     ...
;         if (!has_next) break;
; #pragma unroll
;         for (int a = 0; a < 2; ++a)
; #pragma unroll
;             for (int b = 0; b < 2; ++b)
; #pragma unroll
;                 for (int m = 0; m < 4; ++m)
; #pragma unroll
;                     for (int n = 0; n < 2; ++n) acc[a][b][m][n] = (f32x4){0.f, 0.f, 0.f, 0.f};
;         cur = nxt; cA = nA; cB = nB; ++ui;
;     }
;     PG8_WAIT_V(0);
;     if (wr == 0) PG8_BAR;
;     PG8_BAR;
;     __device__ __forceinline__ void operator()(const f32x4 (&acc)[2][2][4][2], const Unit& u, int wr, int wc, int fr, int fq) const {
;         const int row0 = u.pm * BM + wr * 64 + fr, col0 = u.pn * BM + wc * 32 + 8 * fq;
; #pragma unroll
;         for (int ai = 0; ai < 2; ++ai)
; #pragma unroll
;             for (int m = 0; m < 4; ++m) { const size_t ro = (size_t)(row0 + ai * HALF + m * 16) * DM + col0; const float nr = -LOG2E * rs[row0 + ai * HALF + m * 16];
; #pragma unroll
;                 for (int bj = 0; bj < 2; ++bj) {
;                     const u32x4 pw = *(const u32x4*)(PP + ro + bj * HALF);
;                     const float pv[8] = {bf_lo(pw.x), bf_hi(pw.x), bf_lo(pw.y), bf_hi(pw.y), bf_lo(pw.z), bf_hi(pw.z), bf_lo(pw.w), bf_hi(pw.w)};
;                     f32x4 t0, t1;
; #pragma unroll
;                     for (int j = 0; j < 4; ++j) {
;                         t0[j] = fast_rcp(1.0f + fast_exp2(acc[ai][bj][m][0][j] * nr)) * pv[j];
;                         t1[j] = fast_rcp(1.0f + fast_exp2(acc[ai][bj][m][1][j] * nr)) * pv[4 + j]; }
;                     *(u32x4*)(O + ro + bj * HALF) = pack8(t0, t1); } }
	v_mul_f32_e32 v38, 0xbfb8aa3b, v38
	v_mul_f32_e32 v28, v28, v38
	v_mul_f32_e32 v24, v24, v38
	v_mul_f32_e32 v29, v29, v38
	v_mul_f32_e32 v25, v25, v38
	v_mul_f32_e32 v30, v30, v38
	v_mul_f32_e32 v26, v26, v38
	v_mul_f32_e32 v31, v31, v38
	v_mul_f32_e32 v27, v27, v38
	v_exp_f32_e32 v28, v28
	v_exp_f32_e32 v24, v24
	v_exp_f32_e32 v29, v29
	v_exp_f32_e32 v25, v25
	v_exp_f32_e32 v30, v30
	v_exp_f32_e32 v26, v26
	v_exp_f32_e32 v31, v31
	v_exp_f32_e32 v27, v27
	v_add_f32_e32 v28, 1.0, v28
	v_add_f32_e32 v24, 1.0, v24
	v_add_f32_e32 v29, 1.0, v29
	v_add_f32_e32 v25, 1.0, v25
	v_add_f32_e32 v30, 1.0, v30
	v_add_f32_e32 v26, 1.0, v26
	v_add_f32_e32 v31, 1.0, v31
	v_add_f32_e32 v27, 1.0, v27
	v_rcp_f32_e32 v28, v28
	v_rcp_f32_e32 v24, v24
	v_rcp_f32_e32 v29, v29
	v_rcp_f32_e32 v25, v25
	v_rcp_f32_e32 v30, v30
	v_rcp_f32_e32 v26, v26
	v_rcp_f32_e32 v31, v31
	v_rcp_f32_e32 v27, v27
	v_lshlrev_b32_e32 v39, 16, v32
	v_and_b32_e32 v32, 0xffff0000, v32
	v_lshlrev_b32_e32 v40, 16, v33
	v_and_b32_e32 v33, 0xffff0000, v33
	v_lshlrev_b32_e32 v41, 16, v34
	v_and_b32_e32 v34, 0xffff0000, v34
	v_lshlrev_b32_e32 v42, 16, v35
	v_and_b32_e32 v35, 0xffff0000, v35
	v_mul_f32_e32 v28, v28, v39
	v_mul_f32_e32 v39, v24, v41
	v_mul_f32_e32 v24, v29, v32
	v_mul_f32_e32 v29, v25, v34
	v_mul_f32_e32 v25, v30, v40
	v_mul_f32_e32 v30, v26, v42
	v_mul_f32_e32 v26, v31, v33
	v_mul_f32_e32 v27, v27, v35
	v_cvt_pk_bf16_f32 v24, v28, v24
	v_cvt_pk_bf16_f32 v25, v25, v26
	v_cvt_pk_bf16_f32 v26, v39, v29
	v_cvt_pk_bf16_f32 v27, v30, v27
	global_store_dwordx4 v[36:37], v[24:27], off
	v_mul_f32_e32 v20, v20, v38
	v_mul_f32_e32 v16, v16, v38
	v_mul_f32_e32 v21, v21, v38
	v_mul_f32_e32 v17, v17, v38
	v_mul_f32_e32 v22, v22, v38
	v_mul_f32_e32 v18, v18, v38
	v_mul_f32_e32 v23, v23, v38
	v_mul_f32_e32 v19, v19, v38
	v_exp_f32_e32 v20, v20
	v_exp_f32_e32 v16, v16
	v_exp_f32_e32 v21, v21
	v_exp_f32_e32 v17, v17
	v_exp_f32_e32 v22, v22
	v_exp_f32_e32 v18, v18
	v_exp_f32_e32 v23, v23
	v_exp_f32_e32 v19, v19
	v_add_f32_e32 v20, 1.0, v20
	v_add_f32_e32 v16, 1.0, v16
	v_add_f32_e32 v21, 1.0, v21
	v_add_f32_e32 v17, 1.0, v17
	v_add_f32_e32 v22, 1.0, v22
	v_add_f32_e32 v18, 1.0, v18
	v_add_f32_e32 v23, 1.0, v23
	v_add_f32_e32 v19, 1.0, v19
	v_rcp_f32_e32 v20, v20
	v_rcp_f32_e32 v16, v16
	v_rcp_f32_e32 v21, v21
	v_rcp_f32_e32 v17, v17
	v_rcp_f32_e32 v22, v22
	v_rcp_f32_e32 v18, v18
	v_rcp_f32_e32 v23, v23
	v_rcp_f32_e32 v19, v19
	v_lshl_add_u64 v[28:29], v[142:143], 0, s[30:31]
	v_lshl_add_u64 v[30:31], s[20:21], 0, v[28:29]
	v_lshlrev_b32_e32 v32, 16, v220
	v_and_b32_e32 v24, 0xffff0000, v220
	v_lshlrev_b32_e32 v33, 16, v221
	v_and_b32_e32 v25, 0xffff0000, v221
	v_lshlrev_b32_e32 v34, 16, v222
	v_and_b32_e32 v26, 0xffff0000, v222
	v_lshlrev_b32_e32 v35, 16, v223
	v_and_b32_e32 v27, 0xffff0000, v223
	v_mul_f32_e32 v20, v20, v32
	v_mul_f32_e32 v32, v16, v34
	v_mul_f32_e32 v16, v21, v24
	v_mul_f32_e32 v21, v17, v26
	v_mul_f32_e32 v17, v22, v33
	v_mul_f32_e32 v22, v18, v35
	v_mul_f32_e32 v18, v23, v25
	v_mul_f32_e32 v19, v19, v27
	v_cvt_pk_bf16_f32 v16, v20, v16
	v_cvt_pk_bf16_f32 v17, v17, v18
	v_cvt_pk_bf16_f32 v18, v32, v21
	v_cvt_pk_bf16_f32 v19, v22, v19
	global_store_dwordx4 v[36:37], v[16:19], off offset:256
	global_load_dword v22, v[140:141], off offset:704
	s_nop 0
	global_load_dwordx4 v[16:19], v[30:31], off
	global_load_dwordx4 v[224:227], v[30:31], off offset:256
	v_lshl_add_u64 v[20:21], s[24:25], 0, v[28:29]
	s_waitcnt vmcnt(0)
	v_mul_f32_e32 v22, 0xbfb8aa3b, v22
	v_mul_f32_e32 v12, v12, v22
	v_mul_f32_e32 v8, v8, v22
	v_mul_f32_e32 v13, v13, v22
	v_mul_f32_e32 v9, v9, v22
	v_mul_f32_e32 v14, v14, v22
	v_mul_f32_e32 v10, v10, v22
	v_mul_f32_e32 v15, v15, v22
	v_mul_f32_e32 v11, v11, v22
	v_exp_f32_e32 v12, v12
	v_exp_f32_e32 v8, v8
	v_exp_f32_e32 v13, v13
	v_exp_f32_e32 v9, v9
	v_exp_f32_e32 v14, v14
	v_exp_f32_e32 v10, v10
	v_exp_f32_e32 v15, v15
	v_exp_f32_e32 v11, v11
	v_add_f32_e32 v12, 1.0, v12
	v_add_f32_e32 v8, 1.0, v8
	v_add_f32_e32 v13, 1.0, v13
	v_add_f32_e32 v9, 1.0, v9
	v_add_f32_e32 v14, 1.0, v14
	v_add_f32_e32 v10, 1.0, v10
	v_add_f32_e32 v15, 1.0, v15
	v_add_f32_e32 v11, 1.0, v11
	v_rcp_f32_e32 v12, v12
	v_rcp_f32_e32 v8, v8
	v_rcp_f32_e32 v13, v13
	v_rcp_f32_e32 v9, v9
	v_rcp_f32_e32 v14, v14
	v_rcp_f32_e32 v10, v10
	v_rcp_f32_e32 v15, v15
	v_rcp_f32_e32 v11, v11
	v_lshlrev_b32_e32 v23, 16, v16
	v_and_b32_e32 v16, 0xffff0000, v16
	v_lshlrev_b32_e32 v24, 16, v17
	v_and_b32_e32 v17, 0xffff0000, v17
	v_lshlrev_b32_e32 v25, 16, v18
	v_and_b32_e32 v18, 0xffff0000, v18
	v_lshlrev_b32_e32 v26, 16, v19
	v_and_b32_e32 v19, 0xffff0000, v19
	v_mul_f32_e32 v12, v12, v23
	v_mul_f32_e32 v23, v8, v25
	v_mul_f32_e32 v8, v13, v16
	v_mul_f32_e32 v13, v9, v18
	v_mul_f32_e32 v9, v14, v24
	v_mul_f32_e32 v14, v10, v26
	v_mul_f32_e32 v10, v15, v17
	v_mul_f32_e32 v11, v11, v19
	v_cvt_pk_bf16_f32 v8, v12, v8
	v_cvt_pk_bf16_f32 v9, v9, v10
	v_cvt_pk_bf16_f32 v10, v23, v13
	v_cvt_pk_bf16_f32 v11, v14, v11
	global_store_dwordx4 v[20:21], v[8:11], off
	v_mul_f32_e32 v4, v4, v22
	v_mul_f32_e32 v0, v0, v22
	v_mul_f32_e32 v5, v5, v22
	v_mul_f32_e32 v1, v1, v22
	v_mul_f32_e32 v6, v6, v22
	v_mul_f32_e32 v2, v2, v22
	v_mul_f32_e32 v7, v7, v22
	v_mul_f32_e32 v3, v3, v22
	v_exp_f32_e32 v4, v4
	v_exp_f32_e32 v0, v0
	v_exp_f32_e32 v5, v5
	v_exp_f32_e32 v1, v1
	v_exp_f32_e32 v6, v6
	v_exp_f32_e32 v2, v2
	v_exp_f32_e32 v7, v7
	v_exp_f32_e32 v3, v3
	v_add_f32_e32 v4, 1.0, v4
	v_add_f32_e32 v0, 1.0, v0
	v_add_f32_e32 v5, 1.0, v5
	v_add_f32_e32 v1, 1.0, v1
	v_add_f32_e32 v6, 1.0, v6
	v_add_f32_e32 v2, 1.0, v2
	v_add_f32_e32 v7, 1.0, v7
	v_add_f32_e32 v3, 1.0, v3
	v_rcp_f32_e32 v4, v4
	v_rcp_f32_e32 v0, v0
	v_rcp_f32_e32 v5, v5
	v_rcp_f32_e32 v1, v1
	v_rcp_f32_e32 v6, v6
	v_rcp_f32_e32 v2, v2
	v_rcp_f32_e32 v7, v7
	v_rcp_f32_e32 v3, v3
	v_lshlrev_b32_e32 v12, 16, v224
	v_and_b32_e32 v8, 0xffff0000, v224
	v_lshlrev_b32_e32 v13, 16, v225
	v_and_b32_e32 v9, 0xffff0000, v225
	v_lshlrev_b32_e32 v14, 16, v226
	v_and_b32_e32 v10, 0xffff0000, v226
	v_lshlrev_b32_e32 v15, 16, v227
	v_and_b32_e32 v11, 0xffff0000, v227
	v_mul_f32_e32 v4, v4, v12
	v_mul_f32_e32 v12, v0, v14
	v_mul_f32_e32 v0, v5, v8
	v_mul_f32_e32 v5, v1, v10
	v_mul_f32_e32 v1, v6, v13
	v_mul_f32_e32 v6, v2, v15
	v_mul_f32_e32 v2, v7, v9
	v_mul_f32_e32 v3, v3, v11
	v_cvt_pk_bf16_f32 v0, v4, v0
	v_cvt_pk_bf16_f32 v1, v1, v2
	v_cvt_pk_bf16_f32 v2, v12, v5
	v_cvt_pk_bf16_f32 v3, v6, v3
	global_store_dwordx4 v[20:21], v[0:3], off offset:256
	s_cbranch_vccz .LBB0_996
	s_waitcnt vmcnt(0)
	s_cmpk_gt_u32 s10, 0xff
	s_cbranch_scc1 .LBB0_1003
	s_barrier
